# v32 + GEMM epilogue 16B output stores written through (sc1) in P1,P2,P6,P7,P8 to shorten the grid barriers' L2 write-back
# baseline (speedup 1.0000x reference)
.LBB0_344:
	s_mov_b64 s[16:17], -1
	s_mov_b64 s[12:13], 0
	s_cmp_lt_i32 s44, 1
	s_mov_b64 s[14:15], 0
	s_cbranch_scc1 .LBB0_350
	s_cmp_eq_u32 s44, 1
	s_mov_b64 s[14:15], -1
	s_cbranch_scc0 .LBB0_347
	s_lshl_b32 s14, s47, 8
	v_mov_b32_e32 v2, v171
	v_mov_b32_e32 v4, v172
	s_or_b32 s14, s14, s42
	v_cvt_pk_bf16_f32 v142, v130, v131
	v_cvt_pk_bf16_f32 v143, v132, v133
	v_cvt_pk_bf16_f32 v144, v126, v127
	s_waitcnt lgkmcnt(0)
	v_cvt_pk_bf16_f32 v145, v128, v129
	v_lshl_add_u32 v140, v4, 3, s14
	s_lshl_b32 s14, s54, 8
	s_add_i32 s14, s14, s35
	v_add_u32_e32 v4, s14, v2
	v_ashrrev_i32_e32 v5, 31, v4
	v_ashrrev_i32_e32 v141, 31, v140
	v_lshlrev_b64 v[146:147], 15, v[4:5]
	v_lshl_add_u64 v[146:147], s[84:85], 0, v[146:147]
	v_lshlrev_b64 v[140:141], 1, v[140:141]
	v_lshl_add_u64 v[146:147], v[146:147], 0, v[140:141]
	global_store_dwordx4 v[146:147], v[142:145], off sc1
	s_mov_b64 s[14:15], 0
	s_nop 0
	v_cvt_pk_bf16_f32 v142, v98, v99
	v_cvt_pk_bf16_f32 v143, v100, v101
	v_cvt_pk_bf16_f32 v144, v94, v95
	v_cvt_pk_bf16_f32 v145, v96, v97
	global_store_dwordx4 v[146:147], v[142:145], off offset:256 sc1
	v_add_u32_e32 v146, 16, v4
	v_ashrrev_i32_e32 v147, 31, v146
	v_lshlrev_b64 v[146:147], 15, v[146:147]
	v_lshl_add_u64 v[146:147], s[84:85], 0, v[146:147]
	v_cvt_pk_bf16_f32 v142, v122, v123
	v_cvt_pk_bf16_f32 v143, v124, v125
	v_cvt_pk_bf16_f32 v144, v118, v119
	v_cvt_pk_bf16_f32 v145, v120, v121
	v_lshl_add_u64 v[146:147], v[146:147], 0, v[140:141]
	global_store_dwordx4 v[146:147], v[142:145], off sc1
	s_nop 1
	v_cvt_pk_bf16_f32 v142, v90, v91
	v_cvt_pk_bf16_f32 v143, v92, v93
	v_cvt_pk_bf16_f32 v144, v86, v87
	v_cvt_pk_bf16_f32 v145, v88, v89
	global_store_dwordx4 v[146:147], v[142:145], off offset:256 sc1
	v_add_u32_e32 v146, 32, v4
	v_ashrrev_i32_e32 v147, 31, v146
	v_lshlrev_b64 v[146:147], 15, v[146:147]
	v_lshl_add_u64 v[146:147], s[84:85], 0, v[146:147]
	v_cvt_pk_bf16_f32 v142, v114, v115
	v_cvt_pk_bf16_f32 v143, v116, v117
	v_cvt_pk_bf16_f32 v144, v110, v111
	v_cvt_pk_bf16_f32 v145, v112, v113
	v_lshl_add_u64 v[146:147], v[146:147], 0, v[140:141]
	global_store_dwordx4 v[146:147], v[142:145], off sc1
	s_nop 1
	v_cvt_pk_bf16_f32 v142, v82, v83
	v_cvt_pk_bf16_f32 v143, v84, v85
	v_cvt_pk_bf16_f32 v144, v78, v79
	v_cvt_pk_bf16_f32 v145, v80, v81
	global_store_dwordx4 v[146:147], v[142:145], off offset:256 sc1
	v_add_u32_e32 v146, 48, v4
	v_ashrrev_i32_e32 v147, 31, v146
	v_lshlrev_b64 v[146:147], 15, v[146:147]
	v_lshl_add_u64 v[146:147], s[84:85], 0, v[146:147]
	v_cvt_pk_bf16_f32 v142, v106, v107
	v_cvt_pk_bf16_f32 v143, v108, v109
	v_cvt_pk_bf16_f32 v144, v102, v103
	v_cvt_pk_bf16_f32 v145, v104, v105
	v_lshl_add_u64 v[146:147], v[146:147], 0, v[140:141]
	global_store_dwordx4 v[146:147], v[142:145], off sc1
	s_nop 1
	v_cvt_pk_bf16_f32 v142, v74, v75
	v_cvt_pk_bf16_f32 v143, v76, v77
	v_cvt_pk_bf16_f32 v144, v70, v71
	v_cvt_pk_bf16_f32 v145, v72, v73
	global_store_dwordx4 v[146:147], v[142:145], off offset:256 sc1
	v_add_u32_e32 v146, 0x80, v4
	v_ashrrev_i32_e32 v147, 31, v146
	v_lshlrev_b64 v[146:147], 15, v[146:147]
	v_lshl_add_u64 v[146:147], s[84:85], 0, v[146:147]
	v_cvt_pk_bf16_f32 v142, v66, v67
	v_cvt_pk_bf16_f32 v143, v68, v69
	v_cvt_pk_bf16_f32 v144, v62, v63
	v_cvt_pk_bf16_f32 v145, v64, v65
	v_lshl_add_u64 v[146:147], v[146:147], 0, v[140:141]
	global_store_dwordx4 v[146:147], v[142:145], off sc1
	s_nop 1
	v_cvt_pk_bf16_f32 v142, v34, v35
	v_cvt_pk_bf16_f32 v143, v36, v37
	v_cvt_pk_bf16_f32 v144, v30, v31
	v_cvt_pk_bf16_f32 v145, v32, v33
	global_store_dwordx4 v[146:147], v[142:145], off offset:256 sc1
	v_add_u32_e32 v146, 0x90, v4
	v_ashrrev_i32_e32 v147, 31, v146
	v_lshlrev_b64 v[146:147], 15, v[146:147]
	v_lshl_add_u64 v[146:147], s[84:85], 0, v[146:147]
	v_cvt_pk_bf16_f32 v142, v58, v59
	v_cvt_pk_bf16_f32 v143, v60, v61
	v_cvt_pk_bf16_f32 v144, v54, v55
	v_cvt_pk_bf16_f32 v145, v56, v57
	v_lshl_add_u64 v[146:147], v[146:147], 0, v[140:141]
	global_store_dwordx4 v[146:147], v[142:145], off sc1
	s_nop 1
	v_cvt_pk_bf16_f32 v142, v26, v27
	v_cvt_pk_bf16_f32 v143, v28, v29
	v_cvt_pk_bf16_f32 v144, v22, v23
	v_cvt_pk_bf16_f32 v145, v24, v25
	global_store_dwordx4 v[146:147], v[142:145], off offset:256 sc1
	v_add_u32_e32 v146, 0xa0, v4
	v_ashrrev_i32_e32 v147, 31, v146
	v_lshlrev_b64 v[146:147], 15, v[146:147]
	v_add_u32_e32 v4, 0xb0, v4
	v_lshl_add_u64 v[146:147], s[84:85], 0, v[146:147]
	v_ashrrev_i32_e32 v5, 31, v4
	v_cvt_pk_bf16_f32 v142, v50, v51
	v_cvt_pk_bf16_f32 v143, v52, v53
	v_lshl_add_u64 v[146:147], v[146:147], 0, v[140:141]
	v_lshlrev_b64 v[4:5], 15, v[4:5]
	v_cvt_pk_bf16_f32 v144, v46, v47
	v_cvt_pk_bf16_f32 v145, v48, v49
	global_store_dwordx4 v[146:147], v[142:145], off sc1
	v_lshl_add_u64 v[4:5], s[84:85], 0, v[4:5]
	v_lshl_add_u64 v[4:5], v[4:5], 0, v[140:141]
	v_cvt_pk_bf16_f32 v142, v18, v19
	v_cvt_pk_bf16_f32 v143, v20, v21
	v_cvt_pk_bf16_f32 v144, v14, v15
	v_cvt_pk_bf16_f32 v145, v16, v17
	global_store_dwordx4 v[146:147], v[142:145], off offset:256 sc1
	s_nop 1
	v_cvt_pk_bf16_f32 v142, v42, v43
	v_cvt_pk_bf16_f32 v143, v44, v45
	v_cvt_pk_bf16_f32 v144, v38, v39
	v_cvt_pk_bf16_f32 v145, v40, v41
	global_store_dwordx4 v[4:5], v[142:145], off sc1
	v_cvt_pk_bf16_f32 v140, v10, v11
	v_cvt_pk_bf16_f32 v141, v12, v13
	s_nop 1
	v_cvt_pk_bf16_f32 v142, v6, v7
	v_cvt_pk_bf16_f32 v143, v8, v9
	global_store_dwordx4 v[4:5], v[140:143], off offset:256 sc1

.LBB0_349:
	s_lshl_b32 s12, s47, 8
	v_mov_b32_e32 v2, v172
	v_mov_b32_e32 v5, v171
	s_or_b32 s12, s12, s42
	v_cvt_pk_bf16_f32 v140, v130, v131
	v_cvt_pk_bf16_f32 v141, v132, v133
	v_cvt_pk_bf16_f32 v142, v126, v127
	v_cvt_pk_bf16_f32 v143, v128, v129
	s_nop 0
	v_lshl_add_u32 v4, v2, 3, s12
	v_add_u32_e32 v146, s35, v5
	s_lshl_b32 s12, s54, 8
	v_add_u32_e32 v2, s12, v146
	v_ashrrev_i32_e32 v144, 8, v2
	s_waitcnt lgkmcnt(0)
	v_ashrrev_i32_e32 v145, 31, v144
	v_lshlrev_b64 v[144:145], 21, v[144:145]
	v_lshlrev_b32_e32 v2, 12, v146
	v_ashrrev_i32_e32 v5, 31, v4
	v_lshl_add_u64 v[144:145], s[28:29], 0, v[144:145]
	v_and_b32_e32 v2, 0xff000, v2
	v_lshl_add_u64 v[144:145], v[144:145], 0, v[2:3]
	v_lshlrev_b64 v[4:5], 1, v[4:5]
	v_lshl_add_u64 v[144:145], v[144:145], 0, v[4:5]
	global_store_dwordx4 v[144:145], v[140:143], off sc1
	v_add_u32_e32 v2, 16, v146
	s_nop 0
	v_cvt_pk_bf16_f32 v140, v98, v99
	v_cvt_pk_bf16_f32 v141, v100, v101
	v_cvt_pk_bf16_f32 v142, v94, v95
	v_cvt_pk_bf16_f32 v143, v96, v97
	global_store_dwordx4 v[144:145], v[140:143], off offset:256 sc1
	s_nop 1
	v_add_u32_e32 v140, s12, v2
	v_ashrrev_i32_e32 v144, 8, v140
	v_ashrrev_i32_e32 v145, 31, v144
	v_lshlrev_b64 v[144:145], 21, v[144:145]
	v_lshlrev_b32_e32 v2, 12, v2
	v_lshl_add_u64 v[144:145], s[28:29], 0, v[144:145]
	v_and_b32_e32 v2, 0xff000, v2
	v_lshl_add_u64 v[144:145], v[144:145], 0, v[2:3]
	v_cvt_pk_bf16_f32 v140, v122, v123
	v_lshl_add_u64 v[144:145], v[144:145], 0, v[4:5]
	v_cvt_pk_bf16_f32 v141, v124, v125
	v_cvt_pk_bf16_f32 v142, v118, v119
	v_cvt_pk_bf16_f32 v143, v120, v121
	global_store_dwordx4 v[144:145], v[140:143], off sc1
	v_add_u32_e32 v2, 32, v146
	s_nop 0
	v_cvt_pk_bf16_f32 v140, v90, v91
	v_cvt_pk_bf16_f32 v141, v92, v93
	v_cvt_pk_bf16_f32 v142, v86, v87
	v_cvt_pk_bf16_f32 v143, v88, v89
	global_store_dwordx4 v[144:145], v[140:143], off offset:256 sc1
	s_nop 1
	v_add_u32_e32 v140, s12, v2
	v_ashrrev_i32_e32 v144, 8, v140
	v_ashrrev_i32_e32 v145, 31, v144
	v_lshlrev_b64 v[144:145], 21, v[144:145]
	v_lshlrev_b32_e32 v2, 12, v2
	v_lshl_add_u64 v[144:145], s[28:29], 0, v[144:145]
	v_and_b32_e32 v2, 0xff000, v2
	v_lshl_add_u64 v[144:145], v[144:145], 0, v[2:3]
	v_cvt_pk_bf16_f32 v140, v114, v115
	v_lshl_add_u64 v[144:145], v[144:145], 0, v[4:5]
	v_cvt_pk_bf16_f32 v141, v116, v117
	v_cvt_pk_bf16_f32 v142, v110, v111
	v_cvt_pk_bf16_f32 v143, v112, v113
	global_store_dwordx4 v[144:145], v[140:143], off sc1
	v_add_u32_e32 v2, 48, v146
	s_nop 0
	v_cvt_pk_bf16_f32 v140, v82, v83
	v_cvt_pk_bf16_f32 v141, v84, v85
	v_cvt_pk_bf16_f32 v142, v78, v79
	v_cvt_pk_bf16_f32 v143, v80, v81
	global_store_dwordx4 v[144:145], v[140:143], off offset:256 sc1
	s_nop 1
	v_add_u32_e32 v140, s12, v2
	v_ashrrev_i32_e32 v144, 8, v140
	v_ashrrev_i32_e32 v145, 31, v144
	v_lshlrev_b64 v[144:145], 21, v[144:145]
	v_lshlrev_b32_e32 v2, 12, v2
	v_lshl_add_u64 v[144:145], s[28:29], 0, v[144:145]
	v_and_b32_e32 v2, 0xff000, v2
	v_lshl_add_u64 v[144:145], v[144:145], 0, v[2:3]
	v_cvt_pk_bf16_f32 v140, v106, v107
	v_lshl_add_u64 v[144:145], v[144:145], 0, v[4:5]
	v_cvt_pk_bf16_f32 v141, v108, v109
	v_cvt_pk_bf16_f32 v142, v102, v103
	v_cvt_pk_bf16_f32 v143, v104, v105
	global_store_dwordx4 v[144:145], v[140:143], off sc1
	v_add_u32_e32 v2, 0x80, v146
	s_nop 0
	v_cvt_pk_bf16_f32 v140, v74, v75
	v_cvt_pk_bf16_f32 v141, v76, v77
	v_cvt_pk_bf16_f32 v142, v70, v71
	v_cvt_pk_bf16_f32 v143, v72, v73
	global_store_dwordx4 v[144:145], v[140:143], off offset:256 sc1
	s_nop 1
	v_add_u32_e32 v140, s12, v2
	v_ashrrev_i32_e32 v144, 8, v140
	v_ashrrev_i32_e32 v145, 31, v144
	v_lshlrev_b64 v[144:145], 21, v[144:145]
	v_lshlrev_b32_e32 v2, 12, v2
	v_lshl_add_u64 v[144:145], s[28:29], 0, v[144:145]
	v_and_b32_e32 v2, 0xff000, v2
	v_lshl_add_u64 v[144:145], v[144:145], 0, v[2:3]
	v_cvt_pk_bf16_f32 v140, v66, v67
	v_lshl_add_u64 v[144:145], v[144:145], 0, v[4:5]
	v_cvt_pk_bf16_f32 v141, v68, v69
	v_cvt_pk_bf16_f32 v142, v62, v63
	v_cvt_pk_bf16_f32 v143, v64, v65
	global_store_dwordx4 v[144:145], v[140:143], off sc1
	v_add_u32_e32 v2, 0x90, v146
	s_nop 0
	v_cvt_pk_bf16_f32 v140, v34, v35
	v_cvt_pk_bf16_f32 v141, v36, v37
	v_cvt_pk_bf16_f32 v142, v30, v31
	v_cvt_pk_bf16_f32 v143, v32, v33
	global_store_dwordx4 v[144:145], v[140:143], off offset:256 sc1
	s_nop 1
	v_add_u32_e32 v140, s12, v2
	v_ashrrev_i32_e32 v144, 8, v140
	v_ashrrev_i32_e32 v145, 31, v144
	v_lshlrev_b64 v[144:145], 21, v[144:145]
	v_lshlrev_b32_e32 v2, 12, v2
	v_lshl_add_u64 v[144:145], s[28:29], 0, v[144:145]
	v_and_b32_e32 v2, 0xff000, v2
	v_lshl_add_u64 v[144:145], v[144:145], 0, v[2:3]
	v_cvt_pk_bf16_f32 v140, v58, v59
	v_lshl_add_u64 v[144:145], v[144:145], 0, v[4:5]
	v_cvt_pk_bf16_f32 v141, v60, v61
	v_cvt_pk_bf16_f32 v142, v54, v55
	v_cvt_pk_bf16_f32 v143, v56, v57
	global_store_dwordx4 v[144:145], v[140:143], off sc1
	v_add_u32_e32 v2, 0xa0, v146
	s_nop 0
	v_cvt_pk_bf16_f32 v140, v26, v27
	v_cvt_pk_bf16_f32 v141, v28, v29
	v_cvt_pk_bf16_f32 v142, v22, v23
	v_cvt_pk_bf16_f32 v143, v24, v25
	global_store_dwordx4 v[144:145], v[140:143], off offset:256 sc1
	s_nop 1
	v_add_u32_e32 v140, s12, v2
	v_ashrrev_i32_e32 v144, 8, v140
	v_ashrrev_i32_e32 v145, 31, v144
	v_lshlrev_b64 v[144:145], 21, v[144:145]
	v_lshlrev_b32_e32 v2, 12, v2
	v_lshl_add_u64 v[144:145], s[28:29], 0, v[144:145]
	v_and_b32_e32 v2, 0xff000, v2
	v_lshl_add_u64 v[144:145], v[144:145], 0, v[2:3]
	v_cvt_pk_bf16_f32 v140, v50, v51
	v_lshl_add_u64 v[144:145], v[144:145], 0, v[4:5]
	v_cvt_pk_bf16_f32 v141, v52, v53
	v_cvt_pk_bf16_f32 v142, v46, v47
	v_cvt_pk_bf16_f32 v143, v48, v49
	global_store_dwordx4 v[144:145], v[140:143], off sc1
	v_add_u32_e32 v2, 0xb0, v146
	s_nop 0
	v_cvt_pk_bf16_f32 v140, v18, v19
	v_cvt_pk_bf16_f32 v141, v20, v21
	v_cvt_pk_bf16_f32 v142, v14, v15
	v_cvt_pk_bf16_f32 v143, v16, v17
	global_store_dwordx4 v[144:145], v[140:143], off offset:256 sc1
	s_nop 1
	v_add_u32_e32 v140, s12, v2
	v_ashrrev_i32_e32 v144, 8, v140
	v_ashrrev_i32_e32 v145, 31, v144
	v_lshlrev_b64 v[144:145], 21, v[144:145]
	v_lshlrev_b32_e32 v2, 12, v2
	v_lshl_add_u64 v[144:145], s[28:29], 0, v[144:145]
	v_and_b32_e32 v2, 0xff000, v2
	v_lshl_add_u64 v[144:145], v[144:145], 0, v[2:3]
	v_cvt_pk_bf16_f32 v140, v42, v43
	v_cvt_pk_bf16_f32 v141, v44, v45
	v_cvt_pk_bf16_f32 v142, v38, v39
	v_cvt_pk_bf16_f32 v143, v40, v41
	v_lshl_add_u64 v[4:5], v[144:145], 0, v[4:5]
	global_store_dwordx4 v[4:5], v[140:143], off sc1
	s_nop 1
	v_cvt_pk_bf16_f32 v140, v10, v11
	v_cvt_pk_bf16_f32 v141, v12, v13
	v_cvt_pk_bf16_f32 v142, v6, v7
	v_cvt_pk_bf16_f32 v143, v8, v9
	global_store_dwordx4 v[4:5], v[140:143], off offset:256 sc1
	s_cbranch_execnz .LBB0_513
	s_branch .LBB0_353

.LBB0_353:
	s_cmp_gt_i32 s47, 3
	s_cselect_b64 s[18:19], -1, 0
	s_cmp_gt_u32 s47, 5
	s_cselect_b64 s[50:51], -1, 0
	s_cmp_gt_u32 s47, 7
	s_cselect_b64 s[80:81], -1, 0
	s_cmp_gt_u32 s47, 15
	s_cselect_b64 s[22:23], -1, 0
	s_cmp_lt_u32 s47, 12
	v_mov_b32_e32 v144, v171
	v_mov_b32_e32 v140, v172
	s_cselect_b64 s[14:15], -1, 0
	s_and_b64 s[12:13], s[14:15], exec
	v_lshlrev_b32_e32 v141, 3, v140
	v_add_u32_e32 v4, s42, v141
	s_mov_b32 s12, 0xfffff8
	s_cselect_b32 s12, s12, 0xfffff4
	v_lshlrev_b32_e32 v142, 1, v4
	s_add_i32 s12, s12, s47
	v_and_b32_e32 v142, 0xffffff80, v142
	v_lshl_add_u32 v148, s12, 8, v142
	s_lshl_b32 s12, s47, 8
	s_add_i32 s66, s12, 0xfffffa00
	v_cmp_eq_u32_e64 s[12:13], 0, v140
	s_lshl_b32 s20, s47, 2
	v_lshrrev_b32_e32 v140, 5, v4
	v_add3_u32 v140, s20, -16, v140
	s_movk_i32 s20, 0xc0
	v_mul_lo_u32 v140, v140, s20
	s_lshl_b32 s20, s54, 8
	v_ashrrev_i32_e32 v5, 31, v4
	v_cndmask_b32_e64 v146, 1.0, v177, s[14:15]
	v_and_b32_e32 v180, 56, v4
	v_and_b32_e32 v179, 24, v141
	s_add_i32 s20, s20, s35
	v_cmp_gt_i32_e64 s[16:17], 32, v4
	v_lshlrev_b64 v[150:151], 3, v[4:5]
	v_lshlrev_b32_e32 v2, 3, v180
	v_ashrrev_i32_e32 v149, 31, v148
	v_mov_b32_e32 v147, v146
	v_lshlrev_b32_e32 v142, 3, v179
	v_mov_b32_e32 v143, v3
	v_ashrrev_i32_e32 v141, 31, v140
	v_add_u32_e32 v144, s20, v144
	s_mov_b64 s[20:21], -1
	s_and_b64 vcc, exec, s[18:19]
	s_cbranch_vccz .LBB0_371
	s_and_b64 vcc, exec, s[50:51]
	s_cbranch_vccz .LBB0_368
	s_and_b64 vcc, exec, s[80:81]
	s_cbranch_vccz .LBB0_363
	s_and_b64 vcc, exec, s[22:23]
	s_cbranch_vccz .LBB0_360
	s_and_saveexec_b64 s[20:21], s[16:17]
	s_cbranch_execz .LBB0_359
	s_waitcnt lgkmcnt(0)
	v_ashrrev_i32_e32 v145, 31, v144
	v_lshlrev_b64 v[152:153], 8, v[144:145]
	v_lshl_add_u64 v[152:153], s[88:89], 0, v[152:153]
	v_lshl_add_u64 v[164:165], v[152:153], 0, v[150:151]
	flat_load_dwordx4 v[152:155], v[164:165]
	global_load_dwordx4 v[156:159], v[164:165], off offset:48
	global_load_dwordx4 v[160:163], v[164:165], off offset:32
	s_nop 0
	global_load_dwordx4 v[164:167], v[164:165], off offset:16
	v_mov_b32_e32 v168, v130
	v_mov_b32_e32 v169, v98
	v_readlane_b32 s70, v235, 45
	v_readlane_b32 s71, v235, 46
	s_waitcnt vmcnt(0) lgkmcnt(0)
	v_pk_mul_f32 v[168:169], v[168:169], v[152:153]
	s_nop 0
	v_sub_f32_e32 v145, v168, v169
	v_mov_b32_e32 v168, v131
	v_mov_b32_e32 v169, v99
	v_pk_mul_f32 v[168:169], v[168:169], v[154:155]
	s_nop 0
	v_sub_f32_e32 v181, v168, v169
	v_mov_b32_e32 v168, v132
	v_mov_b32_e32 v169, v100
	v_pk_mul_f32 v[168:169], v[168:169], v[164:165]
	s_nop 0
	v_sub_f32_e32 v182, v168, v169
	v_mov_b32_e32 v168, v133
	v_mov_b32_e32 v169, v101
	v_pk_mul_f32 v[168:169], v[168:169], v[166:167]
	s_nop 0
	v_sub_f32_e32 v183, v168, v169
	v_mov_b32_e32 v168, v126
	v_mov_b32_e32 v169, v94
	v_pk_mul_f32 v[168:169], v[168:169], v[160:161]
	s_nop 0
	v_sub_f32_e32 v184, v168, v169
	v_mov_b32_e32 v168, v127
	v_mov_b32_e32 v169, v95
	v_pk_mul_f32 v[168:169], v[168:169], v[162:163]
	s_nop 0
	v_sub_f32_e32 v185, v168, v169
	v_mov_b32_e32 v168, v128
	v_mov_b32_e32 v169, v96
	v_pk_mul_f32 v[168:169], v[168:169], v[156:157]
	s_nop 0
	v_sub_f32_e32 v186, v168, v169
	v_mov_b32_e32 v168, v129
	v_mov_b32_e32 v169, v97
	v_pk_mul_f32 v[168:169], v[168:169], v[158:159]
	s_nop 0
	v_sub_f32_e32 v187, v168, v169
	v_mov_b32_e32 v168, v98
	v_mov_b32_e32 v169, v130
	v_pk_mul_f32 v[152:153], v[168:169], v[152:153]
	s_nop 0
	v_add_f32_e32 v168, v152, v153
	v_mov_b32_e32 v152, v99
	v_mov_b32_e32 v153, v131
	v_pk_mul_f32 v[152:153], v[152:153], v[154:155]
	s_nop 0
	v_add_f32_e32 v169, v152, v153
	v_mov_b32_e32 v152, v100
	v_mov_b32_e32 v153, v132
	v_pk_mul_f32 v[152:153], v[152:153], v[164:165]
	s_nop 0
	v_add_f32_e32 v164, v152, v153
	v_mov_b32_e32 v152, v101
	v_mov_b32_e32 v153, v133
	v_pk_mul_f32 v[152:153], v[152:153], v[166:167]
	s_nop 0
	v_add_f32_e32 v165, v152, v153
	v_mov_b32_e32 v152, v94
	v_mov_b32_e32 v153, v126
	v_pk_mul_f32 v[152:153], v[152:153], v[160:161]
	s_nop 0
	v_add_f32_e32 v160, v152, v153
	v_mov_b32_e32 v152, v95
	v_mov_b32_e32 v153, v127
	v_pk_mul_f32 v[152:153], v[152:153], v[162:163]
	s_nop 0
	v_add_f32_e32 v161, v152, v153
	v_mov_b32_e32 v152, v96
	v_mov_b32_e32 v153, v128
	v_pk_mul_f32 v[152:153], v[152:153], v[156:157]
	s_nop 0
	v_add_f32_e32 v162, v152, v153
	v_mov_b32_e32 v152, v97
	v_mov_b32_e32 v153, v129
	v_pk_mul_f32 v[152:153], v[152:153], v[158:159]
	s_nop 0
	v_add_f32_e32 v159, v152, v153
	v_cvt_pk_bf16_f32 v152, v145, v181
	v_cvt_pk_bf16_f32 v153, v182, v183
	v_cvt_pk_bf16_f32 v154, v184, v185
	v_cvt_pk_bf16_f32 v155, v186, v187
	v_cvt_pk_bf16_f32 v156, v168, v169
	v_cvt_pk_bf16_f32 v157, v164, v165
	v_cvt_pk_bf16_f32 v158, v160, v161
	v_mov_b64_e32 v[160:161], s[70:71]
	v_mad_i64_i32 v[160:161], s[70:71], v144, s83, v[160:161]
	v_lshl_add_u64 v[160:161], v[4:5], 1, v[160:161]
	v_cvt_pk_bf16_f32 v159, v162, v159
	global_store_dwordx4 v[160:161], v[152:155], off offset:256 sc1
	global_store_dwordx4 v[160:161], v[156:159], off offset:320 sc1
	global_store_dwordx4 v[160:161], v[152:155], off offset:640 sc1
	global_store_dwordx4 v[160:161], v[156:159], off offset:704 sc1
	global_store_dwordx4 v[160:161], v[152:155], off offset:1024 sc1
	global_store_dwordx4 v[160:161], v[156:159], off offset:1088 sc1
	global_store_dwordx4 v[160:161], v[152:155], off offset:1408 sc1
	global_store_dwordx4 v[160:161], v[156:159], off offset:1472 sc1
	global_store_dwordx4 v[160:161], v[152:155], off offset:1792 sc1
	global_store_dwordx4 v[160:161], v[156:159], off offset:1856 sc1
	global_store_dwordx4 v[160:161], v[152:155], off offset:2176 sc1
	global_store_dwordx4 v[160:161], v[156:159], off offset:2240 sc1
	global_store_dwordx4 v[160:161], v[152:155], off offset:2560 sc1
	global_store_dwordx4 v[160:161], v[156:159], off offset:2624 sc1
	global_store_dwordx4 v[160:161], v[152:155], off offset:2944 sc1
	global_store_dwordx4 v[160:161], v[156:159], off offset:3008 sc1

.LBB0_360:
	s_andn2_b64 vcc, exec, s[20:21]
	s_cbranch_vccnz .LBB0_362
	s_waitcnt lgkmcnt(0)
	v_ashrrev_i32_e32 v145, 31, v144
	v_readlane_b32 s20, v235, 53
	v_lshlrev_b64 v[152:153], 9, v[144:145]
	v_readlane_b32 s21, v235, 54
	v_readlane_b32 s70, v235, 51
	s_nop 0
	v_lshl_add_u64 v[152:153], s[20:21], 0, v[152:153]
	v_lshl_add_u64 v[160:161], v[152:153], 0, v[2:3]
	flat_load_dwordx4 v[152:155], v[160:161]
	global_load_dwordx4 v[156:159], v[160:161], off offset:48
	global_load_dwordx4 v[166:169], v[160:161], off offset:32
	global_load_dwordx4 v[182:185], v[160:161], off offset:16
	s_and_b64 s[20:21], s[14:15], exec
	v_readlane_b32 s20, v235, 50
	v_readlane_b32 s21, v235, 52
	s_cselect_b32 s21, s20, s21
	v_readlane_b32 s20, v235, 49
	s_cselect_b32 s20, s20, s70
	s_waitcnt vmcnt(0) lgkmcnt(0)
	v_mov_b32_e32 v187, v154
	v_mov_b32_e32 v154, v153
	v_mov_b32_e32 v186, v152
	v_pk_mul_f32 v[152:153], v[98:99], v[154:155]
	v_mov_b32_e32 v189, v184
	v_mov_b32_e32 v184, v183
	v_pk_fma_f32 v[160:161], v[130:131], v[186:187], v[152:153] neg_lo:[0,0,1] neg_hi:[0,0,1]
	v_mov_b32_e32 v188, v182
	v_pk_mul_f32 v[152:153], v[100:101], v[184:185]
	v_mov_b32_e32 v183, v168
	v_mov_b32_e32 v168, v167
	v_pk_fma_f32 v[162:163], v[132:133], v[188:189], v[152:153] neg_lo:[0,0,1] neg_hi:[0,0,1]
	v_mov_b32_e32 v182, v166
	v_pk_mul_f32 v[152:153], v[94:95], v[168:169]
	v_mov_b32_e32 v191, v158
	v_mov_b32_e32 v158, v157
	v_pk_fma_f32 v[164:165], v[126:127], v[182:183], v[152:153] neg_lo:[0,0,1] neg_hi:[0,0,1]
	v_mov_b32_e32 v190, v156
	v_pk_mul_f32 v[152:153], v[96:97], v[158:159]
	v_pk_mul_f32 v[158:159], v[128:129], v[158:159]
	v_pk_fma_f32 v[166:167], v[128:129], v[190:191], v[152:153] neg_lo:[0,0,1] neg_hi:[0,0,1]
	v_pk_mul_f32 v[152:153], v[130:131], v[154:155]
	v_pk_mul_f32 v[154:155], v[132:133], v[184:185]
	v_pk_fma_f32 v[152:153], v[98:99], v[186:187], v[152:153]
	v_pk_fma_f32 v[156:157], v[100:101], v[188:189], v[154:155]
	v_pk_mul_f32 v[154:155], v[126:127], v[168:169]
	v_lshlrev_b64 v[168:169], 11, v[144:145]
	v_lshl_add_u64 v[168:169], s[20:21], 0, v[168:169]
	v_pk_fma_f32 v[154:155], v[94:95], v[182:183], v[154:155]
	v_lshl_add_u64 v[168:169], v[148:149], 1, v[168:169]
	v_lshlrev_b32_e32 v182, 1, v180
	v_mov_b32_e32 v183, v3
	v_lshl_add_u64 v[168:169], v[168:169], 0, v[182:183]
	v_mov_b32_e32 v182, v146
	v_mov_b32_e32 v183, v146
	v_pk_fma_f32 v[158:159], v[96:97], v[190:191], v[158:159]
	v_pk_mul_f32 v[162:163], v[182:183], v[162:163]
	v_pk_mul_f32 v[160:161], v[146:147], v[160:161]
	v_pk_mul_f32 v[152:153], v[146:147], v[152:153]
	v_pk_mul_f32 v[154:155], v[146:147], v[154:155]
	v_pk_mul_f32 v[166:167], v[182:183], v[166:167]
	v_pk_mul_f32 v[164:165], v[146:147], v[164:165]
	v_cvt_pk_bf16_f32 v160, v160, v161
	v_cvt_pk_bf16_f32 v161, v162, v163
	v_pk_mul_f32 v[156:157], v[182:183], v[156:157]
	v_cvt_pk_bf16_f32 v162, v164, v165
	v_cvt_pk_bf16_f32 v163, v166, v167
	global_store_dwordx4 v[168:169], v[160:163], off sc1
	v_pk_mul_f32 v[158:159], v[182:183], v[158:159]
	v_cvt_pk_bf16_f32 v152, v152, v153
	v_cvt_pk_bf16_f32 v153, v156, v157
	v_cvt_pk_bf16_f32 v154, v154, v155
	s_nop 0
	v_cvt_pk_bf16_f32 v155, v158, v159
	global_store_dwordx4 v[168:169], v[152:155], off offset:128 sc1

.LBB0_363:
	s_andn2_b64 vcc, exec, s[20:21]
	s_cbranch_vccnz .LBB0_367
	s_waitcnt lgkmcnt(0)
	v_ashrrev_i32_e32 v145, 31, v144
	v_readlane_b32 s20, v235, 47
	v_lshlrev_b64 v[156:157], 10, v[144:145]
	v_readlane_b32 s21, v235, 48
	v_cvt_pk_bf16_f32 v152, v130, v131
	v_cvt_pk_bf16_f32 v153, v132, v133
	v_cvt_pk_bf16_f32 v154, v126, v127
	v_cvt_pk_bf16_f32 v155, v128, v129
	s_nop 1
	v_lshl_add_u64 v[156:157], s[20:21], 0, v[156:157]
	v_lshl_add_u64 v[156:157], s[66:67], 1, v[156:157]
	v_lshl_add_u64 v[156:157], v[4:5], 1, v[156:157]
	global_store_dwordx4 v[156:157], v[152:155], off sc1
	s_nop 1
	v_cvt_pk_bf16_f32 v152, v98, v99
	v_cvt_pk_bf16_f32 v153, v100, v101
	v_cvt_pk_bf16_f32 v154, v94, v95
	v_cvt_pk_bf16_f32 v155, v96, v97
	global_store_dwordx4 v[156:157], v[152:155], off offset:256 sc1
	s_nop 1
	v_mul_f32_e32 v152, v131, v131
	v_mul_f32_e32 v153, v133, v133
	v_fmac_f32_e32 v152, v130, v130
	v_fmac_f32_e32 v153, v132, v132
	v_add_f32_e32 v152, v152, v153
	v_mul_f32_e32 v153, v127, v127
	v_mul_f32_e32 v154, v129, v129
	v_fmac_f32_e32 v153, v126, v126
	v_fmac_f32_e32 v154, v128, v128
	v_add_f32_e32 v153, v153, v154
	v_add_f32_e32 v152, v153, v152
	v_mul_f32_e32 v153, v99, v99
	v_mul_f32_e32 v154, v101, v101
	v_fmac_f32_e32 v153, v98, v98
	v_fmac_f32_e32 v154, v100, v100
	v_add_f32_e32 v153, v153, v154
	v_mul_f32_e32 v154, v95, v95
	v_mul_f32_e32 v155, v97, v97
	v_fmac_f32_e32 v154, v94, v94
	v_fmac_f32_e32 v155, v96, v96
	v_add_f32_e32 v154, v154, v155
	v_add_f32_e32 v153, v154, v153
	v_and_b32_e32 v154, 64, v178
	v_add_f32_e32 v152, v153, v152
	v_xor_b32_e32 v153, 16, v178
	v_add_u32_e32 v154, 64, v154
	v_cmp_lt_i32_e32 vcc, v153, v154
	s_nop 1
	v_cndmask_b32_e32 v153, v178, v153, vcc
	v_lshlrev_b32_e32 v153, 2, v153
	ds_bpermute_b32 v153, v153, v152
	s_waitcnt lgkmcnt(0)
	v_add_f32_e32 v152, v152, v153
	v_xor_b32_e32 v153, 32, v178
	v_cmp_lt_i32_e32 vcc, v153, v154
	s_nop 1
	v_cndmask_b32_e32 v153, v178, v153, vcc
	v_lshlrev_b32_e32 v153, 2, v153
	ds_bpermute_b32 v153, v153, v152
	s_and_saveexec_b64 s[20:21], s[12:13]
	s_cbranch_execz .LBB0_366
	s_waitcnt lgkmcnt(0)
	v_add_f32_e32 v154, v152, v153
	v_lshl_add_u64 v[152:153], v[144:145], 2, s[36:37]
	s_waitcnt vmcnt(0)
	flat_atomic_add_f32 v[152:153], v154

.LBB0_368:
	s_andn2_b64 vcc, exec, s[20:21]
	s_cbranch_vccnz .LBB0_370
	s_waitcnt lgkmcnt(0)
	v_ashrrev_i32_e32 v145, 31, v144
	s_waitcnt lgkmcnt(0)
	v_lshlrev_b64 v[152:153], 8, v[144:145]
	v_lshl_add_u64 v[152:153], s[88:89], 0, v[152:153]
	v_lshl_add_u64 v[164:165], v[152:153], 0, v[142:143]
	flat_load_dwordx4 v[152:155], v[164:165]
	global_load_dwordx4 v[156:159], v[164:165], off offset:48
	global_load_dwordx4 v[160:163], v[164:165], off offset:32
	s_nop 0
	global_load_dwordx4 v[164:167], v[164:165], off offset:16
	s_waitcnt vmcnt(0) lgkmcnt(0)
	v_mov_b32_e32 v169, v154
	v_mov_b32_e32 v154, v153
	v_mov_b32_e32 v168, v152
	v_pk_mul_f32 v[152:153], v[98:99], v[154:155]
	v_mov_b32_e32 v185, v166
	v_mov_b32_e32 v166, v165
	v_pk_fma_f32 v[182:183], v[130:131], v[168:169], v[152:153] neg_lo:[0,0,1] neg_hi:[0,0,1]
	v_mov_b32_e32 v184, v164
	v_pk_mul_f32 v[152:153], v[100:101], v[166:167]
	v_mov_b32_e32 v187, v162
	v_mov_b32_e32 v162, v161
	v_pk_fma_f32 v[164:165], v[132:133], v[184:185], v[152:153] neg_lo:[0,0,1] neg_hi:[0,0,1]
	v_mov_b32_e32 v186, v160
	v_pk_mul_f32 v[152:153], v[94:95], v[162:163]
	v_mov_b32_e32 v189, v158
	v_mov_b32_e32 v158, v157
	v_pk_fma_f32 v[160:161], v[126:127], v[186:187], v[152:153] neg_lo:[0,0,1] neg_hi:[0,0,1]
	v_mov_b32_e32 v188, v156
	v_pk_mul_f32 v[152:153], v[96:97], v[158:159]
	v_pk_mul_f32 v[158:159], v[128:129], v[158:159]
	v_pk_fma_f32 v[190:191], v[128:129], v[188:189], v[152:153] neg_lo:[0,0,1] neg_hi:[0,0,1]
	v_pk_mul_f32 v[152:153], v[130:131], v[154:155]
	v_pk_mul_f32 v[154:155], v[132:133], v[166:167]
	v_pk_fma_f32 v[152:153], v[98:99], v[168:169], v[152:153]
	v_pk_fma_f32 v[156:157], v[100:101], v[184:185], v[154:155]
	v_pk_mul_f32 v[154:155], v[126:127], v[162:163]
	v_pk_mul_f32 v[162:163], v[164:165], s[96:97] op_sel_hi:[1,0]
	v_pk_mul_f32 v[164:165], v[182:183], s[96:97] op_sel_hi:[1,0]
	v_pk_mul_f32 v[168:169], v[160:161], s[96:97] op_sel_hi:[1,0]
	v_cvt_pk_bf16_f32 v160, v164, v165
	v_mov_b64_e32 v[164:165], s[78:79]
	v_pk_mul_f32 v[166:167], v[190:191], s[96:97] op_sel_hi:[1,0]
	v_mad_i64_i32 v[164:165], s[20:21], v144, s83, v[164:165]
	v_pk_fma_f32 v[154:155], v[94:95], v[186:187], v[154:155]
	v_cvt_pk_bf16_f32 v161, v162, v163
	v_cvt_pk_bf16_f32 v162, v168, v169
	v_cvt_pk_bf16_f32 v163, v166, v167
	v_lshl_add_u64 v[164:165], v[140:141], 1, v[164:165]
	v_lshlrev_b32_e32 v166, 1, v179
	v_mov_b32_e32 v167, v3
	v_pk_fma_f32 v[158:159], v[96:97], v[188:189], v[158:159]
	v_lshl_add_u64 v[164:165], v[164:165], 0, v[166:167]
	v_pk_mul_f32 v[152:153], v[152:153], s[96:97] op_sel_hi:[1,0]
	v_pk_mul_f32 v[154:155], v[154:155], s[96:97] op_sel_hi:[1,0]
	global_store_dwordx4 v[164:165], v[160:163], off offset:256 sc1
	v_pk_mul_f32 v[156:157], v[156:157], s[96:97] op_sel_hi:[1,0]
	v_pk_mul_f32 v[158:159], v[158:159], s[96:97] op_sel_hi:[1,0]
	v_cvt_pk_bf16_f32 v152, v152, v153
	v_cvt_pk_bf16_f32 v153, v156, v157
	v_cvt_pk_bf16_f32 v154, v154, v155
	s_nop 0
	v_cvt_pk_bf16_f32 v155, v158, v159
	global_store_dwordx4 v[164:165], v[152:155], off offset:320 sc1

.LBB0_371:
	s_mul_i32 s70, s47, 0x180
	s_andn2_b64 vcc, exec, s[20:21]
	s_ashr_i32 s71, s70, 31
	s_cbranch_vccnz .LBB0_373
	v_pk_mul_f32 v[154:155], v[132:133], s[96:97] op_sel_hi:[1,0]
	s_waitcnt lgkmcnt(0)
	v_pk_mul_f32 v[152:153], v[130:131], s[96:97] op_sel_hi:[1,0]
	v_pk_mul_f32 v[156:157], v[128:129], s[96:97] op_sel_hi:[1,0]
	v_pk_mul_f32 v[158:159], v[126:127], s[96:97] op_sel_hi:[1,0]
	v_cvt_pk_bf16_f32 v152, v152, v153
	v_cvt_pk_bf16_f32 v153, v154, v155
	v_pk_mul_f32 v[160:161], v[94:95], s[96:97] op_sel_hi:[1,0]
	v_cvt_pk_bf16_f32 v154, v158, v159
	v_cvt_pk_bf16_f32 v155, v156, v157
	v_mov_b64_e32 v[156:157], s[78:79]
	v_mad_i64_i32 v[156:157], s[20:21], v144, s83, v[156:157]
	v_lshl_add_u64 v[156:157], s[70:71], 1, v[156:157]
	v_lshl_add_u64 v[156:157], v[4:5], 1, v[156:157]
	global_store_dwordx4 v[156:157], v[152:155], off sc1
	v_pk_mul_f32 v[158:159], v[96:97], s[96:97] op_sel_hi:[1,0]
	s_nop 0
	v_pk_mul_f32 v[154:155], v[100:101], s[96:97] op_sel_hi:[1,0]
	v_pk_mul_f32 v[152:153], v[98:99], s[96:97] op_sel_hi:[1,0]
	s_nop 0
	v_cvt_pk_bf16_f32 v152, v152, v153
	v_cvt_pk_bf16_f32 v153, v154, v155
	v_cvt_pk_bf16_f32 v154, v160, v161
	v_cvt_pk_bf16_f32 v155, v158, v159
	global_store_dwordx4 v[156:157], v[152:155], off offset:384 sc1
.LBB0_373:
	s_waitcnt lgkmcnt(0)
	v_cndmask_b32_e64 v145, 0, 1, s[18:19]
	v_cmp_ne_u32_e64 s[20:21], 1, v145
	v_cndmask_b32_e64 v145, 0, 1, s[50:51]
	v_add_u32_e32 v152, 16, v144
	s_mov_b64 s[86:87], -1
	s_andn2_b64 vcc, exec, s[18:19]
	v_cmp_ne_u32_e64 s[18:19], 1, v145
	s_cbranch_vccnz .LBB0_499
	s_and_b64 vcc, exec, s[18:19]
	s_mov_b64 s[50:51], -1
	s_cbranch_vccnz .LBB0_388
	s_andn2_b64 vcc, exec, s[80:81]
	s_cbranch_vccnz .LBB0_383
	s_andn2_b64 vcc, exec, s[22:23]
	s_cbranch_vccnz .LBB0_380
	s_and_saveexec_b64 s[50:51], s[16:17]
	s_cbranch_execz .LBB0_379
	s_waitcnt lgkmcnt(0)
	v_ashrrev_i32_e32 v153, 31, v152
	v_lshlrev_b64 v[154:155], 8, v[152:153]
	v_lshl_add_u64 v[154:155], s[88:89], 0, v[154:155]
	v_lshl_add_u64 v[166:167], v[154:155], 0, v[150:151]
	flat_load_dwordx4 v[154:157], v[166:167]
	global_load_dwordx4 v[158:161], v[166:167], off offset:48
	global_load_dwordx4 v[162:165], v[166:167], off offset:32
	s_nop 0
	global_load_dwordx4 v[166:169], v[166:167], off offset:16
	v_mov_b32_e32 v182, v122
	v_mov_b32_e32 v183, v90
	v_readlane_b32 s86, v235, 45
	v_readlane_b32 s87, v235, 46
	s_waitcnt vmcnt(0) lgkmcnt(0)
	v_pk_mul_f32 v[182:183], v[182:183], v[154:155]
	s_nop 0
	v_sub_f32_e32 v145, v182, v183
	v_mov_b32_e32 v182, v123
	v_mov_b32_e32 v183, v91
	v_pk_mul_f32 v[182:183], v[182:183], v[156:157]
	s_nop 0
	v_sub_f32_e32 v153, v182, v183
	v_mov_b32_e32 v182, v124
	v_mov_b32_e32 v183, v92
	v_pk_mul_f32 v[182:183], v[182:183], v[166:167]
	s_nop 0
	v_sub_f32_e32 v181, v182, v183
	v_mov_b32_e32 v182, v125
	v_mov_b32_e32 v183, v93
	v_pk_mul_f32 v[182:183], v[182:183], v[168:169]
	s_nop 0
	v_sub_f32_e32 v184, v182, v183
	v_mov_b32_e32 v182, v118
	v_mov_b32_e32 v183, v86
	v_pk_mul_f32 v[182:183], v[182:183], v[162:163]
	s_nop 0
	v_sub_f32_e32 v185, v182, v183
	v_mov_b32_e32 v182, v119
	v_mov_b32_e32 v183, v87
	v_pk_mul_f32 v[182:183], v[182:183], v[164:165]
	s_nop 0
	v_sub_f32_e32 v186, v182, v183
	v_mov_b32_e32 v182, v120
	v_mov_b32_e32 v183, v88
	v_pk_mul_f32 v[182:183], v[182:183], v[158:159]
	s_nop 0
	v_sub_f32_e32 v187, v182, v183
	v_mov_b32_e32 v182, v121
	v_mov_b32_e32 v183, v89
	v_pk_mul_f32 v[182:183], v[182:183], v[160:161]
	s_nop 0
	v_sub_f32_e32 v188, v182, v183
	v_mov_b32_e32 v182, v90
	v_mov_b32_e32 v183, v122
	v_pk_mul_f32 v[154:155], v[182:183], v[154:155]
	s_nop 0
	v_add_f32_e32 v182, v154, v155
	v_mov_b32_e32 v154, v91
	v_mov_b32_e32 v155, v123
	v_pk_mul_f32 v[154:155], v[154:155], v[156:157]
	s_nop 0
	v_add_f32_e32 v183, v154, v155
	v_mov_b32_e32 v154, v92
	v_mov_b32_e32 v155, v124
	v_pk_mul_f32 v[154:155], v[154:155], v[166:167]
	s_nop 0
	v_add_f32_e32 v166, v154, v155
	v_mov_b32_e32 v154, v93
	v_mov_b32_e32 v155, v125
	v_pk_mul_f32 v[154:155], v[154:155], v[168:169]
	s_nop 0
	v_add_f32_e32 v167, v154, v155
	v_mov_b32_e32 v154, v86
	v_mov_b32_e32 v155, v118
	v_pk_mul_f32 v[154:155], v[154:155], v[162:163]
	s_nop 0
	v_add_f32_e32 v162, v154, v155
	v_mov_b32_e32 v154, v87
	v_mov_b32_e32 v155, v119
	v_pk_mul_f32 v[154:155], v[154:155], v[164:165]
	s_nop 0
	v_add_f32_e32 v163, v154, v155
	v_mov_b32_e32 v154, v88
	v_mov_b32_e32 v155, v120
	v_pk_mul_f32 v[154:155], v[154:155], v[158:159]
	s_nop 0
	v_add_f32_e32 v164, v154, v155
	v_mov_b32_e32 v154, v89
	v_mov_b32_e32 v155, v121
	v_pk_mul_f32 v[154:155], v[154:155], v[160:161]
	s_nop 0
	v_add_f32_e32 v161, v154, v155
	v_cvt_pk_bf16_f32 v154, v145, v153
	v_cvt_pk_bf16_f32 v155, v181, v184
	v_cvt_pk_bf16_f32 v156, v185, v186
	v_cvt_pk_bf16_f32 v157, v187, v188
	v_cvt_pk_bf16_f32 v158, v182, v183
	v_cvt_pk_bf16_f32 v159, v166, v167
	v_cvt_pk_bf16_f32 v160, v162, v163
	v_mov_b64_e32 v[162:163], s[86:87]
	v_mad_i64_i32 v[162:163], s[86:87], v152, s83, v[162:163]
	v_lshl_add_u64 v[162:163], v[4:5], 1, v[162:163]
	v_cvt_pk_bf16_f32 v161, v164, v161
	global_store_dwordx4 v[162:163], v[154:157], off offset:256 sc1
	global_store_dwordx4 v[162:163], v[158:161], off offset:320 sc1
	global_store_dwordx4 v[162:163], v[154:157], off offset:640 sc1
	global_store_dwordx4 v[162:163], v[158:161], off offset:704 sc1
	global_store_dwordx4 v[162:163], v[154:157], off offset:1024 sc1
	global_store_dwordx4 v[162:163], v[158:161], off offset:1088 sc1
	global_store_dwordx4 v[162:163], v[154:157], off offset:1408 sc1
	global_store_dwordx4 v[162:163], v[158:161], off offset:1472 sc1
	global_store_dwordx4 v[162:163], v[154:157], off offset:1792 sc1
	global_store_dwordx4 v[162:163], v[158:161], off offset:1856 sc1
	global_store_dwordx4 v[162:163], v[154:157], off offset:2176 sc1
	global_store_dwordx4 v[162:163], v[158:161], off offset:2240 sc1
	global_store_dwordx4 v[162:163], v[154:157], off offset:2560 sc1
	global_store_dwordx4 v[162:163], v[158:161], off offset:2624 sc1
	global_store_dwordx4 v[162:163], v[154:157], off offset:2944 sc1
	global_store_dwordx4 v[162:163], v[158:161], off offset:3008 sc1

.LBB0_380:
	s_andn2_b64 vcc, exec, s[50:51]
	s_cbranch_vccnz .LBB0_382
	s_waitcnt lgkmcnt(0)
	v_ashrrev_i32_e32 v153, 31, v152
	v_readlane_b32 s50, v235, 53
	v_lshlrev_b64 v[154:155], 9, v[152:153]
	v_readlane_b32 s51, v235, 54
	v_readlane_b32 s86, v235, 51
	s_nop 0
	v_lshl_add_u64 v[154:155], s[50:51], 0, v[154:155]
	v_lshl_add_u64 v[162:163], v[154:155], 0, v[2:3]
	flat_load_dwordx4 v[154:157], v[162:163]
	global_load_dwordx4 v[158:161], v[162:163], off offset:48
	global_load_dwordx4 v[182:185], v[162:163], off offset:32
	global_load_dwordx4 v[186:189], v[162:163], off offset:16
	s_and_b64 s[50:51], s[14:15], exec
	v_readlane_b32 s50, v235, 50
	v_readlane_b32 s51, v235, 52
	s_cselect_b32 s51, s50, s51
	v_readlane_b32 s50, v235, 49
	s_cselect_b32 s50, s50, s86
	s_waitcnt vmcnt(0) lgkmcnt(0)
	v_mov_b32_e32 v191, v156
	v_mov_b32_e32 v156, v155
	v_mov_b32_e32 v190, v154
	v_pk_mul_f32 v[154:155], v[90:91], v[156:157]
	v_mov_b32_e32 v193, v188
	v_mov_b32_e32 v188, v187
	v_pk_fma_f32 v[162:163], v[122:123], v[190:191], v[154:155] neg_lo:[0,0,1] neg_hi:[0,0,1]
	v_mov_b32_e32 v192, v186
	v_pk_mul_f32 v[154:155], v[92:93], v[188:189]
	v_mov_b32_e32 v187, v184
	v_mov_b32_e32 v184, v183
	v_pk_fma_f32 v[164:165], v[124:125], v[192:193], v[154:155] neg_lo:[0,0,1] neg_hi:[0,0,1]
	v_mov_b32_e32 v186, v182
	v_pk_mul_f32 v[154:155], v[86:87], v[184:185]
	v_mov_b32_e32 v183, v160
	v_mov_b32_e32 v160, v159
	v_pk_fma_f32 v[166:167], v[118:119], v[186:187], v[154:155] neg_lo:[0,0,1] neg_hi:[0,0,1]
	v_mov_b32_e32 v182, v158
	v_pk_mul_f32 v[154:155], v[88:89], v[160:161]
	v_pk_mul_f32 v[160:161], v[120:121], v[160:161]
	v_pk_fma_f32 v[168:169], v[120:121], v[182:183], v[154:155] neg_lo:[0,0,1] neg_hi:[0,0,1]
	v_pk_fma_f32 v[160:161], v[88:89], v[182:183], v[160:161]
	v_lshlrev_b64 v[182:183], 11, v[152:153]
	v_pk_mul_f32 v[154:155], v[122:123], v[156:157]
	v_pk_mul_f32 v[156:157], v[124:125], v[188:189]
	v_lshl_add_u64 v[182:183], s[50:51], 0, v[182:183]
	v_pk_fma_f32 v[158:159], v[92:93], v[192:193], v[156:157]
	v_pk_mul_f32 v[156:157], v[118:119], v[184:185]
	v_lshl_add_u64 v[182:183], v[148:149], 1, v[182:183]
	v_lshlrev_b32_e32 v184, 1, v180
	v_mov_b32_e32 v185, v3
	v_pk_fma_f32 v[154:155], v[90:91], v[190:191], v[154:155]
	v_pk_fma_f32 v[156:157], v[86:87], v[186:187], v[156:157]
	v_lshl_add_u64 v[182:183], v[182:183], 0, v[184:185]
	v_mov_b32_e32 v184, v146
	v_mov_b32_e32 v185, v146
	v_pk_mul_f32 v[164:165], v[184:185], v[164:165]
	v_pk_mul_f32 v[162:163], v[146:147], v[162:163]
	v_pk_mul_f32 v[154:155], v[146:147], v[154:155]
	v_pk_mul_f32 v[156:157], v[146:147], v[156:157]
	v_pk_mul_f32 v[168:169], v[184:185], v[168:169]
	v_pk_mul_f32 v[166:167], v[146:147], v[166:167]
	v_cvt_pk_bf16_f32 v162, v162, v163
	v_cvt_pk_bf16_f32 v163, v164, v165
	v_pk_mul_f32 v[158:159], v[184:185], v[158:159]
	v_cvt_pk_bf16_f32 v164, v166, v167
	v_cvt_pk_bf16_f32 v165, v168, v169
	global_store_dwordx4 v[182:183], v[162:165], off sc1
	v_pk_mul_f32 v[160:161], v[184:185], v[160:161]
	v_cvt_pk_bf16_f32 v154, v154, v155
	v_cvt_pk_bf16_f32 v155, v158, v159
	v_cvt_pk_bf16_f32 v156, v156, v157
	s_nop 0
	v_cvt_pk_bf16_f32 v157, v160, v161
	global_store_dwordx4 v[182:183], v[154:157], off offset:128 sc1

.LBB0_383:
	s_andn2_b64 vcc, exec, s[50:51]
	s_cbranch_vccnz .LBB0_387
	s_waitcnt lgkmcnt(0)
	v_ashrrev_i32_e32 v153, 31, v152
	v_readlane_b32 s50, v235, 47
	v_lshlrev_b64 v[158:159], 10, v[152:153]
	v_readlane_b32 s51, v235, 48
	v_cvt_pk_bf16_f32 v154, v122, v123
	v_mul_f32_e32 v145, v123, v123
	v_mul_f32_e32 v153, v125, v125
	v_lshl_add_u64 v[158:159], s[50:51], 0, v[158:159]
	v_lshl_add_u64 v[158:159], s[66:67], 1, v[158:159]
	v_lshl_add_u64 v[158:159], v[4:5], 1, v[158:159]
	v_cvt_pk_bf16_f32 v155, v124, v125
	v_cvt_pk_bf16_f32 v156, v118, v119
	v_cvt_pk_bf16_f32 v157, v120, v121
	global_store_dwordx4 v[158:159], v[154:157], off sc1
	v_fmac_f32_e32 v145, v122, v122
	v_fmac_f32_e32 v153, v124, v124
	v_cvt_pk_bf16_f32 v154, v90, v91
	v_cvt_pk_bf16_f32 v155, v92, v93
	v_cvt_pk_bf16_f32 v156, v86, v87
	v_cvt_pk_bf16_f32 v157, v88, v89
	global_store_dwordx4 v[158:159], v[154:157], off offset:256 sc1
	v_add_f32_e32 v145, v145, v153
	v_mul_f32_e32 v153, v119, v119
	v_mul_f32_e32 v154, v121, v121
	v_fmac_f32_e32 v153, v118, v118
	v_fmac_f32_e32 v154, v120, v120
	v_add_f32_e32 v153, v153, v154
	v_add_f32_e32 v145, v153, v145
	v_mul_f32_e32 v153, v91, v91
	v_mul_f32_e32 v154, v93, v93
	v_fmac_f32_e32 v153, v90, v90
	v_fmac_f32_e32 v154, v92, v92
	v_add_f32_e32 v153, v153, v154
	v_mul_f32_e32 v154, v87, v87
	v_mul_f32_e32 v155, v89, v89
	v_fmac_f32_e32 v154, v86, v86
	v_fmac_f32_e32 v155, v88, v88
	v_add_f32_e32 v154, v154, v155
	v_add_f32_e32 v153, v154, v153
	v_and_b32_e32 v154, 64, v178
	v_add_f32_e32 v145, v153, v145
	v_xor_b32_e32 v153, 16, v178
	v_add_u32_e32 v154, 64, v154
	v_cmp_lt_i32_e32 vcc, v153, v154
	s_nop 1
	v_cndmask_b32_e32 v153, v178, v153, vcc
	v_lshlrev_b32_e32 v153, 2, v153
	ds_bpermute_b32 v153, v153, v145
	s_waitcnt lgkmcnt(0)
	v_add_f32_e32 v145, v145, v153
	v_xor_b32_e32 v153, 32, v178
	v_cmp_lt_i32_e32 vcc, v153, v154
	s_nop 1
	v_cndmask_b32_e32 v153, v178, v153, vcc
	v_lshlrev_b32_e32 v153, 2, v153
	ds_bpermute_b32 v153, v153, v145
	s_and_saveexec_b64 s[50:51], s[12:13]
	s_cbranch_execz .LBB0_386
	s_waitcnt lgkmcnt(0)
	v_add_f32_e32 v153, v145, v153
	v_ashrrev_i32_e32 v145, 31, v144
	v_lshl_add_u64 v[154:155], v[144:145], 2, s[36:37]
	s_waitcnt vmcnt(0)
	flat_atomic_add_f32 v[154:155], v153 offset:64

.LBB0_388:
	s_andn2_b64 vcc, exec, s[50:51]
	s_cbranch_vccnz .LBB0_390
	s_waitcnt lgkmcnt(0)
	v_ashrrev_i32_e32 v153, 31, v152
	v_lshlrev_b64 v[154:155], 8, v[152:153]
	v_lshl_add_u64 v[154:155], s[88:89], 0, v[154:155]
	v_lshl_add_u64 v[166:167], v[154:155], 0, v[142:143]
	flat_load_dwordx4 v[154:157], v[166:167]
	global_load_dwordx4 v[158:161], v[166:167], off offset:48
	global_load_dwordx4 v[162:165], v[166:167], off offset:32
	s_nop 0
	global_load_dwordx4 v[166:169], v[166:167], off offset:16
	s_waitcnt vmcnt(0) lgkmcnt(0)
	v_mov_b32_e32 v183, v156
	v_mov_b32_e32 v156, v155
	v_mov_b32_e32 v182, v154
	v_pk_mul_f32 v[154:155], v[90:91], v[156:157]
	v_mov_b32_e32 v187, v168
	v_mov_b32_e32 v168, v167
	v_pk_fma_f32 v[184:185], v[122:123], v[182:183], v[154:155] neg_lo:[0,0,1] neg_hi:[0,0,1]
	v_mov_b32_e32 v186, v166
	v_pk_mul_f32 v[154:155], v[92:93], v[168:169]
	v_mov_b32_e32 v189, v164
	v_mov_b32_e32 v164, v163
	v_pk_fma_f32 v[166:167], v[124:125], v[186:187], v[154:155] neg_lo:[0,0,1] neg_hi:[0,0,1]
	v_mov_b32_e32 v188, v162
	v_pk_mul_f32 v[154:155], v[86:87], v[164:165]
	v_mov_b32_e32 v191, v160
	v_mov_b32_e32 v160, v159
	v_pk_fma_f32 v[162:163], v[118:119], v[188:189], v[154:155] neg_lo:[0,0,1] neg_hi:[0,0,1]
	v_mov_b32_e32 v190, v158
	v_pk_mul_f32 v[154:155], v[88:89], v[160:161]
	v_pk_mul_f32 v[160:161], v[120:121], v[160:161]
	v_pk_fma_f32 v[192:193], v[120:121], v[190:191], v[154:155] neg_lo:[0,0,1] neg_hi:[0,0,1]
	v_pk_mul_f32 v[154:155], v[122:123], v[156:157]
	v_pk_mul_f32 v[156:157], v[124:125], v[168:169]
	v_pk_fma_f32 v[154:155], v[90:91], v[182:183], v[154:155]
	v_pk_fma_f32 v[158:159], v[92:93], v[186:187], v[156:157]
	v_pk_mul_f32 v[156:157], v[118:119], v[164:165]
	v_pk_mul_f32 v[164:165], v[166:167], s[96:97] op_sel_hi:[1,0]
	v_pk_mul_f32 v[166:167], v[184:185], s[96:97] op_sel_hi:[1,0]
	v_pk_mul_f32 v[182:183], v[162:163], s[96:97] op_sel_hi:[1,0]
	v_cvt_pk_bf16_f32 v162, v166, v167
	v_mov_b64_e32 v[166:167], s[78:79]
	v_pk_mul_f32 v[168:169], v[192:193], s[96:97] op_sel_hi:[1,0]
	v_mad_i64_i32 v[166:167], s[50:51], v152, s83, v[166:167]
	v_pk_fma_f32 v[156:157], v[86:87], v[188:189], v[156:157]
	v_cvt_pk_bf16_f32 v163, v164, v165
	v_cvt_pk_bf16_f32 v164, v182, v183
	v_cvt_pk_bf16_f32 v165, v168, v169
	v_lshl_add_u64 v[166:167], v[140:141], 1, v[166:167]
	v_lshlrev_b32_e32 v168, 1, v179
	v_mov_b32_e32 v169, v3
	v_pk_fma_f32 v[160:161], v[88:89], v[190:191], v[160:161]
	v_lshl_add_u64 v[166:167], v[166:167], 0, v[168:169]
	v_pk_mul_f32 v[154:155], v[154:155], s[96:97] op_sel_hi:[1,0]
	v_pk_mul_f32 v[156:157], v[156:157], s[96:97] op_sel_hi:[1,0]
	global_store_dwordx4 v[166:167], v[162:165], off offset:256 sc1
	v_pk_mul_f32 v[158:159], v[158:159], s[96:97] op_sel_hi:[1,0]
	v_pk_mul_f32 v[160:161], v[160:161], s[96:97] op_sel_hi:[1,0]
	v_cvt_pk_bf16_f32 v154, v154, v155
	v_cvt_pk_bf16_f32 v155, v158, v159
	v_cvt_pk_bf16_f32 v156, v156, v157
	s_nop 0
	v_cvt_pk_bf16_f32 v157, v160, v161
	global_store_dwordx4 v[166:167], v[154:157], off offset:320 sc1

.LBB0_392:
	s_and_b64 vcc, exec, s[18:19]
	s_cbranch_vccnz .LBB0_406
	s_andn2_b64 vcc, exec, s[80:81]
	s_cbranch_vccnz .LBB0_401
	s_andn2_b64 vcc, exec, s[22:23]
	s_cbranch_vccnz .LBB0_398
	s_and_saveexec_b64 s[50:51], s[16:17]
	s_cbranch_execz .LBB0_397
	s_waitcnt lgkmcnt(0)
	v_ashrrev_i32_e32 v153, 31, v152
	v_lshlrev_b64 v[154:155], 8, v[152:153]
	v_lshl_add_u64 v[154:155], s[88:89], 0, v[154:155]
	v_lshl_add_u64 v[166:167], v[154:155], 0, v[150:151]
	flat_load_dwordx4 v[154:157], v[166:167]
	global_load_dwordx4 v[158:161], v[166:167], off offset:48
	global_load_dwordx4 v[162:165], v[166:167], off offset:32
	s_nop 0
	global_load_dwordx4 v[166:169], v[166:167], off offset:16
	v_mov_b32_e32 v182, v114
	v_mov_b32_e32 v183, v82
	v_readlane_b32 s86, v235, 45
	v_readlane_b32 s87, v235, 46
	s_waitcnt vmcnt(0) lgkmcnt(0)
	v_pk_mul_f32 v[182:183], v[182:183], v[154:155]
	s_nop 0
	v_sub_f32_e32 v145, v182, v183
	v_mov_b32_e32 v182, v115
	v_mov_b32_e32 v183, v83
	v_pk_mul_f32 v[182:183], v[182:183], v[156:157]
	s_nop 0
	v_sub_f32_e32 v153, v182, v183
	v_mov_b32_e32 v182, v116
	v_mov_b32_e32 v183, v84
	v_pk_mul_f32 v[182:183], v[182:183], v[166:167]
	s_nop 0
	v_sub_f32_e32 v181, v182, v183
	v_mov_b32_e32 v182, v117
	v_mov_b32_e32 v183, v85
	v_pk_mul_f32 v[182:183], v[182:183], v[168:169]
	s_nop 0
	v_sub_f32_e32 v184, v182, v183
	v_mov_b32_e32 v182, v110
	v_mov_b32_e32 v183, v78
	v_pk_mul_f32 v[182:183], v[182:183], v[162:163]
	s_nop 0
	v_sub_f32_e32 v185, v182, v183
	v_mov_b32_e32 v182, v111
	v_mov_b32_e32 v183, v79
	v_pk_mul_f32 v[182:183], v[182:183], v[164:165]
	s_nop 0
	v_sub_f32_e32 v186, v182, v183
	v_mov_b32_e32 v182, v112
	v_mov_b32_e32 v183, v80
	v_pk_mul_f32 v[182:183], v[182:183], v[158:159]
	s_nop 0
	v_sub_f32_e32 v187, v182, v183
	v_mov_b32_e32 v182, v113
	v_mov_b32_e32 v183, v81
	v_pk_mul_f32 v[182:183], v[182:183], v[160:161]
	s_nop 0
	v_sub_f32_e32 v188, v182, v183
	v_mov_b32_e32 v182, v82
	v_mov_b32_e32 v183, v114
	v_pk_mul_f32 v[154:155], v[182:183], v[154:155]
	s_nop 0
	v_add_f32_e32 v182, v154, v155
	v_mov_b32_e32 v154, v83
	v_mov_b32_e32 v155, v115
	v_pk_mul_f32 v[154:155], v[154:155], v[156:157]
	s_nop 0
	v_add_f32_e32 v183, v154, v155
	v_mov_b32_e32 v154, v84
	v_mov_b32_e32 v155, v116
	v_pk_mul_f32 v[154:155], v[154:155], v[166:167]
	s_nop 0
	v_add_f32_e32 v166, v154, v155
	v_mov_b32_e32 v154, v85
	v_mov_b32_e32 v155, v117
	v_pk_mul_f32 v[154:155], v[154:155], v[168:169]
	s_nop 0
	v_add_f32_e32 v167, v154, v155
	v_mov_b32_e32 v154, v78
	v_mov_b32_e32 v155, v110
	v_pk_mul_f32 v[154:155], v[154:155], v[162:163]
	s_nop 0
	v_add_f32_e32 v162, v154, v155
	v_mov_b32_e32 v154, v79
	v_mov_b32_e32 v155, v111
	v_pk_mul_f32 v[154:155], v[154:155], v[164:165]
	s_nop 0
	v_add_f32_e32 v163, v154, v155
	v_mov_b32_e32 v154, v80
	v_mov_b32_e32 v155, v112
	v_pk_mul_f32 v[154:155], v[154:155], v[158:159]
	s_nop 0
	v_add_f32_e32 v164, v154, v155
	v_mov_b32_e32 v154, v81
	v_mov_b32_e32 v155, v113
	v_pk_mul_f32 v[154:155], v[154:155], v[160:161]
	s_nop 0
	v_add_f32_e32 v161, v154, v155
	v_cvt_pk_bf16_f32 v154, v145, v153
	v_cvt_pk_bf16_f32 v155, v181, v184
	v_cvt_pk_bf16_f32 v156, v185, v186
	v_cvt_pk_bf16_f32 v157, v187, v188
	v_cvt_pk_bf16_f32 v158, v182, v183
	v_cvt_pk_bf16_f32 v159, v166, v167
	v_cvt_pk_bf16_f32 v160, v162, v163
	v_mov_b64_e32 v[162:163], s[86:87]
	v_mad_i64_i32 v[162:163], s[86:87], v152, s83, v[162:163]
	v_lshl_add_u64 v[162:163], v[4:5], 1, v[162:163]
	v_cvt_pk_bf16_f32 v161, v164, v161
	global_store_dwordx4 v[162:163], v[154:157], off offset:256 sc1
	global_store_dwordx4 v[162:163], v[158:161], off offset:320 sc1
	global_store_dwordx4 v[162:163], v[154:157], off offset:640 sc1
	global_store_dwordx4 v[162:163], v[158:161], off offset:704 sc1
	global_store_dwordx4 v[162:163], v[154:157], off offset:1024 sc1
	global_store_dwordx4 v[162:163], v[158:161], off offset:1088 sc1
	global_store_dwordx4 v[162:163], v[154:157], off offset:1408 sc1
	global_store_dwordx4 v[162:163], v[158:161], off offset:1472 sc1
	global_store_dwordx4 v[162:163], v[154:157], off offset:1792 sc1
	global_store_dwordx4 v[162:163], v[158:161], off offset:1856 sc1
	global_store_dwordx4 v[162:163], v[154:157], off offset:2176 sc1
	global_store_dwordx4 v[162:163], v[158:161], off offset:2240 sc1
	global_store_dwordx4 v[162:163], v[154:157], off offset:2560 sc1
	global_store_dwordx4 v[162:163], v[158:161], off offset:2624 sc1
	global_store_dwordx4 v[162:163], v[154:157], off offset:2944 sc1
	global_store_dwordx4 v[162:163], v[158:161], off offset:3008 sc1

.LBB0_398:
	s_andn2_b64 vcc, exec, s[50:51]
	s_cbranch_vccnz .LBB0_400
	s_waitcnt lgkmcnt(0)
	v_ashrrev_i32_e32 v153, 31, v152
	v_readlane_b32 s50, v235, 53
	v_lshlrev_b64 v[154:155], 9, v[152:153]
	v_readlane_b32 s51, v235, 54
	v_readlane_b32 s86, v235, 51
	s_nop 0
	v_lshl_add_u64 v[154:155], s[50:51], 0, v[154:155]
	v_lshl_add_u64 v[162:163], v[154:155], 0, v[2:3]
	flat_load_dwordx4 v[154:157], v[162:163]
	global_load_dwordx4 v[158:161], v[162:163], off offset:48
	global_load_dwordx4 v[182:185], v[162:163], off offset:32
	global_load_dwordx4 v[186:189], v[162:163], off offset:16
	s_and_b64 s[50:51], s[14:15], exec
	v_readlane_b32 s50, v235, 50
	v_readlane_b32 s51, v235, 52
	s_cselect_b32 s51, s50, s51
	v_readlane_b32 s50, v235, 49
	s_cselect_b32 s50, s50, s86
	s_waitcnt vmcnt(0) lgkmcnt(0)
	v_mov_b32_e32 v191, v156
	v_mov_b32_e32 v156, v155
	v_mov_b32_e32 v190, v154
	v_pk_mul_f32 v[154:155], v[82:83], v[156:157]
	v_mov_b32_e32 v193, v188
	v_mov_b32_e32 v188, v187
	v_pk_fma_f32 v[162:163], v[114:115], v[190:191], v[154:155] neg_lo:[0,0,1] neg_hi:[0,0,1]
	v_mov_b32_e32 v192, v186
	v_pk_mul_f32 v[154:155], v[84:85], v[188:189]
	v_mov_b32_e32 v187, v184
	v_mov_b32_e32 v184, v183
	v_pk_fma_f32 v[164:165], v[116:117], v[192:193], v[154:155] neg_lo:[0,0,1] neg_hi:[0,0,1]
	v_mov_b32_e32 v186, v182
	v_pk_mul_f32 v[154:155], v[78:79], v[184:185]
	v_mov_b32_e32 v183, v160
	v_mov_b32_e32 v160, v159
	v_pk_fma_f32 v[166:167], v[110:111], v[186:187], v[154:155] neg_lo:[0,0,1] neg_hi:[0,0,1]
	v_mov_b32_e32 v182, v158
	v_pk_mul_f32 v[154:155], v[80:81], v[160:161]
	v_pk_mul_f32 v[160:161], v[112:113], v[160:161]
	v_pk_fma_f32 v[168:169], v[112:113], v[182:183], v[154:155] neg_lo:[0,0,1] neg_hi:[0,0,1]
	v_pk_fma_f32 v[160:161], v[80:81], v[182:183], v[160:161]
	v_lshlrev_b64 v[182:183], 11, v[152:153]
	v_pk_mul_f32 v[154:155], v[114:115], v[156:157]
	v_pk_mul_f32 v[156:157], v[116:117], v[188:189]
	v_lshl_add_u64 v[182:183], s[50:51], 0, v[182:183]
	v_pk_fma_f32 v[158:159], v[84:85], v[192:193], v[156:157]
	v_pk_mul_f32 v[156:157], v[110:111], v[184:185]
	v_lshl_add_u64 v[182:183], v[148:149], 1, v[182:183]
	v_lshlrev_b32_e32 v184, 1, v180
	v_mov_b32_e32 v185, v3
	v_pk_fma_f32 v[154:155], v[82:83], v[190:191], v[154:155]
	v_pk_fma_f32 v[156:157], v[78:79], v[186:187], v[156:157]
	v_lshl_add_u64 v[182:183], v[182:183], 0, v[184:185]
	v_mov_b32_e32 v184, v146
	v_mov_b32_e32 v185, v146
	v_pk_mul_f32 v[164:165], v[184:185], v[164:165]
	v_pk_mul_f32 v[162:163], v[146:147], v[162:163]
	v_pk_mul_f32 v[154:155], v[146:147], v[154:155]
	v_pk_mul_f32 v[156:157], v[146:147], v[156:157]
	v_pk_mul_f32 v[168:169], v[184:185], v[168:169]
	v_pk_mul_f32 v[166:167], v[146:147], v[166:167]
	v_cvt_pk_bf16_f32 v162, v162, v163
	v_cvt_pk_bf16_f32 v163, v164, v165
	v_pk_mul_f32 v[158:159], v[184:185], v[158:159]
	v_cvt_pk_bf16_f32 v164, v166, v167
	v_cvt_pk_bf16_f32 v165, v168, v169
	global_store_dwordx4 v[182:183], v[162:165], off sc1
	v_pk_mul_f32 v[160:161], v[184:185], v[160:161]
	v_cvt_pk_bf16_f32 v154, v154, v155
	v_cvt_pk_bf16_f32 v155, v158, v159
	v_cvt_pk_bf16_f32 v156, v156, v157
	s_nop 0
	v_cvt_pk_bf16_f32 v157, v160, v161
	global_store_dwordx4 v[182:183], v[154:157], off offset:128 sc1

.LBB0_401:
	s_andn2_b64 vcc, exec, s[50:51]
	s_cbranch_vccnz .LBB0_405
	s_waitcnt lgkmcnt(0)
	v_ashrrev_i32_e32 v153, 31, v152
	v_readlane_b32 s50, v235, 47
	v_lshlrev_b64 v[158:159], 10, v[152:153]
	v_readlane_b32 s51, v235, 48
	v_cvt_pk_bf16_f32 v154, v114, v115
	v_mul_f32_e32 v145, v115, v115
	v_mul_f32_e32 v153, v117, v117
	v_lshl_add_u64 v[158:159], s[50:51], 0, v[158:159]
	v_lshl_add_u64 v[158:159], s[66:67], 1, v[158:159]
	v_lshl_add_u64 v[158:159], v[4:5], 1, v[158:159]
	v_cvt_pk_bf16_f32 v155, v116, v117
	v_cvt_pk_bf16_f32 v156, v110, v111
	v_cvt_pk_bf16_f32 v157, v112, v113
	global_store_dwordx4 v[158:159], v[154:157], off sc1
	v_fmac_f32_e32 v145, v114, v114
	v_fmac_f32_e32 v153, v116, v116
	v_cvt_pk_bf16_f32 v154, v82, v83
	v_cvt_pk_bf16_f32 v155, v84, v85
	v_cvt_pk_bf16_f32 v156, v78, v79
	v_cvt_pk_bf16_f32 v157, v80, v81
	global_store_dwordx4 v[158:159], v[154:157], off offset:256 sc1
	v_add_f32_e32 v145, v145, v153
	v_mul_f32_e32 v153, v111, v111
	v_mul_f32_e32 v154, v113, v113
	v_fmac_f32_e32 v153, v110, v110
	v_fmac_f32_e32 v154, v112, v112
	v_add_f32_e32 v153, v153, v154
	v_add_f32_e32 v145, v153, v145
	v_mul_f32_e32 v153, v83, v83
	v_mul_f32_e32 v154, v85, v85
	v_fmac_f32_e32 v153, v82, v82
	v_fmac_f32_e32 v154, v84, v84
	v_add_f32_e32 v153, v153, v154
	v_mul_f32_e32 v154, v79, v79
	v_mul_f32_e32 v155, v81, v81
	v_fmac_f32_e32 v154, v78, v78
	v_fmac_f32_e32 v155, v80, v80
	v_add_f32_e32 v154, v154, v155
	v_add_f32_e32 v153, v154, v153
	v_and_b32_e32 v154, 64, v178
	v_add_f32_e32 v145, v153, v145
	v_xor_b32_e32 v153, 16, v178
	v_add_u32_e32 v154, 64, v154
	v_cmp_lt_i32_e32 vcc, v153, v154
	s_nop 1
	v_cndmask_b32_e32 v153, v178, v153, vcc
	v_lshlrev_b32_e32 v153, 2, v153
	ds_bpermute_b32 v153, v153, v145
	s_waitcnt lgkmcnt(0)
	v_add_f32_e32 v145, v145, v153
	v_xor_b32_e32 v153, 32, v178
	v_cmp_lt_i32_e32 vcc, v153, v154
	s_nop 1
	v_cndmask_b32_e32 v153, v178, v153, vcc
	v_lshlrev_b32_e32 v153, 2, v153
	ds_bpermute_b32 v153, v153, v145
	s_and_saveexec_b64 s[50:51], s[12:13]
	s_cbranch_execz .LBB0_404
	s_waitcnt lgkmcnt(0)
	v_add_f32_e32 v153, v145, v153
	v_ashrrev_i32_e32 v145, 31, v144
	v_lshl_add_u64 v[154:155], v[144:145], 2, s[36:37]
	s_waitcnt vmcnt(0)
	flat_atomic_add_f32 v[154:155], v153 offset:128

.LBB0_406:
	s_andn2_b64 vcc, exec, s[50:51]
	s_cbranch_vccnz .LBB0_408
	s_waitcnt lgkmcnt(0)
	v_ashrrev_i32_e32 v153, 31, v152
	v_lshlrev_b64 v[154:155], 8, v[152:153]
	v_lshl_add_u64 v[154:155], s[88:89], 0, v[154:155]
	v_lshl_add_u64 v[166:167], v[154:155], 0, v[142:143]
	flat_load_dwordx4 v[154:157], v[166:167]
	global_load_dwordx4 v[158:161], v[166:167], off offset:48
	global_load_dwordx4 v[162:165], v[166:167], off offset:32
	s_nop 0
	global_load_dwordx4 v[166:169], v[166:167], off offset:16
	s_waitcnt vmcnt(0) lgkmcnt(0)
	v_mov_b32_e32 v183, v156
	v_mov_b32_e32 v156, v155
	v_mov_b32_e32 v182, v154
	v_pk_mul_f32 v[154:155], v[82:83], v[156:157]
	v_mov_b32_e32 v187, v168
	v_mov_b32_e32 v168, v167
	v_pk_fma_f32 v[184:185], v[114:115], v[182:183], v[154:155] neg_lo:[0,0,1] neg_hi:[0,0,1]
	v_mov_b32_e32 v186, v166
	v_pk_mul_f32 v[154:155], v[84:85], v[168:169]
	v_mov_b32_e32 v189, v164
	v_mov_b32_e32 v164, v163
	v_pk_fma_f32 v[166:167], v[116:117], v[186:187], v[154:155] neg_lo:[0,0,1] neg_hi:[0,0,1]
	v_mov_b32_e32 v188, v162
	v_pk_mul_f32 v[154:155], v[78:79], v[164:165]
	v_mov_b32_e32 v191, v160
	v_mov_b32_e32 v160, v159
	v_pk_fma_f32 v[162:163], v[110:111], v[188:189], v[154:155] neg_lo:[0,0,1] neg_hi:[0,0,1]
	v_mov_b32_e32 v190, v158
	v_pk_mul_f32 v[154:155], v[80:81], v[160:161]
	v_pk_mul_f32 v[160:161], v[112:113], v[160:161]
	v_pk_fma_f32 v[192:193], v[112:113], v[190:191], v[154:155] neg_lo:[0,0,1] neg_hi:[0,0,1]
	v_pk_mul_f32 v[154:155], v[114:115], v[156:157]
	v_pk_mul_f32 v[156:157], v[116:117], v[168:169]
	v_pk_fma_f32 v[154:155], v[82:83], v[182:183], v[154:155]
	v_pk_fma_f32 v[158:159], v[84:85], v[186:187], v[156:157]
	v_pk_mul_f32 v[156:157], v[110:111], v[164:165]
	v_pk_mul_f32 v[164:165], v[166:167], s[96:97] op_sel_hi:[1,0]
	v_pk_mul_f32 v[166:167], v[184:185], s[96:97] op_sel_hi:[1,0]
	v_pk_mul_f32 v[182:183], v[162:163], s[96:97] op_sel_hi:[1,0]
	v_cvt_pk_bf16_f32 v162, v166, v167
	v_mov_b64_e32 v[166:167], s[78:79]
	v_pk_mul_f32 v[168:169], v[192:193], s[96:97] op_sel_hi:[1,0]
	v_mad_i64_i32 v[166:167], s[50:51], v152, s83, v[166:167]
	v_pk_fma_f32 v[156:157], v[78:79], v[188:189], v[156:157]
	v_cvt_pk_bf16_f32 v163, v164, v165
	v_cvt_pk_bf16_f32 v164, v182, v183
	v_cvt_pk_bf16_f32 v165, v168, v169
	v_lshl_add_u64 v[166:167], v[140:141], 1, v[166:167]
	v_lshlrev_b32_e32 v168, 1, v179
	v_mov_b32_e32 v169, v3
	v_pk_fma_f32 v[160:161], v[80:81], v[190:191], v[160:161]
	v_lshl_add_u64 v[166:167], v[166:167], 0, v[168:169]
	v_pk_mul_f32 v[154:155], v[154:155], s[96:97] op_sel_hi:[1,0]
	v_pk_mul_f32 v[156:157], v[156:157], s[96:97] op_sel_hi:[1,0]
	global_store_dwordx4 v[166:167], v[162:165], off offset:256 sc1
	v_pk_mul_f32 v[158:159], v[158:159], s[96:97] op_sel_hi:[1,0]
	v_pk_mul_f32 v[160:161], v[160:161], s[96:97] op_sel_hi:[1,0]
	v_cvt_pk_bf16_f32 v154, v154, v155
	v_cvt_pk_bf16_f32 v155, v158, v159
	v_cvt_pk_bf16_f32 v156, v156, v157
	s_nop 0
	v_cvt_pk_bf16_f32 v157, v160, v161
	global_store_dwordx4 v[166:167], v[154:157], off offset:320 sc1

.LBB0_410:
	s_and_b64 vcc, exec, s[18:19]
	s_cbranch_vccnz .LBB0_424
	s_andn2_b64 vcc, exec, s[80:81]
	s_cbranch_vccnz .LBB0_419
	s_andn2_b64 vcc, exec, s[22:23]
	s_cbranch_vccnz .LBB0_416
	s_and_saveexec_b64 s[50:51], s[16:17]
	s_cbranch_execz .LBB0_415
	s_waitcnt lgkmcnt(0)
	v_ashrrev_i32_e32 v153, 31, v152
	v_lshlrev_b64 v[154:155], 8, v[152:153]
	v_lshl_add_u64 v[154:155], s[88:89], 0, v[154:155]
	v_lshl_add_u64 v[166:167], v[154:155], 0, v[150:151]
	flat_load_dwordx4 v[154:157], v[166:167]
	global_load_dwordx4 v[158:161], v[166:167], off offset:48
	global_load_dwordx4 v[162:165], v[166:167], off offset:32
	s_nop 0
	global_load_dwordx4 v[166:169], v[166:167], off offset:16
	v_mov_b32_e32 v182, v106
	v_mov_b32_e32 v183, v74
	v_readlane_b32 s86, v235, 45
	v_readlane_b32 s87, v235, 46
	s_waitcnt vmcnt(0) lgkmcnt(0)
	v_pk_mul_f32 v[182:183], v[182:183], v[154:155]
	s_nop 0
	v_sub_f32_e32 v145, v182, v183
	v_mov_b32_e32 v182, v107
	v_mov_b32_e32 v183, v75
	v_pk_mul_f32 v[182:183], v[182:183], v[156:157]
	s_nop 0
	v_sub_f32_e32 v153, v182, v183
	v_mov_b32_e32 v182, v108
	v_mov_b32_e32 v183, v76
	v_pk_mul_f32 v[182:183], v[182:183], v[166:167]
	s_nop 0
	v_sub_f32_e32 v181, v182, v183
	v_mov_b32_e32 v182, v109
	v_mov_b32_e32 v183, v77
	v_pk_mul_f32 v[182:183], v[182:183], v[168:169]
	s_nop 0
	v_sub_f32_e32 v184, v182, v183
	v_mov_b32_e32 v182, v102
	v_mov_b32_e32 v183, v70
	v_pk_mul_f32 v[182:183], v[182:183], v[162:163]
	s_nop 0
	v_sub_f32_e32 v185, v182, v183
	v_mov_b32_e32 v182, v103
	v_mov_b32_e32 v183, v71
	v_pk_mul_f32 v[182:183], v[182:183], v[164:165]
	s_nop 0
	v_sub_f32_e32 v186, v182, v183
	v_mov_b32_e32 v182, v104
	v_mov_b32_e32 v183, v72
	v_pk_mul_f32 v[182:183], v[182:183], v[158:159]
	s_nop 0
	v_sub_f32_e32 v187, v182, v183
	v_mov_b32_e32 v182, v105
	v_mov_b32_e32 v183, v73
	v_pk_mul_f32 v[182:183], v[182:183], v[160:161]
	s_nop 0
	v_sub_f32_e32 v188, v182, v183
	v_mov_b32_e32 v182, v74
	v_mov_b32_e32 v183, v106
	v_pk_mul_f32 v[154:155], v[182:183], v[154:155]
	s_nop 0
	v_add_f32_e32 v182, v154, v155
	v_mov_b32_e32 v154, v75
	v_mov_b32_e32 v155, v107
	v_pk_mul_f32 v[154:155], v[154:155], v[156:157]
	s_nop 0
	v_add_f32_e32 v183, v154, v155
	v_mov_b32_e32 v154, v76
	v_mov_b32_e32 v155, v108
	v_pk_mul_f32 v[154:155], v[154:155], v[166:167]
	s_nop 0
	v_add_f32_e32 v166, v154, v155
	v_mov_b32_e32 v154, v77
	v_mov_b32_e32 v155, v109
	v_pk_mul_f32 v[154:155], v[154:155], v[168:169]
	s_nop 0
	v_add_f32_e32 v167, v154, v155
	v_mov_b32_e32 v154, v70
	v_mov_b32_e32 v155, v102
	v_pk_mul_f32 v[154:155], v[154:155], v[162:163]
	s_nop 0
	v_add_f32_e32 v162, v154, v155
	v_mov_b32_e32 v154, v71
	v_mov_b32_e32 v155, v103
	v_pk_mul_f32 v[154:155], v[154:155], v[164:165]
	s_nop 0
	v_add_f32_e32 v163, v154, v155
	v_mov_b32_e32 v154, v72
	v_mov_b32_e32 v155, v104
	v_pk_mul_f32 v[154:155], v[154:155], v[158:159]
	s_nop 0
	v_add_f32_e32 v164, v154, v155
	v_mov_b32_e32 v154, v73
	v_mov_b32_e32 v155, v105
	v_pk_mul_f32 v[154:155], v[154:155], v[160:161]
	s_nop 0
	v_add_f32_e32 v161, v154, v155
	v_cvt_pk_bf16_f32 v154, v145, v153
	v_cvt_pk_bf16_f32 v155, v181, v184
	v_cvt_pk_bf16_f32 v156, v185, v186
	v_cvt_pk_bf16_f32 v157, v187, v188
	v_cvt_pk_bf16_f32 v158, v182, v183
	v_cvt_pk_bf16_f32 v159, v166, v167
	v_cvt_pk_bf16_f32 v160, v162, v163
	v_mov_b64_e32 v[162:163], s[86:87]
	v_mad_i64_i32 v[162:163], s[86:87], v152, s83, v[162:163]
	v_lshl_add_u64 v[162:163], v[4:5], 1, v[162:163]
	v_cvt_pk_bf16_f32 v161, v164, v161
	global_store_dwordx4 v[162:163], v[154:157], off offset:256 sc1
	global_store_dwordx4 v[162:163], v[158:161], off offset:320 sc1
	global_store_dwordx4 v[162:163], v[154:157], off offset:640 sc1
	global_store_dwordx4 v[162:163], v[158:161], off offset:704 sc1
	global_store_dwordx4 v[162:163], v[154:157], off offset:1024 sc1
	global_store_dwordx4 v[162:163], v[158:161], off offset:1088 sc1
	global_store_dwordx4 v[162:163], v[154:157], off offset:1408 sc1
	global_store_dwordx4 v[162:163], v[158:161], off offset:1472 sc1
	global_store_dwordx4 v[162:163], v[154:157], off offset:1792 sc1
	global_store_dwordx4 v[162:163], v[158:161], off offset:1856 sc1
	global_store_dwordx4 v[162:163], v[154:157], off offset:2176 sc1
	global_store_dwordx4 v[162:163], v[158:161], off offset:2240 sc1
	global_store_dwordx4 v[162:163], v[154:157], off offset:2560 sc1
	global_store_dwordx4 v[162:163], v[158:161], off offset:2624 sc1
	global_store_dwordx4 v[162:163], v[154:157], off offset:2944 sc1
	global_store_dwordx4 v[162:163], v[158:161], off offset:3008 sc1

.LBB0_416:
	s_andn2_b64 vcc, exec, s[50:51]
	s_cbranch_vccnz .LBB0_418
	s_waitcnt lgkmcnt(0)
	v_ashrrev_i32_e32 v153, 31, v152
	v_readlane_b32 s50, v235, 53
	v_lshlrev_b64 v[154:155], 9, v[152:153]
	v_readlane_b32 s51, v235, 54
	v_readlane_b32 s86, v235, 51
	s_nop 0
	v_lshl_add_u64 v[154:155], s[50:51], 0, v[154:155]
	v_lshl_add_u64 v[162:163], v[154:155], 0, v[2:3]
	flat_load_dwordx4 v[154:157], v[162:163]
	global_load_dwordx4 v[158:161], v[162:163], off offset:48
	global_load_dwordx4 v[182:185], v[162:163], off offset:32
	global_load_dwordx4 v[186:189], v[162:163], off offset:16
	s_and_b64 s[50:51], s[14:15], exec
	v_readlane_b32 s50, v235, 50
	v_readlane_b32 s51, v235, 52
	s_cselect_b32 s51, s50, s51
	v_readlane_b32 s50, v235, 49
	s_cselect_b32 s50, s50, s86
	s_waitcnt vmcnt(0) lgkmcnt(0)
	v_mov_b32_e32 v191, v156
	v_mov_b32_e32 v156, v155
	v_mov_b32_e32 v190, v154
	v_pk_mul_f32 v[154:155], v[74:75], v[156:157]
	v_mov_b32_e32 v193, v188
	v_mov_b32_e32 v188, v187
	v_pk_fma_f32 v[162:163], v[106:107], v[190:191], v[154:155] neg_lo:[0,0,1] neg_hi:[0,0,1]
	v_mov_b32_e32 v192, v186
	v_pk_mul_f32 v[154:155], v[76:77], v[188:189]
	v_mov_b32_e32 v187, v184
	v_mov_b32_e32 v184, v183
	v_pk_fma_f32 v[164:165], v[108:109], v[192:193], v[154:155] neg_lo:[0,0,1] neg_hi:[0,0,1]
	v_mov_b32_e32 v186, v182
	v_pk_mul_f32 v[154:155], v[70:71], v[184:185]
	v_mov_b32_e32 v183, v160
	v_mov_b32_e32 v160, v159
	v_pk_fma_f32 v[166:167], v[102:103], v[186:187], v[154:155] neg_lo:[0,0,1] neg_hi:[0,0,1]
	v_mov_b32_e32 v182, v158
	v_pk_mul_f32 v[154:155], v[72:73], v[160:161]
	v_pk_mul_f32 v[160:161], v[104:105], v[160:161]
	v_pk_fma_f32 v[168:169], v[104:105], v[182:183], v[154:155] neg_lo:[0,0,1] neg_hi:[0,0,1]
	v_pk_fma_f32 v[160:161], v[72:73], v[182:183], v[160:161]
	v_lshlrev_b64 v[182:183], 11, v[152:153]
	v_pk_mul_f32 v[154:155], v[106:107], v[156:157]
	v_pk_mul_f32 v[156:157], v[108:109], v[188:189]
	v_lshl_add_u64 v[182:183], s[50:51], 0, v[182:183]
	v_pk_fma_f32 v[158:159], v[76:77], v[192:193], v[156:157]
	v_pk_mul_f32 v[156:157], v[102:103], v[184:185]
	v_lshl_add_u64 v[182:183], v[148:149], 1, v[182:183]
	v_lshlrev_b32_e32 v184, 1, v180
	v_mov_b32_e32 v185, v3
	v_pk_fma_f32 v[154:155], v[74:75], v[190:191], v[154:155]
	v_pk_fma_f32 v[156:157], v[70:71], v[186:187], v[156:157]
	v_lshl_add_u64 v[182:183], v[182:183], 0, v[184:185]
	v_mov_b32_e32 v184, v146
	v_mov_b32_e32 v185, v146
	v_pk_mul_f32 v[164:165], v[184:185], v[164:165]
	v_pk_mul_f32 v[162:163], v[146:147], v[162:163]
	v_pk_mul_f32 v[154:155], v[146:147], v[154:155]
	v_pk_mul_f32 v[156:157], v[146:147], v[156:157]
	v_pk_mul_f32 v[168:169], v[184:185], v[168:169]
	v_pk_mul_f32 v[166:167], v[146:147], v[166:167]
	v_cvt_pk_bf16_f32 v162, v162, v163
	v_cvt_pk_bf16_f32 v163, v164, v165
	v_pk_mul_f32 v[158:159], v[184:185], v[158:159]
	v_cvt_pk_bf16_f32 v164, v166, v167
	v_cvt_pk_bf16_f32 v165, v168, v169
	global_store_dwordx4 v[182:183], v[162:165], off sc1
	v_pk_mul_f32 v[160:161], v[184:185], v[160:161]
	v_cvt_pk_bf16_f32 v154, v154, v155
	v_cvt_pk_bf16_f32 v155, v158, v159
	v_cvt_pk_bf16_f32 v156, v156, v157
	s_nop 0
	v_cvt_pk_bf16_f32 v157, v160, v161
	global_store_dwordx4 v[182:183], v[154:157], off offset:128 sc1

.LBB0_419:
	s_andn2_b64 vcc, exec, s[50:51]
	s_cbranch_vccnz .LBB0_423
	s_waitcnt lgkmcnt(0)
	v_ashrrev_i32_e32 v153, 31, v152
	v_readlane_b32 s50, v235, 47
	v_lshlrev_b64 v[158:159], 10, v[152:153]
	v_readlane_b32 s51, v235, 48
	v_cvt_pk_bf16_f32 v154, v106, v107
	v_mul_f32_e32 v145, v107, v107
	v_mul_f32_e32 v153, v109, v109
	v_lshl_add_u64 v[158:159], s[50:51], 0, v[158:159]
	v_lshl_add_u64 v[158:159], s[66:67], 1, v[158:159]
	v_lshl_add_u64 v[158:159], v[4:5], 1, v[158:159]
	v_cvt_pk_bf16_f32 v155, v108, v109
	v_cvt_pk_bf16_f32 v156, v102, v103
	v_cvt_pk_bf16_f32 v157, v104, v105
	global_store_dwordx4 v[158:159], v[154:157], off sc1
	v_fmac_f32_e32 v145, v106, v106
	v_fmac_f32_e32 v153, v108, v108
	v_cvt_pk_bf16_f32 v154, v74, v75
	v_cvt_pk_bf16_f32 v155, v76, v77
	v_cvt_pk_bf16_f32 v156, v70, v71
	v_cvt_pk_bf16_f32 v157, v72, v73
	global_store_dwordx4 v[158:159], v[154:157], off offset:256 sc1
	v_add_f32_e32 v145, v145, v153
	v_mul_f32_e32 v153, v103, v103
	v_mul_f32_e32 v154, v105, v105
	v_fmac_f32_e32 v153, v102, v102
	v_fmac_f32_e32 v154, v104, v104
	v_add_f32_e32 v153, v153, v154
	v_add_f32_e32 v145, v153, v145
	v_mul_f32_e32 v153, v75, v75
	v_mul_f32_e32 v154, v77, v77
	v_fmac_f32_e32 v153, v74, v74
	v_fmac_f32_e32 v154, v76, v76
	v_add_f32_e32 v153, v153, v154
	v_mul_f32_e32 v154, v71, v71
	v_mul_f32_e32 v155, v73, v73
	v_fmac_f32_e32 v154, v70, v70
	v_fmac_f32_e32 v155, v72, v72
	v_add_f32_e32 v154, v154, v155
	v_add_f32_e32 v153, v154, v153
	v_and_b32_e32 v154, 64, v178
	v_add_f32_e32 v145, v153, v145
	v_xor_b32_e32 v153, 16, v178
	v_add_u32_e32 v154, 64, v154
	v_cmp_lt_i32_e32 vcc, v153, v154
	s_nop 1
	v_cndmask_b32_e32 v153, v178, v153, vcc
	v_lshlrev_b32_e32 v153, 2, v153
	ds_bpermute_b32 v153, v153, v145
	s_waitcnt lgkmcnt(0)
	v_add_f32_e32 v145, v145, v153
	v_xor_b32_e32 v153, 32, v178
	v_cmp_lt_i32_e32 vcc, v153, v154
	s_nop 1
	v_cndmask_b32_e32 v153, v178, v153, vcc
	v_lshlrev_b32_e32 v153, 2, v153
	ds_bpermute_b32 v153, v153, v145
	s_and_saveexec_b64 s[50:51], s[12:13]
	s_cbranch_execz .LBB0_422
	s_waitcnt lgkmcnt(0)
	v_add_f32_e32 v153, v145, v153
	v_ashrrev_i32_e32 v145, 31, v144
	v_lshl_add_u64 v[154:155], v[144:145], 2, s[36:37]
	s_waitcnt vmcnt(0)
	flat_atomic_add_f32 v[154:155], v153 offset:192

.LBB0_424:
	s_andn2_b64 vcc, exec, s[50:51]
	s_cbranch_vccnz .LBB0_426
	s_waitcnt lgkmcnt(0)
	v_ashrrev_i32_e32 v153, 31, v152
	v_lshlrev_b64 v[154:155], 8, v[152:153]
	v_lshl_add_u64 v[154:155], s[88:89], 0, v[154:155]
	v_lshl_add_u64 v[166:167], v[154:155], 0, v[142:143]
	flat_load_dwordx4 v[154:157], v[166:167]
	global_load_dwordx4 v[158:161], v[166:167], off offset:48
	global_load_dwordx4 v[162:165], v[166:167], off offset:32
	s_nop 0
	global_load_dwordx4 v[166:169], v[166:167], off offset:16
	s_waitcnt vmcnt(0) lgkmcnt(0)
	v_mov_b32_e32 v183, v156
	v_mov_b32_e32 v156, v155
	v_mov_b32_e32 v182, v154
	v_pk_mul_f32 v[154:155], v[74:75], v[156:157]
	v_mov_b32_e32 v187, v168
	v_mov_b32_e32 v168, v167
	v_pk_fma_f32 v[184:185], v[106:107], v[182:183], v[154:155] neg_lo:[0,0,1] neg_hi:[0,0,1]
	v_mov_b32_e32 v186, v166
	v_pk_mul_f32 v[154:155], v[76:77], v[168:169]
	v_mov_b32_e32 v189, v164
	v_mov_b32_e32 v164, v163
	v_pk_fma_f32 v[166:167], v[108:109], v[186:187], v[154:155] neg_lo:[0,0,1] neg_hi:[0,0,1]
	v_mov_b32_e32 v188, v162
	v_pk_mul_f32 v[154:155], v[70:71], v[164:165]
	v_mov_b32_e32 v191, v160
	v_mov_b32_e32 v160, v159
	v_pk_fma_f32 v[162:163], v[102:103], v[188:189], v[154:155] neg_lo:[0,0,1] neg_hi:[0,0,1]
	v_mov_b32_e32 v190, v158
	v_pk_mul_f32 v[154:155], v[72:73], v[160:161]
	v_pk_mul_f32 v[160:161], v[104:105], v[160:161]
	v_pk_fma_f32 v[192:193], v[104:105], v[190:191], v[154:155] neg_lo:[0,0,1] neg_hi:[0,0,1]
	v_pk_mul_f32 v[154:155], v[106:107], v[156:157]
	v_pk_mul_f32 v[156:157], v[108:109], v[168:169]
	v_pk_fma_f32 v[154:155], v[74:75], v[182:183], v[154:155]
	v_pk_fma_f32 v[158:159], v[76:77], v[186:187], v[156:157]
	v_pk_mul_f32 v[156:157], v[102:103], v[164:165]
	v_pk_mul_f32 v[164:165], v[166:167], s[96:97] op_sel_hi:[1,0]
	v_pk_mul_f32 v[166:167], v[184:185], s[96:97] op_sel_hi:[1,0]
	v_pk_mul_f32 v[182:183], v[162:163], s[96:97] op_sel_hi:[1,0]
	v_cvt_pk_bf16_f32 v162, v166, v167
	v_mov_b64_e32 v[166:167], s[78:79]
	v_pk_mul_f32 v[168:169], v[192:193], s[96:97] op_sel_hi:[1,0]
	v_mad_i64_i32 v[166:167], s[50:51], v152, s83, v[166:167]
	v_pk_fma_f32 v[156:157], v[70:71], v[188:189], v[156:157]
	v_cvt_pk_bf16_f32 v163, v164, v165
	v_cvt_pk_bf16_f32 v164, v182, v183
	v_cvt_pk_bf16_f32 v165, v168, v169
	v_lshl_add_u64 v[166:167], v[140:141], 1, v[166:167]
	v_lshlrev_b32_e32 v168, 1, v179
	v_mov_b32_e32 v169, v3
	v_pk_fma_f32 v[160:161], v[72:73], v[190:191], v[160:161]
	v_lshl_add_u64 v[166:167], v[166:167], 0, v[168:169]
	v_pk_mul_f32 v[154:155], v[154:155], s[96:97] op_sel_hi:[1,0]
	v_pk_mul_f32 v[156:157], v[156:157], s[96:97] op_sel_hi:[1,0]
	global_store_dwordx4 v[166:167], v[162:165], off offset:256 sc1
	v_pk_mul_f32 v[158:159], v[158:159], s[96:97] op_sel_hi:[1,0]
	v_pk_mul_f32 v[160:161], v[160:161], s[96:97] op_sel_hi:[1,0]
	v_cvt_pk_bf16_f32 v154, v154, v155
	v_cvt_pk_bf16_f32 v155, v158, v159
	v_cvt_pk_bf16_f32 v156, v156, v157
	s_nop 0
	v_cvt_pk_bf16_f32 v157, v160, v161
	global_store_dwordx4 v[166:167], v[154:157], off offset:320 sc1

.LBB0_428:
	s_and_b64 vcc, exec, s[18:19]
	s_cbranch_vccnz .LBB0_442
	s_andn2_b64 vcc, exec, s[80:81]
	s_cbranch_vccnz .LBB0_437
	s_andn2_b64 vcc, exec, s[22:23]
	s_cbranch_vccnz .LBB0_434
	s_and_saveexec_b64 s[50:51], s[16:17]
	s_cbranch_execz .LBB0_433
	s_waitcnt lgkmcnt(0)
	v_ashrrev_i32_e32 v153, 31, v152
	v_lshlrev_b64 v[154:155], 8, v[152:153]
	v_lshl_add_u64 v[154:155], s[88:89], 0, v[154:155]
	v_lshl_add_u64 v[166:167], v[154:155], 0, v[150:151]
	flat_load_dwordx4 v[154:157], v[166:167]
	global_load_dwordx4 v[158:161], v[166:167], off offset:48
	global_load_dwordx4 v[162:165], v[166:167], off offset:32
	s_nop 0
	global_load_dwordx4 v[166:169], v[166:167], off offset:16
	v_mov_b32_e32 v182, v66
	v_mov_b32_e32 v183, v34
	v_readlane_b32 s86, v235, 45
	v_readlane_b32 s87, v235, 46
	s_waitcnt vmcnt(0) lgkmcnt(0)
	v_pk_mul_f32 v[182:183], v[182:183], v[154:155]
	s_nop 0
	v_sub_f32_e32 v145, v182, v183
	v_mov_b32_e32 v182, v67
	v_mov_b32_e32 v183, v35
	v_pk_mul_f32 v[182:183], v[182:183], v[156:157]
	s_nop 0
	v_sub_f32_e32 v153, v182, v183
	v_mov_b32_e32 v182, v68
	v_mov_b32_e32 v183, v36
	v_pk_mul_f32 v[182:183], v[182:183], v[166:167]
	s_nop 0
	v_sub_f32_e32 v181, v182, v183
	v_mov_b32_e32 v182, v69
	v_mov_b32_e32 v183, v37
	v_pk_mul_f32 v[182:183], v[182:183], v[168:169]
	s_nop 0
	v_sub_f32_e32 v184, v182, v183
	v_mov_b32_e32 v182, v62
	v_mov_b32_e32 v183, v30
	v_pk_mul_f32 v[182:183], v[182:183], v[162:163]
	s_nop 0
	v_sub_f32_e32 v185, v182, v183
	v_mov_b32_e32 v182, v63
	v_mov_b32_e32 v183, v31
	v_pk_mul_f32 v[182:183], v[182:183], v[164:165]
	s_nop 0
	v_sub_f32_e32 v186, v182, v183
	v_mov_b32_e32 v182, v64
	v_mov_b32_e32 v183, v32
	v_pk_mul_f32 v[182:183], v[182:183], v[158:159]
	s_nop 0
	v_sub_f32_e32 v187, v182, v183
	v_mov_b32_e32 v182, v65
	v_mov_b32_e32 v183, v33
	v_pk_mul_f32 v[182:183], v[182:183], v[160:161]
	s_nop 0
	v_sub_f32_e32 v188, v182, v183
	v_mov_b32_e32 v182, v34
	v_mov_b32_e32 v183, v66
	v_pk_mul_f32 v[154:155], v[182:183], v[154:155]
	s_nop 0
	v_add_f32_e32 v182, v154, v155
	v_mov_b32_e32 v154, v35
	v_mov_b32_e32 v155, v67
	v_pk_mul_f32 v[154:155], v[154:155], v[156:157]
	s_nop 0
	v_add_f32_e32 v183, v154, v155
	v_mov_b32_e32 v154, v36
	v_mov_b32_e32 v155, v68
	v_pk_mul_f32 v[154:155], v[154:155], v[166:167]
	s_nop 0
	v_add_f32_e32 v166, v154, v155
	v_mov_b32_e32 v154, v37
	v_mov_b32_e32 v155, v69
	v_pk_mul_f32 v[154:155], v[154:155], v[168:169]
	s_nop 0
	v_add_f32_e32 v167, v154, v155
	v_mov_b32_e32 v154, v30
	v_mov_b32_e32 v155, v62
	v_pk_mul_f32 v[154:155], v[154:155], v[162:163]
	s_nop 0
	v_add_f32_e32 v162, v154, v155
	v_mov_b32_e32 v154, v31
	v_mov_b32_e32 v155, v63
	v_pk_mul_f32 v[154:155], v[154:155], v[164:165]
	s_nop 0
	v_add_f32_e32 v163, v154, v155
	v_mov_b32_e32 v154, v32
	v_mov_b32_e32 v155, v64
	v_pk_mul_f32 v[154:155], v[154:155], v[158:159]
	s_nop 0
	v_add_f32_e32 v164, v154, v155
	v_mov_b32_e32 v154, v33
	v_mov_b32_e32 v155, v65
	v_pk_mul_f32 v[154:155], v[154:155], v[160:161]
	s_nop 0
	v_add_f32_e32 v161, v154, v155
	v_cvt_pk_bf16_f32 v154, v145, v153
	v_cvt_pk_bf16_f32 v155, v181, v184
	v_cvt_pk_bf16_f32 v156, v185, v186
	v_cvt_pk_bf16_f32 v157, v187, v188
	v_cvt_pk_bf16_f32 v158, v182, v183
	v_cvt_pk_bf16_f32 v159, v166, v167
	v_cvt_pk_bf16_f32 v160, v162, v163
	v_mov_b64_e32 v[162:163], s[86:87]
	v_mad_i64_i32 v[162:163], s[86:87], v152, s83, v[162:163]
	v_lshl_add_u64 v[162:163], v[4:5], 1, v[162:163]
	v_cvt_pk_bf16_f32 v161, v164, v161
	global_store_dwordx4 v[162:163], v[154:157], off offset:256 sc1
	global_store_dwordx4 v[162:163], v[158:161], off offset:320 sc1
	global_store_dwordx4 v[162:163], v[154:157], off offset:640 sc1
	global_store_dwordx4 v[162:163], v[158:161], off offset:704 sc1
	global_store_dwordx4 v[162:163], v[154:157], off offset:1024 sc1
	global_store_dwordx4 v[162:163], v[158:161], off offset:1088 sc1
	global_store_dwordx4 v[162:163], v[154:157], off offset:1408 sc1
	global_store_dwordx4 v[162:163], v[158:161], off offset:1472 sc1
	global_store_dwordx4 v[162:163], v[154:157], off offset:1792 sc1
	global_store_dwordx4 v[162:163], v[158:161], off offset:1856 sc1
	global_store_dwordx4 v[162:163], v[154:157], off offset:2176 sc1
	global_store_dwordx4 v[162:163], v[158:161], off offset:2240 sc1
	global_store_dwordx4 v[162:163], v[154:157], off offset:2560 sc1
	global_store_dwordx4 v[162:163], v[158:161], off offset:2624 sc1
	global_store_dwordx4 v[162:163], v[154:157], off offset:2944 sc1
	global_store_dwordx4 v[162:163], v[158:161], off offset:3008 sc1

.LBB0_434:
	s_andn2_b64 vcc, exec, s[50:51]
	s_cbranch_vccnz .LBB0_436
	s_waitcnt lgkmcnt(0)
	v_ashrrev_i32_e32 v153, 31, v152
	v_readlane_b32 s50, v235, 53
	v_lshlrev_b64 v[154:155], 9, v[152:153]
	v_readlane_b32 s51, v235, 54
	v_readlane_b32 s86, v235, 51
	s_nop 0
	v_lshl_add_u64 v[154:155], s[50:51], 0, v[154:155]
	v_lshl_add_u64 v[162:163], v[154:155], 0, v[2:3]
	flat_load_dwordx4 v[154:157], v[162:163]
	global_load_dwordx4 v[158:161], v[162:163], off offset:48
	global_load_dwordx4 v[182:185], v[162:163], off offset:32
	global_load_dwordx4 v[186:189], v[162:163], off offset:16
	s_and_b64 s[50:51], s[14:15], exec
	v_readlane_b32 s50, v235, 50
	v_readlane_b32 s51, v235, 52
	s_cselect_b32 s51, s50, s51
	v_readlane_b32 s50, v235, 49
	s_cselect_b32 s50, s50, s86
	s_waitcnt vmcnt(0) lgkmcnt(0)
	v_mov_b32_e32 v191, v156
	v_mov_b32_e32 v156, v155
	v_mov_b32_e32 v190, v154
	v_pk_mul_f32 v[154:155], v[34:35], v[156:157]
	v_mov_b32_e32 v193, v188
	v_mov_b32_e32 v188, v187
	v_pk_fma_f32 v[162:163], v[66:67], v[190:191], v[154:155] neg_lo:[0,0,1] neg_hi:[0,0,1]
	v_mov_b32_e32 v192, v186
	v_pk_mul_f32 v[154:155], v[36:37], v[188:189]
	v_mov_b32_e32 v187, v184
	v_mov_b32_e32 v184, v183
	v_pk_fma_f32 v[164:165], v[68:69], v[192:193], v[154:155] neg_lo:[0,0,1] neg_hi:[0,0,1]
	v_mov_b32_e32 v186, v182
	v_pk_mul_f32 v[154:155], v[30:31], v[184:185]
	v_mov_b32_e32 v183, v160
	v_mov_b32_e32 v160, v159
	v_pk_fma_f32 v[166:167], v[62:63], v[186:187], v[154:155] neg_lo:[0,0,1] neg_hi:[0,0,1]
	v_mov_b32_e32 v182, v158
	v_pk_mul_f32 v[154:155], v[32:33], v[160:161]
	v_pk_mul_f32 v[160:161], v[64:65], v[160:161]
	v_pk_fma_f32 v[168:169], v[64:65], v[182:183], v[154:155] neg_lo:[0,0,1] neg_hi:[0,0,1]
	v_pk_fma_f32 v[160:161], v[32:33], v[182:183], v[160:161]
	v_lshlrev_b64 v[182:183], 11, v[152:153]
	v_pk_mul_f32 v[154:155], v[66:67], v[156:157]
	v_pk_mul_f32 v[156:157], v[68:69], v[188:189]
	v_lshl_add_u64 v[182:183], s[50:51], 0, v[182:183]
	v_pk_fma_f32 v[158:159], v[36:37], v[192:193], v[156:157]
	v_pk_mul_f32 v[156:157], v[62:63], v[184:185]
	v_lshl_add_u64 v[182:183], v[148:149], 1, v[182:183]
	v_lshlrev_b32_e32 v184, 1, v180
	v_mov_b32_e32 v185, v3
	v_pk_fma_f32 v[154:155], v[34:35], v[190:191], v[154:155]
	v_pk_fma_f32 v[156:157], v[30:31], v[186:187], v[156:157]
	v_lshl_add_u64 v[182:183], v[182:183], 0, v[184:185]
	v_mov_b32_e32 v184, v146
	v_mov_b32_e32 v185, v146
	v_pk_mul_f32 v[164:165], v[184:185], v[164:165]
	v_pk_mul_f32 v[162:163], v[146:147], v[162:163]
	v_pk_mul_f32 v[154:155], v[146:147], v[154:155]
	v_pk_mul_f32 v[156:157], v[146:147], v[156:157]
	v_pk_mul_f32 v[168:169], v[184:185], v[168:169]
	v_pk_mul_f32 v[166:167], v[146:147], v[166:167]
	v_cvt_pk_bf16_f32 v162, v162, v163
	v_cvt_pk_bf16_f32 v163, v164, v165
	v_pk_mul_f32 v[158:159], v[184:185], v[158:159]
	v_cvt_pk_bf16_f32 v164, v166, v167
	v_cvt_pk_bf16_f32 v165, v168, v169
	global_store_dwordx4 v[182:183], v[162:165], off sc1
	v_pk_mul_f32 v[160:161], v[184:185], v[160:161]
	v_cvt_pk_bf16_f32 v154, v154, v155
	v_cvt_pk_bf16_f32 v155, v158, v159
	v_cvt_pk_bf16_f32 v156, v156, v157
	s_nop 0
	v_cvt_pk_bf16_f32 v157, v160, v161
	global_store_dwordx4 v[182:183], v[154:157], off offset:128 sc1

.LBB0_437:
	s_andn2_b64 vcc, exec, s[50:51]
	s_cbranch_vccnz .LBB0_441
	s_waitcnt lgkmcnt(0)
	v_ashrrev_i32_e32 v153, 31, v152
	v_readlane_b32 s50, v235, 47
	v_lshlrev_b64 v[158:159], 10, v[152:153]
	v_readlane_b32 s51, v235, 48
	v_cvt_pk_bf16_f32 v154, v66, v67
	v_mul_f32_e32 v145, v67, v67
	v_mul_f32_e32 v153, v69, v69
	v_lshl_add_u64 v[158:159], s[50:51], 0, v[158:159]
	v_lshl_add_u64 v[158:159], s[66:67], 1, v[158:159]
	v_lshl_add_u64 v[158:159], v[4:5], 1, v[158:159]
	v_cvt_pk_bf16_f32 v155, v68, v69
	v_cvt_pk_bf16_f32 v156, v62, v63
	v_cvt_pk_bf16_f32 v157, v64, v65
	global_store_dwordx4 v[158:159], v[154:157], off sc1
	v_fmac_f32_e32 v145, v66, v66
	v_fmac_f32_e32 v153, v68, v68
	v_cvt_pk_bf16_f32 v154, v34, v35
	v_cvt_pk_bf16_f32 v155, v36, v37
	v_cvt_pk_bf16_f32 v156, v30, v31
	v_cvt_pk_bf16_f32 v157, v32, v33
	global_store_dwordx4 v[158:159], v[154:157], off offset:256 sc1
	v_add_f32_e32 v145, v145, v153
	v_mul_f32_e32 v153, v63, v63
	v_mul_f32_e32 v154, v65, v65
	v_fmac_f32_e32 v153, v62, v62
	v_fmac_f32_e32 v154, v64, v64
	v_add_f32_e32 v153, v153, v154
	v_add_f32_e32 v145, v153, v145
	v_mul_f32_e32 v153, v35, v35
	v_mul_f32_e32 v154, v37, v37
	v_fmac_f32_e32 v153, v34, v34
	v_fmac_f32_e32 v154, v36, v36
	v_add_f32_e32 v153, v153, v154
	v_mul_f32_e32 v154, v31, v31
	v_mul_f32_e32 v155, v33, v33
	v_fmac_f32_e32 v154, v30, v30
	v_fmac_f32_e32 v155, v32, v32
	v_add_f32_e32 v154, v154, v155
	v_add_f32_e32 v153, v154, v153
	v_and_b32_e32 v154, 64, v178
	v_add_f32_e32 v145, v153, v145
	v_xor_b32_e32 v153, 16, v178
	v_add_u32_e32 v154, 64, v154
	v_cmp_lt_i32_e32 vcc, v153, v154
	s_nop 1
	v_cndmask_b32_e32 v153, v178, v153, vcc
	v_lshlrev_b32_e32 v153, 2, v153
	ds_bpermute_b32 v153, v153, v145
	s_waitcnt lgkmcnt(0)
	v_add_f32_e32 v145, v145, v153
	v_xor_b32_e32 v153, 32, v178
	v_cmp_lt_i32_e32 vcc, v153, v154
	s_nop 1
	v_cndmask_b32_e32 v153, v178, v153, vcc
	v_lshlrev_b32_e32 v153, 2, v153
	ds_bpermute_b32 v153, v153, v145
	s_and_saveexec_b64 s[50:51], s[12:13]
	s_cbranch_execz .LBB0_440
	s_waitcnt lgkmcnt(0)
	v_add_f32_e32 v153, v145, v153
	v_ashrrev_i32_e32 v145, 31, v144
	v_lshl_add_u64 v[154:155], v[144:145], 2, s[36:37]
	s_waitcnt vmcnt(0)
	flat_atomic_add_f32 v[154:155], v153 offset:512

.LBB0_442:
	s_andn2_b64 vcc, exec, s[50:51]
	s_cbranch_vccnz .LBB0_444
	s_waitcnt lgkmcnt(0)
	v_ashrrev_i32_e32 v153, 31, v152
	v_lshlrev_b64 v[154:155], 8, v[152:153]
	v_lshl_add_u64 v[154:155], s[88:89], 0, v[154:155]
	v_lshl_add_u64 v[166:167], v[154:155], 0, v[142:143]
	flat_load_dwordx4 v[154:157], v[166:167]
	global_load_dwordx4 v[158:161], v[166:167], off offset:48
	global_load_dwordx4 v[162:165], v[166:167], off offset:32
	s_nop 0
	global_load_dwordx4 v[166:169], v[166:167], off offset:16
	s_waitcnt vmcnt(0) lgkmcnt(0)
	v_mov_b32_e32 v183, v156
	v_mov_b32_e32 v156, v155
	v_mov_b32_e32 v182, v154
	v_pk_mul_f32 v[154:155], v[34:35], v[156:157]
	v_mov_b32_e32 v187, v168
	v_mov_b32_e32 v168, v167
	v_pk_fma_f32 v[184:185], v[66:67], v[182:183], v[154:155] neg_lo:[0,0,1] neg_hi:[0,0,1]
	v_mov_b32_e32 v186, v166
	v_pk_mul_f32 v[154:155], v[36:37], v[168:169]
	v_mov_b32_e32 v189, v164
	v_mov_b32_e32 v164, v163
	v_pk_fma_f32 v[166:167], v[68:69], v[186:187], v[154:155] neg_lo:[0,0,1] neg_hi:[0,0,1]
	v_mov_b32_e32 v188, v162
	v_pk_mul_f32 v[154:155], v[30:31], v[164:165]
	v_mov_b32_e32 v191, v160
	v_mov_b32_e32 v160, v159
	v_pk_fma_f32 v[162:163], v[62:63], v[188:189], v[154:155] neg_lo:[0,0,1] neg_hi:[0,0,1]
	v_mov_b32_e32 v190, v158
	v_pk_mul_f32 v[154:155], v[32:33], v[160:161]
	v_pk_mul_f32 v[160:161], v[64:65], v[160:161]
	v_pk_fma_f32 v[192:193], v[64:65], v[190:191], v[154:155] neg_lo:[0,0,1] neg_hi:[0,0,1]
	v_pk_mul_f32 v[154:155], v[66:67], v[156:157]
	v_pk_mul_f32 v[156:157], v[68:69], v[168:169]
	v_pk_fma_f32 v[154:155], v[34:35], v[182:183], v[154:155]
	v_pk_fma_f32 v[158:159], v[36:37], v[186:187], v[156:157]
	v_pk_mul_f32 v[156:157], v[62:63], v[164:165]
	v_pk_mul_f32 v[164:165], v[166:167], s[96:97] op_sel_hi:[1,0]
	v_pk_mul_f32 v[166:167], v[184:185], s[96:97] op_sel_hi:[1,0]
	v_pk_mul_f32 v[182:183], v[162:163], s[96:97] op_sel_hi:[1,0]
	v_cvt_pk_bf16_f32 v162, v166, v167
	v_mov_b64_e32 v[166:167], s[78:79]
	v_pk_mul_f32 v[168:169], v[192:193], s[96:97] op_sel_hi:[1,0]
	v_mad_i64_i32 v[166:167], s[50:51], v152, s83, v[166:167]
	v_pk_fma_f32 v[156:157], v[30:31], v[188:189], v[156:157]
	v_cvt_pk_bf16_f32 v163, v164, v165
	v_cvt_pk_bf16_f32 v164, v182, v183
	v_cvt_pk_bf16_f32 v165, v168, v169
	v_lshl_add_u64 v[166:167], v[140:141], 1, v[166:167]
	v_lshlrev_b32_e32 v168, 1, v179
	v_mov_b32_e32 v169, v3
	v_pk_fma_f32 v[160:161], v[32:33], v[190:191], v[160:161]
	v_lshl_add_u64 v[166:167], v[166:167], 0, v[168:169]
	v_pk_mul_f32 v[154:155], v[154:155], s[96:97] op_sel_hi:[1,0]
	v_pk_mul_f32 v[156:157], v[156:157], s[96:97] op_sel_hi:[1,0]
	global_store_dwordx4 v[166:167], v[162:165], off offset:256 sc1
	v_pk_mul_f32 v[158:159], v[158:159], s[96:97] op_sel_hi:[1,0]
	v_pk_mul_f32 v[160:161], v[160:161], s[96:97] op_sel_hi:[1,0]
	v_cvt_pk_bf16_f32 v154, v154, v155
	v_cvt_pk_bf16_f32 v155, v158, v159
	v_cvt_pk_bf16_f32 v156, v156, v157
	s_nop 0
	v_cvt_pk_bf16_f32 v157, v160, v161
	global_store_dwordx4 v[166:167], v[154:157], off offset:320 sc1

.LBB0_446:
	s_and_b64 vcc, exec, s[18:19]
	s_cbranch_vccnz .LBB0_460
	s_andn2_b64 vcc, exec, s[80:81]
	s_cbranch_vccnz .LBB0_455
	s_andn2_b64 vcc, exec, s[22:23]
	s_cbranch_vccnz .LBB0_452
	s_and_saveexec_b64 s[50:51], s[16:17]
	s_cbranch_execz .LBB0_451
	s_waitcnt lgkmcnt(0)
	v_ashrrev_i32_e32 v153, 31, v152
	v_lshlrev_b64 v[154:155], 8, v[152:153]
	v_lshl_add_u64 v[154:155], s[88:89], 0, v[154:155]
	v_lshl_add_u64 v[166:167], v[154:155], 0, v[150:151]
	flat_load_dwordx4 v[154:157], v[166:167]
	global_load_dwordx4 v[158:161], v[166:167], off offset:48
	global_load_dwordx4 v[162:165], v[166:167], off offset:32
	s_nop 0
	global_load_dwordx4 v[166:169], v[166:167], off offset:16
	v_mov_b32_e32 v182, v58
	v_mov_b32_e32 v183, v26
	v_readlane_b32 s86, v235, 45
	v_readlane_b32 s87, v235, 46
	s_waitcnt vmcnt(0) lgkmcnt(0)
	v_pk_mul_f32 v[182:183], v[182:183], v[154:155]
	s_nop 0
	v_sub_f32_e32 v145, v182, v183
	v_mov_b32_e32 v182, v59
	v_mov_b32_e32 v183, v27
	v_pk_mul_f32 v[182:183], v[182:183], v[156:157]
	s_nop 0
	v_sub_f32_e32 v153, v182, v183
	v_mov_b32_e32 v182, v60
	v_mov_b32_e32 v183, v28
	v_pk_mul_f32 v[182:183], v[182:183], v[166:167]
	s_nop 0
	v_sub_f32_e32 v181, v182, v183
	v_mov_b32_e32 v182, v61
	v_mov_b32_e32 v183, v29
	v_pk_mul_f32 v[182:183], v[182:183], v[168:169]
	s_nop 0
	v_sub_f32_e32 v184, v182, v183
	v_mov_b32_e32 v182, v54
	v_mov_b32_e32 v183, v22
	v_pk_mul_f32 v[182:183], v[182:183], v[162:163]
	s_nop 0
	v_sub_f32_e32 v185, v182, v183
	v_mov_b32_e32 v182, v55
	v_mov_b32_e32 v183, v23
	v_pk_mul_f32 v[182:183], v[182:183], v[164:165]
	s_nop 0
	v_sub_f32_e32 v186, v182, v183
	v_mov_b32_e32 v182, v56
	v_mov_b32_e32 v183, v24
	v_pk_mul_f32 v[182:183], v[182:183], v[158:159]
	s_nop 0
	v_sub_f32_e32 v187, v182, v183
	v_mov_b32_e32 v182, v57
	v_mov_b32_e32 v183, v25
	v_pk_mul_f32 v[182:183], v[182:183], v[160:161]
	s_nop 0
	v_sub_f32_e32 v188, v182, v183
	v_mov_b32_e32 v182, v26
	v_mov_b32_e32 v183, v58
	v_pk_mul_f32 v[154:155], v[182:183], v[154:155]
	s_nop 0
	v_add_f32_e32 v182, v154, v155
	v_mov_b32_e32 v154, v27
	v_mov_b32_e32 v155, v59
	v_pk_mul_f32 v[154:155], v[154:155], v[156:157]
	s_nop 0
	v_add_f32_e32 v183, v154, v155
	v_mov_b32_e32 v154, v28
	v_mov_b32_e32 v155, v60
	v_pk_mul_f32 v[154:155], v[154:155], v[166:167]
	s_nop 0
	v_add_f32_e32 v166, v154, v155
	v_mov_b32_e32 v154, v29
	v_mov_b32_e32 v155, v61
	v_pk_mul_f32 v[154:155], v[154:155], v[168:169]
	s_nop 0
	v_add_f32_e32 v167, v154, v155
	v_mov_b32_e32 v154, v22
	v_mov_b32_e32 v155, v54
	v_pk_mul_f32 v[154:155], v[154:155], v[162:163]
	s_nop 0
	v_add_f32_e32 v162, v154, v155
	v_mov_b32_e32 v154, v23
	v_mov_b32_e32 v155, v55
	v_pk_mul_f32 v[154:155], v[154:155], v[164:165]
	s_nop 0
	v_add_f32_e32 v163, v154, v155
	v_mov_b32_e32 v154, v24
	v_mov_b32_e32 v155, v56
	v_pk_mul_f32 v[154:155], v[154:155], v[158:159]
	s_nop 0
	v_add_f32_e32 v164, v154, v155
	v_mov_b32_e32 v154, v25
	v_mov_b32_e32 v155, v57
	v_pk_mul_f32 v[154:155], v[154:155], v[160:161]
	s_nop 0
	v_add_f32_e32 v161, v154, v155
	v_cvt_pk_bf16_f32 v154, v145, v153
	v_cvt_pk_bf16_f32 v155, v181, v184
	v_cvt_pk_bf16_f32 v156, v185, v186
	v_cvt_pk_bf16_f32 v157, v187, v188
	v_cvt_pk_bf16_f32 v158, v182, v183
	v_cvt_pk_bf16_f32 v159, v166, v167
	v_cvt_pk_bf16_f32 v160, v162, v163
	v_mov_b64_e32 v[162:163], s[86:87]
	v_mad_i64_i32 v[162:163], s[86:87], v152, s83, v[162:163]
	v_lshl_add_u64 v[162:163], v[4:5], 1, v[162:163]
	v_cvt_pk_bf16_f32 v161, v164, v161
	global_store_dwordx4 v[162:163], v[154:157], off offset:256 sc1
	global_store_dwordx4 v[162:163], v[158:161], off offset:320 sc1
	global_store_dwordx4 v[162:163], v[154:157], off offset:640 sc1
	global_store_dwordx4 v[162:163], v[158:161], off offset:704 sc1
	global_store_dwordx4 v[162:163], v[154:157], off offset:1024 sc1
	global_store_dwordx4 v[162:163], v[158:161], off offset:1088 sc1
	global_store_dwordx4 v[162:163], v[154:157], off offset:1408 sc1
	global_store_dwordx4 v[162:163], v[158:161], off offset:1472 sc1
	global_store_dwordx4 v[162:163], v[154:157], off offset:1792 sc1
	global_store_dwordx4 v[162:163], v[158:161], off offset:1856 sc1
	global_store_dwordx4 v[162:163], v[154:157], off offset:2176 sc1
	global_store_dwordx4 v[162:163], v[158:161], off offset:2240 sc1
	global_store_dwordx4 v[162:163], v[154:157], off offset:2560 sc1
	global_store_dwordx4 v[162:163], v[158:161], off offset:2624 sc1
	global_store_dwordx4 v[162:163], v[154:157], off offset:2944 sc1
	global_store_dwordx4 v[162:163], v[158:161], off offset:3008 sc1

.LBB0_452:
	s_andn2_b64 vcc, exec, s[50:51]
	s_cbranch_vccnz .LBB0_454
	s_waitcnt lgkmcnt(0)
	v_ashrrev_i32_e32 v153, 31, v152
	v_readlane_b32 s50, v235, 53
	v_lshlrev_b64 v[154:155], 9, v[152:153]
	v_readlane_b32 s51, v235, 54
	v_readlane_b32 s86, v235, 51
	s_nop 0
	v_lshl_add_u64 v[154:155], s[50:51], 0, v[154:155]
	v_lshl_add_u64 v[162:163], v[154:155], 0, v[2:3]
	flat_load_dwordx4 v[154:157], v[162:163]
	global_load_dwordx4 v[158:161], v[162:163], off offset:48
	global_load_dwordx4 v[182:185], v[162:163], off offset:32
	global_load_dwordx4 v[186:189], v[162:163], off offset:16
	s_and_b64 s[50:51], s[14:15], exec
	v_readlane_b32 s50, v235, 50
	v_readlane_b32 s51, v235, 52
	s_cselect_b32 s51, s50, s51
	v_readlane_b32 s50, v235, 49
	s_cselect_b32 s50, s50, s86
	s_waitcnt vmcnt(0) lgkmcnt(0)
	v_mov_b32_e32 v191, v156
	v_mov_b32_e32 v156, v155
	v_mov_b32_e32 v190, v154
	v_pk_mul_f32 v[154:155], v[26:27], v[156:157]
	v_mov_b32_e32 v193, v188
	v_mov_b32_e32 v188, v187
	v_pk_fma_f32 v[162:163], v[58:59], v[190:191], v[154:155] neg_lo:[0,0,1] neg_hi:[0,0,1]
	v_mov_b32_e32 v192, v186
	v_pk_mul_f32 v[154:155], v[28:29], v[188:189]
	v_mov_b32_e32 v187, v184
	v_mov_b32_e32 v184, v183
	v_pk_fma_f32 v[164:165], v[60:61], v[192:193], v[154:155] neg_lo:[0,0,1] neg_hi:[0,0,1]
	v_mov_b32_e32 v186, v182
	v_pk_mul_f32 v[154:155], v[22:23], v[184:185]
	v_mov_b32_e32 v183, v160
	v_mov_b32_e32 v160, v159
	v_pk_fma_f32 v[166:167], v[54:55], v[186:187], v[154:155] neg_lo:[0,0,1] neg_hi:[0,0,1]
	v_mov_b32_e32 v182, v158
	v_pk_mul_f32 v[154:155], v[24:25], v[160:161]
	v_pk_mul_f32 v[160:161], v[56:57], v[160:161]
	v_pk_fma_f32 v[168:169], v[56:57], v[182:183], v[154:155] neg_lo:[0,0,1] neg_hi:[0,0,1]
	v_pk_fma_f32 v[160:161], v[24:25], v[182:183], v[160:161]
	v_lshlrev_b64 v[182:183], 11, v[152:153]
	v_pk_mul_f32 v[154:155], v[58:59], v[156:157]
	v_pk_mul_f32 v[156:157], v[60:61], v[188:189]
	v_lshl_add_u64 v[182:183], s[50:51], 0, v[182:183]
	v_pk_fma_f32 v[158:159], v[28:29], v[192:193], v[156:157]
	v_pk_mul_f32 v[156:157], v[54:55], v[184:185]
	v_lshl_add_u64 v[182:183], v[148:149], 1, v[182:183]
	v_lshlrev_b32_e32 v184, 1, v180
	v_mov_b32_e32 v185, v3
	v_pk_fma_f32 v[154:155], v[26:27], v[190:191], v[154:155]
	v_pk_fma_f32 v[156:157], v[22:23], v[186:187], v[156:157]
	v_lshl_add_u64 v[182:183], v[182:183], 0, v[184:185]
	v_mov_b32_e32 v184, v146
	v_mov_b32_e32 v185, v146
	v_pk_mul_f32 v[164:165], v[184:185], v[164:165]
	v_pk_mul_f32 v[162:163], v[146:147], v[162:163]
	v_pk_mul_f32 v[154:155], v[146:147], v[154:155]
	v_pk_mul_f32 v[156:157], v[146:147], v[156:157]
	v_pk_mul_f32 v[168:169], v[184:185], v[168:169]
	v_pk_mul_f32 v[166:167], v[146:147], v[166:167]
	v_cvt_pk_bf16_f32 v162, v162, v163
	v_cvt_pk_bf16_f32 v163, v164, v165
	v_pk_mul_f32 v[158:159], v[184:185], v[158:159]
	v_cvt_pk_bf16_f32 v164, v166, v167
	v_cvt_pk_bf16_f32 v165, v168, v169
	global_store_dwordx4 v[182:183], v[162:165], off sc1
	v_pk_mul_f32 v[160:161], v[184:185], v[160:161]
	v_cvt_pk_bf16_f32 v154, v154, v155
	v_cvt_pk_bf16_f32 v155, v158, v159
	v_cvt_pk_bf16_f32 v156, v156, v157
	s_nop 0
	v_cvt_pk_bf16_f32 v157, v160, v161
	global_store_dwordx4 v[182:183], v[154:157], off offset:128 sc1

.LBB0_455:
	s_andn2_b64 vcc, exec, s[50:51]
	s_cbranch_vccnz .LBB0_459
	s_waitcnt lgkmcnt(0)
	v_ashrrev_i32_e32 v153, 31, v152
	v_readlane_b32 s50, v235, 47
	v_lshlrev_b64 v[158:159], 10, v[152:153]
	v_readlane_b32 s51, v235, 48
	v_cvt_pk_bf16_f32 v154, v58, v59
	v_mul_f32_e32 v145, v59, v59
	v_mul_f32_e32 v153, v61, v61
	v_lshl_add_u64 v[158:159], s[50:51], 0, v[158:159]
	v_lshl_add_u64 v[158:159], s[66:67], 1, v[158:159]
	v_lshl_add_u64 v[158:159], v[4:5], 1, v[158:159]
	v_cvt_pk_bf16_f32 v155, v60, v61
	v_cvt_pk_bf16_f32 v156, v54, v55
	v_cvt_pk_bf16_f32 v157, v56, v57
	global_store_dwordx4 v[158:159], v[154:157], off sc1
	v_fmac_f32_e32 v145, v58, v58
	v_fmac_f32_e32 v153, v60, v60
	v_cvt_pk_bf16_f32 v154, v26, v27
	v_cvt_pk_bf16_f32 v155, v28, v29
	v_cvt_pk_bf16_f32 v156, v22, v23
	v_cvt_pk_bf16_f32 v157, v24, v25
	global_store_dwordx4 v[158:159], v[154:157], off offset:256 sc1
	v_add_f32_e32 v145, v145, v153
	v_mul_f32_e32 v153, v55, v55
	v_mul_f32_e32 v154, v57, v57
	v_fmac_f32_e32 v153, v54, v54
	v_fmac_f32_e32 v154, v56, v56
	v_add_f32_e32 v153, v153, v154
	v_add_f32_e32 v145, v153, v145
	v_mul_f32_e32 v153, v27, v27
	v_mul_f32_e32 v154, v29, v29
	v_fmac_f32_e32 v153, v26, v26
	v_fmac_f32_e32 v154, v28, v28
	v_add_f32_e32 v153, v153, v154
	v_mul_f32_e32 v154, v23, v23
	v_mul_f32_e32 v155, v25, v25
	v_fmac_f32_e32 v154, v22, v22
	v_fmac_f32_e32 v155, v24, v24
	v_add_f32_e32 v154, v154, v155
	v_add_f32_e32 v153, v154, v153
	v_and_b32_e32 v154, 64, v178
	v_add_f32_e32 v145, v153, v145
	v_xor_b32_e32 v153, 16, v178
	v_add_u32_e32 v154, 64, v154
	v_cmp_lt_i32_e32 vcc, v153, v154
	s_nop 1
	v_cndmask_b32_e32 v153, v178, v153, vcc
	v_lshlrev_b32_e32 v153, 2, v153
	ds_bpermute_b32 v153, v153, v145
	s_waitcnt lgkmcnt(0)
	v_add_f32_e32 v145, v145, v153
	v_xor_b32_e32 v153, 32, v178
	v_cmp_lt_i32_e32 vcc, v153, v154
	s_nop 1
	v_cndmask_b32_e32 v153, v178, v153, vcc
	v_lshlrev_b32_e32 v153, 2, v153
	ds_bpermute_b32 v153, v153, v145
	s_and_saveexec_b64 s[50:51], s[12:13]
	s_cbranch_execz .LBB0_458
	s_waitcnt lgkmcnt(0)
	v_add_f32_e32 v153, v145, v153
	v_ashrrev_i32_e32 v145, 31, v144
	v_lshl_add_u64 v[154:155], v[144:145], 2, s[36:37]
	s_waitcnt vmcnt(0)
	flat_atomic_add_f32 v[154:155], v153 offset:576

.LBB0_460:
	s_andn2_b64 vcc, exec, s[50:51]
	s_cbranch_vccnz .LBB0_462
	s_waitcnt lgkmcnt(0)
	v_ashrrev_i32_e32 v153, 31, v152
	v_lshlrev_b64 v[154:155], 8, v[152:153]
	v_lshl_add_u64 v[154:155], s[88:89], 0, v[154:155]
	v_lshl_add_u64 v[166:167], v[154:155], 0, v[142:143]
	flat_load_dwordx4 v[154:157], v[166:167]
	global_load_dwordx4 v[158:161], v[166:167], off offset:48
	global_load_dwordx4 v[162:165], v[166:167], off offset:32
	s_nop 0
	global_load_dwordx4 v[166:169], v[166:167], off offset:16
	s_waitcnt vmcnt(0) lgkmcnt(0)
	v_mov_b32_e32 v183, v156
	v_mov_b32_e32 v156, v155
	v_mov_b32_e32 v182, v154
	v_pk_mul_f32 v[154:155], v[26:27], v[156:157]
	v_mov_b32_e32 v187, v168
	v_mov_b32_e32 v168, v167
	v_pk_fma_f32 v[184:185], v[58:59], v[182:183], v[154:155] neg_lo:[0,0,1] neg_hi:[0,0,1]
	v_mov_b32_e32 v186, v166
	v_pk_mul_f32 v[154:155], v[28:29], v[168:169]
	v_mov_b32_e32 v189, v164
	v_mov_b32_e32 v164, v163
	v_pk_fma_f32 v[166:167], v[60:61], v[186:187], v[154:155] neg_lo:[0,0,1] neg_hi:[0,0,1]
	v_mov_b32_e32 v188, v162
	v_pk_mul_f32 v[154:155], v[22:23], v[164:165]
	v_mov_b32_e32 v191, v160
	v_mov_b32_e32 v160, v159
	v_pk_fma_f32 v[162:163], v[54:55], v[188:189], v[154:155] neg_lo:[0,0,1] neg_hi:[0,0,1]
	v_mov_b32_e32 v190, v158
	v_pk_mul_f32 v[154:155], v[24:25], v[160:161]
	v_pk_mul_f32 v[160:161], v[56:57], v[160:161]
	v_pk_fma_f32 v[192:193], v[56:57], v[190:191], v[154:155] neg_lo:[0,0,1] neg_hi:[0,0,1]
	v_pk_mul_f32 v[154:155], v[58:59], v[156:157]
	v_pk_mul_f32 v[156:157], v[60:61], v[168:169]
	v_pk_fma_f32 v[154:155], v[26:27], v[182:183], v[154:155]
	v_pk_fma_f32 v[158:159], v[28:29], v[186:187], v[156:157]
	v_pk_mul_f32 v[156:157], v[54:55], v[164:165]
	v_pk_mul_f32 v[164:165], v[166:167], s[96:97] op_sel_hi:[1,0]
	v_pk_mul_f32 v[166:167], v[184:185], s[96:97] op_sel_hi:[1,0]
	v_pk_mul_f32 v[182:183], v[162:163], s[96:97] op_sel_hi:[1,0]
	v_cvt_pk_bf16_f32 v162, v166, v167
	v_mov_b64_e32 v[166:167], s[78:79]
	v_pk_mul_f32 v[168:169], v[192:193], s[96:97] op_sel_hi:[1,0]
	v_mad_i64_i32 v[166:167], s[50:51], v152, s83, v[166:167]
	v_pk_fma_f32 v[156:157], v[22:23], v[188:189], v[156:157]
	v_cvt_pk_bf16_f32 v163, v164, v165
	v_cvt_pk_bf16_f32 v164, v182, v183
	v_cvt_pk_bf16_f32 v165, v168, v169
	v_lshl_add_u64 v[166:167], v[140:141], 1, v[166:167]
	v_lshlrev_b32_e32 v168, 1, v179
	v_mov_b32_e32 v169, v3
	v_pk_fma_f32 v[160:161], v[24:25], v[190:191], v[160:161]
	v_lshl_add_u64 v[166:167], v[166:167], 0, v[168:169]
	v_pk_mul_f32 v[154:155], v[154:155], s[96:97] op_sel_hi:[1,0]
	v_pk_mul_f32 v[156:157], v[156:157], s[96:97] op_sel_hi:[1,0]
	global_store_dwordx4 v[166:167], v[162:165], off offset:256 sc1
	v_pk_mul_f32 v[158:159], v[158:159], s[96:97] op_sel_hi:[1,0]
	v_pk_mul_f32 v[160:161], v[160:161], s[96:97] op_sel_hi:[1,0]
	v_cvt_pk_bf16_f32 v154, v154, v155
	v_cvt_pk_bf16_f32 v155, v158, v159
	v_cvt_pk_bf16_f32 v156, v156, v157
	s_nop 0
	v_cvt_pk_bf16_f32 v157, v160, v161
	global_store_dwordx4 v[166:167], v[154:157], off offset:320 sc1

.LBB0_464:
	s_and_b64 vcc, exec, s[18:19]
	s_cbranch_vccnz .LBB0_478
	s_andn2_b64 vcc, exec, s[80:81]
	s_cbranch_vccnz .LBB0_473
	s_andn2_b64 vcc, exec, s[22:23]
	s_cbranch_vccnz .LBB0_470
	s_and_saveexec_b64 s[50:51], s[16:17]
	s_cbranch_execz .LBB0_469
	s_waitcnt lgkmcnt(0)
	v_ashrrev_i32_e32 v153, 31, v152
	v_lshlrev_b64 v[154:155], 8, v[152:153]
	v_lshl_add_u64 v[154:155], s[88:89], 0, v[154:155]
	v_lshl_add_u64 v[166:167], v[154:155], 0, v[150:151]
	flat_load_dwordx4 v[154:157], v[166:167]
	global_load_dwordx4 v[158:161], v[166:167], off offset:48
	global_load_dwordx4 v[162:165], v[166:167], off offset:32
	s_nop 0
	global_load_dwordx4 v[166:169], v[166:167], off offset:16
	v_mov_b32_e32 v182, v50
	v_mov_b32_e32 v183, v18
	v_readlane_b32 s86, v235, 45
	v_readlane_b32 s87, v235, 46
	s_waitcnt vmcnt(0) lgkmcnt(0)
	v_pk_mul_f32 v[182:183], v[182:183], v[154:155]
	s_nop 0
	v_sub_f32_e32 v145, v182, v183
	v_mov_b32_e32 v182, v51
	v_mov_b32_e32 v183, v19
	v_pk_mul_f32 v[182:183], v[182:183], v[156:157]
	s_nop 0
	v_sub_f32_e32 v153, v182, v183
	v_mov_b32_e32 v182, v52
	v_mov_b32_e32 v183, v20
	v_pk_mul_f32 v[182:183], v[182:183], v[166:167]
	s_nop 0
	v_sub_f32_e32 v181, v182, v183
	v_mov_b32_e32 v182, v53
	v_mov_b32_e32 v183, v21
	v_pk_mul_f32 v[182:183], v[182:183], v[168:169]
	s_nop 0
	v_sub_f32_e32 v184, v182, v183
	v_mov_b32_e32 v182, v46
	v_mov_b32_e32 v183, v14
	v_pk_mul_f32 v[182:183], v[182:183], v[162:163]
	s_nop 0
	v_sub_f32_e32 v185, v182, v183
	v_mov_b32_e32 v182, v47
	v_mov_b32_e32 v183, v15
	v_pk_mul_f32 v[182:183], v[182:183], v[164:165]
	s_nop 0
	v_sub_f32_e32 v186, v182, v183
	v_mov_b32_e32 v182, v48
	v_mov_b32_e32 v183, v16
	v_pk_mul_f32 v[182:183], v[182:183], v[158:159]
	s_nop 0
	v_sub_f32_e32 v187, v182, v183
	v_mov_b32_e32 v182, v49
	v_mov_b32_e32 v183, v17
	v_pk_mul_f32 v[182:183], v[182:183], v[160:161]
	s_nop 0
	v_sub_f32_e32 v188, v182, v183
	v_mov_b32_e32 v182, v18
	v_mov_b32_e32 v183, v50
	v_pk_mul_f32 v[154:155], v[182:183], v[154:155]
	s_nop 0
	v_add_f32_e32 v182, v154, v155
	v_mov_b32_e32 v154, v19
	v_mov_b32_e32 v155, v51
	v_pk_mul_f32 v[154:155], v[154:155], v[156:157]
	s_nop 0
	v_add_f32_e32 v183, v154, v155
	v_mov_b32_e32 v154, v20
	v_mov_b32_e32 v155, v52
	v_pk_mul_f32 v[154:155], v[154:155], v[166:167]
	s_nop 0
	v_add_f32_e32 v166, v154, v155
	v_mov_b32_e32 v154, v21
	v_mov_b32_e32 v155, v53
	v_pk_mul_f32 v[154:155], v[154:155], v[168:169]
	s_nop 0
	v_add_f32_e32 v167, v154, v155
	v_mov_b32_e32 v154, v14
	v_mov_b32_e32 v155, v46
	v_pk_mul_f32 v[154:155], v[154:155], v[162:163]
	s_nop 0
	v_add_f32_e32 v162, v154, v155
	v_mov_b32_e32 v154, v15
	v_mov_b32_e32 v155, v47
	v_pk_mul_f32 v[154:155], v[154:155], v[164:165]
	s_nop 0
	v_add_f32_e32 v163, v154, v155
	v_mov_b32_e32 v154, v16
	v_mov_b32_e32 v155, v48
	v_pk_mul_f32 v[154:155], v[154:155], v[158:159]
	s_nop 0
	v_add_f32_e32 v164, v154, v155
	v_mov_b32_e32 v154, v17
	v_mov_b32_e32 v155, v49
	v_pk_mul_f32 v[154:155], v[154:155], v[160:161]
	s_nop 0
	v_add_f32_e32 v161, v154, v155
	v_cvt_pk_bf16_f32 v154, v145, v153
	v_cvt_pk_bf16_f32 v155, v181, v184
	v_cvt_pk_bf16_f32 v156, v185, v186
	v_cvt_pk_bf16_f32 v157, v187, v188
	v_cvt_pk_bf16_f32 v158, v182, v183
	v_cvt_pk_bf16_f32 v159, v166, v167
	v_cvt_pk_bf16_f32 v160, v162, v163
	v_mov_b64_e32 v[162:163], s[86:87]
	v_mad_i64_i32 v[162:163], s[86:87], v152, s83, v[162:163]
	v_lshl_add_u64 v[162:163], v[4:5], 1, v[162:163]
	v_cvt_pk_bf16_f32 v161, v164, v161
	global_store_dwordx4 v[162:163], v[154:157], off offset:256 sc1
	global_store_dwordx4 v[162:163], v[158:161], off offset:320 sc1
	global_store_dwordx4 v[162:163], v[154:157], off offset:640 sc1
	global_store_dwordx4 v[162:163], v[158:161], off offset:704 sc1
	global_store_dwordx4 v[162:163], v[154:157], off offset:1024 sc1
	global_store_dwordx4 v[162:163], v[158:161], off offset:1088 sc1
	global_store_dwordx4 v[162:163], v[154:157], off offset:1408 sc1
	global_store_dwordx4 v[162:163], v[158:161], off offset:1472 sc1
	global_store_dwordx4 v[162:163], v[154:157], off offset:1792 sc1
	global_store_dwordx4 v[162:163], v[158:161], off offset:1856 sc1
	global_store_dwordx4 v[162:163], v[154:157], off offset:2176 sc1
	global_store_dwordx4 v[162:163], v[158:161], off offset:2240 sc1
	global_store_dwordx4 v[162:163], v[154:157], off offset:2560 sc1
	global_store_dwordx4 v[162:163], v[158:161], off offset:2624 sc1
	global_store_dwordx4 v[162:163], v[154:157], off offset:2944 sc1
	global_store_dwordx4 v[162:163], v[158:161], off offset:3008 sc1

.LBB0_470:
	s_andn2_b64 vcc, exec, s[50:51]
	s_cbranch_vccnz .LBB0_472
	s_waitcnt lgkmcnt(0)
	v_ashrrev_i32_e32 v153, 31, v152
	v_readlane_b32 s50, v235, 53
	v_lshlrev_b64 v[154:155], 9, v[152:153]
	v_readlane_b32 s51, v235, 54
	v_readlane_b32 s86, v235, 51
	s_nop 0
	v_lshl_add_u64 v[154:155], s[50:51], 0, v[154:155]
	v_lshl_add_u64 v[162:163], v[154:155], 0, v[2:3]
	flat_load_dwordx4 v[154:157], v[162:163]
	global_load_dwordx4 v[158:161], v[162:163], off offset:48
	global_load_dwordx4 v[182:185], v[162:163], off offset:32
	global_load_dwordx4 v[186:189], v[162:163], off offset:16
	s_and_b64 s[50:51], s[14:15], exec
	v_readlane_b32 s50, v235, 50
	v_readlane_b32 s51, v235, 52
	s_cselect_b32 s51, s50, s51
	v_readlane_b32 s50, v235, 49
	s_cselect_b32 s50, s50, s86
	s_waitcnt vmcnt(0) lgkmcnt(0)
	v_mov_b32_e32 v191, v156
	v_mov_b32_e32 v156, v155
	v_mov_b32_e32 v190, v154
	v_pk_mul_f32 v[154:155], v[18:19], v[156:157]
	v_mov_b32_e32 v193, v188
	v_mov_b32_e32 v188, v187
	v_pk_fma_f32 v[162:163], v[50:51], v[190:191], v[154:155] neg_lo:[0,0,1] neg_hi:[0,0,1]
	v_mov_b32_e32 v192, v186
	v_pk_mul_f32 v[154:155], v[20:21], v[188:189]
	v_mov_b32_e32 v187, v184
	v_mov_b32_e32 v184, v183
	v_pk_fma_f32 v[164:165], v[52:53], v[192:193], v[154:155] neg_lo:[0,0,1] neg_hi:[0,0,1]
	v_mov_b32_e32 v186, v182
	v_pk_mul_f32 v[154:155], v[14:15], v[184:185]
	v_mov_b32_e32 v183, v160
	v_mov_b32_e32 v160, v159
	v_pk_fma_f32 v[166:167], v[46:47], v[186:187], v[154:155] neg_lo:[0,0,1] neg_hi:[0,0,1]
	v_mov_b32_e32 v182, v158
	v_pk_mul_f32 v[154:155], v[16:17], v[160:161]
	v_pk_mul_f32 v[160:161], v[48:49], v[160:161]
	v_pk_fma_f32 v[168:169], v[48:49], v[182:183], v[154:155] neg_lo:[0,0,1] neg_hi:[0,0,1]
	v_pk_fma_f32 v[160:161], v[16:17], v[182:183], v[160:161]
	v_lshlrev_b64 v[182:183], 11, v[152:153]
	v_pk_mul_f32 v[154:155], v[50:51], v[156:157]
	v_pk_mul_f32 v[156:157], v[52:53], v[188:189]
	v_lshl_add_u64 v[182:183], s[50:51], 0, v[182:183]
	v_pk_fma_f32 v[158:159], v[20:21], v[192:193], v[156:157]
	v_pk_mul_f32 v[156:157], v[46:47], v[184:185]
	v_lshl_add_u64 v[182:183], v[148:149], 1, v[182:183]
	v_lshlrev_b32_e32 v184, 1, v180
	v_mov_b32_e32 v185, v3
	v_pk_fma_f32 v[154:155], v[18:19], v[190:191], v[154:155]
	v_pk_fma_f32 v[156:157], v[14:15], v[186:187], v[156:157]
	v_lshl_add_u64 v[182:183], v[182:183], 0, v[184:185]
	v_mov_b32_e32 v184, v146
	v_mov_b32_e32 v185, v146
	v_pk_mul_f32 v[164:165], v[184:185], v[164:165]
	v_pk_mul_f32 v[162:163], v[146:147], v[162:163]
	v_pk_mul_f32 v[154:155], v[146:147], v[154:155]
	v_pk_mul_f32 v[156:157], v[146:147], v[156:157]
	v_pk_mul_f32 v[168:169], v[184:185], v[168:169]
	v_pk_mul_f32 v[166:167], v[146:147], v[166:167]
	v_cvt_pk_bf16_f32 v162, v162, v163
	v_cvt_pk_bf16_f32 v163, v164, v165
	v_pk_mul_f32 v[158:159], v[184:185], v[158:159]
	v_cvt_pk_bf16_f32 v164, v166, v167
	v_cvt_pk_bf16_f32 v165, v168, v169
	global_store_dwordx4 v[182:183], v[162:165], off sc1
	v_pk_mul_f32 v[160:161], v[184:185], v[160:161]
	v_cvt_pk_bf16_f32 v154, v154, v155
	v_cvt_pk_bf16_f32 v155, v158, v159
	v_cvt_pk_bf16_f32 v156, v156, v157
	s_nop 0
	v_cvt_pk_bf16_f32 v157, v160, v161
	global_store_dwordx4 v[182:183], v[154:157], off offset:128 sc1

.LBB0_473:
	s_andn2_b64 vcc, exec, s[50:51]
	s_cbranch_vccnz .LBB0_477
	s_waitcnt lgkmcnt(0)
	v_ashrrev_i32_e32 v153, 31, v152
	v_readlane_b32 s50, v235, 47
	v_lshlrev_b64 v[158:159], 10, v[152:153]
	v_readlane_b32 s51, v235, 48
	v_cvt_pk_bf16_f32 v154, v50, v51
	v_mul_f32_e32 v145, v51, v51
	v_mul_f32_e32 v153, v53, v53
	v_lshl_add_u64 v[158:159], s[50:51], 0, v[158:159]
	v_lshl_add_u64 v[158:159], s[66:67], 1, v[158:159]
	v_lshl_add_u64 v[158:159], v[4:5], 1, v[158:159]
	v_cvt_pk_bf16_f32 v155, v52, v53
	v_cvt_pk_bf16_f32 v156, v46, v47
	v_cvt_pk_bf16_f32 v157, v48, v49
	global_store_dwordx4 v[158:159], v[154:157], off sc1
	v_fmac_f32_e32 v145, v50, v50
	v_fmac_f32_e32 v153, v52, v52
	v_cvt_pk_bf16_f32 v154, v18, v19
	v_cvt_pk_bf16_f32 v155, v20, v21
	v_cvt_pk_bf16_f32 v156, v14, v15
	v_cvt_pk_bf16_f32 v157, v16, v17
	global_store_dwordx4 v[158:159], v[154:157], off offset:256 sc1
	v_add_f32_e32 v145, v145, v153
	v_mul_f32_e32 v153, v47, v47
	v_mul_f32_e32 v154, v49, v49
	v_fmac_f32_e32 v153, v46, v46
	v_fmac_f32_e32 v154, v48, v48
	v_add_f32_e32 v153, v153, v154
	v_add_f32_e32 v145, v153, v145
	v_mul_f32_e32 v153, v19, v19
	v_mul_f32_e32 v154, v21, v21
	v_fmac_f32_e32 v153, v18, v18
	v_fmac_f32_e32 v154, v20, v20
	v_add_f32_e32 v153, v153, v154
	v_mul_f32_e32 v154, v15, v15
	v_mul_f32_e32 v155, v17, v17
	v_fmac_f32_e32 v154, v14, v14
	v_fmac_f32_e32 v155, v16, v16
	v_add_f32_e32 v154, v154, v155
	v_add_f32_e32 v153, v154, v153
	v_and_b32_e32 v154, 64, v178
	v_add_f32_e32 v145, v153, v145
	v_xor_b32_e32 v153, 16, v178
	v_add_u32_e32 v154, 64, v154
	v_cmp_lt_i32_e32 vcc, v153, v154
	s_nop 1
	v_cndmask_b32_e32 v153, v178, v153, vcc
	v_lshlrev_b32_e32 v153, 2, v153
	ds_bpermute_b32 v153, v153, v145
	s_waitcnt lgkmcnt(0)
	v_add_f32_e32 v145, v145, v153
	v_xor_b32_e32 v153, 32, v178
	v_cmp_lt_i32_e32 vcc, v153, v154
	s_nop 1
	v_cndmask_b32_e32 v153, v178, v153, vcc
	v_lshlrev_b32_e32 v153, 2, v153
	ds_bpermute_b32 v153, v153, v145
	s_and_saveexec_b64 s[50:51], s[12:13]
	s_cbranch_execz .LBB0_476
	s_waitcnt lgkmcnt(0)
	v_add_f32_e32 v153, v145, v153
	v_ashrrev_i32_e32 v145, 31, v144
	v_lshl_add_u64 v[154:155], v[144:145], 2, s[36:37]
	s_waitcnt vmcnt(0)
	flat_atomic_add_f32 v[154:155], v153 offset:640

.LBB0_478:
	s_andn2_b64 vcc, exec, s[50:51]
	s_cbranch_vccnz .LBB0_480
	s_waitcnt lgkmcnt(0)
	v_ashrrev_i32_e32 v153, 31, v152
	v_lshlrev_b64 v[154:155], 8, v[152:153]
	v_lshl_add_u64 v[154:155], s[88:89], 0, v[154:155]
	v_lshl_add_u64 v[166:167], v[154:155], 0, v[142:143]
	flat_load_dwordx4 v[154:157], v[166:167]
	global_load_dwordx4 v[158:161], v[166:167], off offset:48
	global_load_dwordx4 v[162:165], v[166:167], off offset:32
	s_nop 0
	global_load_dwordx4 v[166:169], v[166:167], off offset:16
	s_waitcnt vmcnt(0) lgkmcnt(0)
	v_mov_b32_e32 v183, v156
	v_mov_b32_e32 v156, v155
	v_mov_b32_e32 v182, v154
	v_pk_mul_f32 v[154:155], v[18:19], v[156:157]
	v_mov_b32_e32 v187, v168
	v_mov_b32_e32 v168, v167
	v_pk_fma_f32 v[184:185], v[50:51], v[182:183], v[154:155] neg_lo:[0,0,1] neg_hi:[0,0,1]
	v_mov_b32_e32 v186, v166
	v_pk_mul_f32 v[154:155], v[20:21], v[168:169]
	v_mov_b32_e32 v189, v164
	v_mov_b32_e32 v164, v163
	v_pk_fma_f32 v[166:167], v[52:53], v[186:187], v[154:155] neg_lo:[0,0,1] neg_hi:[0,0,1]
	v_mov_b32_e32 v188, v162
	v_pk_mul_f32 v[154:155], v[14:15], v[164:165]
	v_mov_b32_e32 v191, v160
	v_mov_b32_e32 v160, v159
	v_pk_fma_f32 v[162:163], v[46:47], v[188:189], v[154:155] neg_lo:[0,0,1] neg_hi:[0,0,1]
	v_mov_b32_e32 v190, v158
	v_pk_mul_f32 v[154:155], v[16:17], v[160:161]
	v_pk_mul_f32 v[160:161], v[48:49], v[160:161]
	v_pk_fma_f32 v[192:193], v[48:49], v[190:191], v[154:155] neg_lo:[0,0,1] neg_hi:[0,0,1]
	v_pk_mul_f32 v[154:155], v[50:51], v[156:157]
	v_pk_mul_f32 v[156:157], v[52:53], v[168:169]
	v_pk_fma_f32 v[154:155], v[18:19], v[182:183], v[154:155]
	v_pk_fma_f32 v[158:159], v[20:21], v[186:187], v[156:157]
	v_pk_mul_f32 v[156:157], v[46:47], v[164:165]
	v_pk_mul_f32 v[164:165], v[166:167], s[96:97] op_sel_hi:[1,0]
	v_pk_mul_f32 v[166:167], v[184:185], s[96:97] op_sel_hi:[1,0]
	v_pk_mul_f32 v[182:183], v[162:163], s[96:97] op_sel_hi:[1,0]
	v_cvt_pk_bf16_f32 v162, v166, v167
	v_mov_b64_e32 v[166:167], s[78:79]
	v_pk_mul_f32 v[168:169], v[192:193], s[96:97] op_sel_hi:[1,0]
	v_mad_i64_i32 v[166:167], s[50:51], v152, s83, v[166:167]
	v_pk_fma_f32 v[156:157], v[14:15], v[188:189], v[156:157]
	v_cvt_pk_bf16_f32 v163, v164, v165
	v_cvt_pk_bf16_f32 v164, v182, v183
	v_cvt_pk_bf16_f32 v165, v168, v169
	v_lshl_add_u64 v[166:167], v[140:141], 1, v[166:167]
	v_lshlrev_b32_e32 v168, 1, v179
	v_mov_b32_e32 v169, v3
	v_pk_fma_f32 v[160:161], v[16:17], v[190:191], v[160:161]
	v_lshl_add_u64 v[166:167], v[166:167], 0, v[168:169]
	v_pk_mul_f32 v[154:155], v[154:155], s[96:97] op_sel_hi:[1,0]
	v_pk_mul_f32 v[156:157], v[156:157], s[96:97] op_sel_hi:[1,0]
	global_store_dwordx4 v[166:167], v[162:165], off offset:256 sc1
	v_pk_mul_f32 v[158:159], v[158:159], s[96:97] op_sel_hi:[1,0]
	v_pk_mul_f32 v[160:161], v[160:161], s[96:97] op_sel_hi:[1,0]
	v_cvt_pk_bf16_f32 v154, v154, v155
	v_cvt_pk_bf16_f32 v155, v158, v159
	v_cvt_pk_bf16_f32 v156, v156, v157
	s_nop 0
	v_cvt_pk_bf16_f32 v157, v160, v161
	global_store_dwordx4 v[166:167], v[154:157], off offset:320 sc1

.LBB0_482:
	s_and_b64 vcc, exec, s[18:19]
	s_mov_b64 s[18:19], -1
	s_cbranch_vccnz .LBB0_496
	s_andn2_b64 vcc, exec, s[80:81]
	s_cbranch_vccnz .LBB0_491
	s_andn2_b64 vcc, exec, s[22:23]
	s_cbranch_vccnz .LBB0_488
	s_and_saveexec_b64 s[18:19], s[16:17]
	s_cbranch_execz .LBB0_487
	s_waitcnt lgkmcnt(0)
	v_ashrrev_i32_e32 v153, 31, v152
	v_lshlrev_b64 v[154:155], 8, v[152:153]
	v_lshl_add_u64 v[154:155], s[88:89], 0, v[154:155]
	v_lshl_add_u64 v[150:151], v[154:155], 0, v[150:151]
	flat_load_dwordx4 v[154:157], v[150:151]
	global_load_dwordx4 v[158:161], v[150:151], off offset:48
	global_load_dwordx4 v[162:165], v[150:151], off offset:32
	global_load_dwordx4 v[166:169], v[150:151], off offset:16
	v_mov_b32_e32 v150, v42
	v_mov_b32_e32 v151, v10
	v_readlane_b32 s16, v235, 45
	v_readlane_b32 s17, v235, 46
	s_waitcnt vmcnt(0) lgkmcnt(0)
	v_pk_mul_f32 v[150:151], v[150:151], v[154:155]
	s_nop 0
	v_sub_f32_e32 v145, v150, v151
	v_mov_b32_e32 v150, v43
	v_mov_b32_e32 v151, v11
	v_pk_mul_f32 v[150:151], v[150:151], v[156:157]
	s_nop 0
	v_sub_f32_e32 v153, v150, v151
	v_mov_b32_e32 v150, v44
	v_mov_b32_e32 v151, v12
	v_pk_mul_f32 v[150:151], v[150:151], v[166:167]
	s_nop 0
	v_sub_f32_e32 v181, v150, v151
	v_mov_b32_e32 v150, v45
	v_mov_b32_e32 v151, v13
	v_pk_mul_f32 v[150:151], v[150:151], v[168:169]
	s_nop 0
	v_sub_f32_e32 v182, v150, v151
	v_mov_b32_e32 v150, v38
	v_mov_b32_e32 v151, v6
	v_pk_mul_f32 v[150:151], v[150:151], v[162:163]
	s_nop 0
	v_sub_f32_e32 v183, v150, v151
	v_mov_b32_e32 v150, v39
	v_mov_b32_e32 v151, v7
	v_pk_mul_f32 v[150:151], v[150:151], v[164:165]
	s_nop 0
	v_sub_f32_e32 v184, v150, v151
	v_mov_b32_e32 v150, v40
	v_mov_b32_e32 v151, v8
	v_pk_mul_f32 v[150:151], v[150:151], v[158:159]
	s_nop 0
	v_sub_f32_e32 v185, v150, v151
	v_mov_b32_e32 v150, v41
	v_mov_b32_e32 v151, v9
	v_pk_mul_f32 v[150:151], v[150:151], v[160:161]
	s_nop 0
	v_sub_f32_e32 v186, v150, v151
	v_mov_b32_e32 v150, v10
	v_mov_b32_e32 v151, v42
	v_pk_mul_f32 v[150:151], v[150:151], v[154:155]
	v_cvt_pk_bf16_f32 v154, v145, v153
	v_cvt_pk_bf16_f32 v155, v181, v182
	s_nop 0
	v_add_f32_e32 v187, v150, v151
	v_mov_b32_e32 v150, v11
	v_mov_b32_e32 v151, v43
	v_pk_mul_f32 v[150:151], v[150:151], v[156:157]
	v_cvt_pk_bf16_f32 v156, v183, v184
	v_cvt_pk_bf16_f32 v157, v185, v186
	s_nop 0
	v_add_f32_e32 v188, v150, v151
	v_mov_b32_e32 v150, v12
	v_mov_b32_e32 v151, v44
	v_pk_mul_f32 v[150:151], v[150:151], v[166:167]
	s_nop 0
	v_add_f32_e32 v166, v150, v151
	v_mov_b32_e32 v150, v13
	v_mov_b32_e32 v151, v45
	v_pk_mul_f32 v[150:151], v[150:151], v[168:169]
	s_nop 0
	v_add_f32_e32 v167, v150, v151
	v_mov_b32_e32 v150, v6
	v_mov_b32_e32 v151, v38
	v_pk_mul_f32 v[150:151], v[150:151], v[162:163]
	s_nop 0
	v_add_f32_e32 v162, v150, v151
	v_mov_b32_e32 v150, v7
	v_mov_b32_e32 v151, v39
	v_pk_mul_f32 v[150:151], v[150:151], v[164:165]
	s_nop 0
	v_add_f32_e32 v163, v150, v151
	v_mov_b32_e32 v150, v8
	v_mov_b32_e32 v151, v40
	v_pk_mul_f32 v[150:151], v[150:151], v[158:159]
	v_cvt_pk_bf16_f32 v158, v187, v188
	v_cvt_pk_bf16_f32 v159, v166, v167
	s_nop 0
	v_add_f32_e32 v164, v150, v151
	v_mov_b32_e32 v150, v9
	v_mov_b32_e32 v151, v41
	v_pk_mul_f32 v[150:151], v[150:151], v[160:161]
	v_cvt_pk_bf16_f32 v160, v162, v163
	s_nop 0
	v_add_f32_e32 v150, v150, v151
	v_cvt_pk_bf16_f32 v161, v164, v150
	v_mov_b64_e32 v[150:151], s[16:17]
	v_mad_i64_i32 v[150:151], s[16:17], v152, s83, v[150:151]
	v_lshl_add_u64 v[150:151], v[4:5], 1, v[150:151]
	global_store_dwordx4 v[150:151], v[154:157], off offset:256 sc1
	global_store_dwordx4 v[150:151], v[158:161], off offset:320 sc1
	global_store_dwordx4 v[150:151], v[154:157], off offset:640 sc1
	global_store_dwordx4 v[150:151], v[158:161], off offset:704 sc1
	global_store_dwordx4 v[150:151], v[154:157], off offset:1024 sc1
	global_store_dwordx4 v[150:151], v[158:161], off offset:1088 sc1
	global_store_dwordx4 v[150:151], v[154:157], off offset:1408 sc1
	global_store_dwordx4 v[150:151], v[158:161], off offset:1472 sc1
	global_store_dwordx4 v[150:151], v[154:157], off offset:1792 sc1
	global_store_dwordx4 v[150:151], v[158:161], off offset:1856 sc1
	global_store_dwordx4 v[150:151], v[154:157], off offset:2176 sc1
	global_store_dwordx4 v[150:151], v[158:161], off offset:2240 sc1
	global_store_dwordx4 v[150:151], v[154:157], off offset:2560 sc1
	global_store_dwordx4 v[150:151], v[158:161], off offset:2624 sc1
	global_store_dwordx4 v[150:151], v[154:157], off offset:2944 sc1
	global_store_dwordx4 v[150:151], v[158:161], off offset:3008 sc1

.LBB0_488:
	s_andn2_b64 vcc, exec, s[18:19]
	s_cbranch_vccnz .LBB0_490
	s_waitcnt lgkmcnt(0)
	v_ashrrev_i32_e32 v153, 31, v152
	v_readlane_b32 s16, v235, 53
	v_lshlrev_b64 v[150:151], 9, v[152:153]
	v_readlane_b32 s17, v235, 54
	s_and_b64 s[14:15], s[14:15], exec
	v_readlane_b32 s14, v235, 50
	v_lshl_add_u64 v[150:151], s[16:17], 0, v[150:151]
	v_lshl_add_u64 v[150:151], v[150:151], 0, v[2:3]
	flat_load_dwordx4 v[154:157], v[150:151]
	global_load_dwordx4 v[166:169], v[150:151], off offset:48
	global_load_dwordx4 v[182:185], v[150:151], off offset:32
	global_load_dwordx4 v[186:189], v[150:151], off offset:16
	v_readlane_b32 s15, v235, 52
	s_cselect_b32 s15, s14, s15
	v_readlane_b32 s14, v235, 49
	v_readlane_b32 s16, v235, 51
	s_cselect_b32 s14, s14, s16
	v_lshlrev_b32_e32 v2, 1, v180
	s_waitcnt vmcnt(0) lgkmcnt(0)
	v_mov_b32_e32 v151, v156
	v_mov_b32_e32 v156, v155
	v_mov_b32_e32 v150, v154
	v_pk_mul_f32 v[154:155], v[10:11], v[156:157]
	v_pk_mul_f32 v[156:157], v[42:43], v[156:157]
	v_pk_fma_f32 v[160:161], v[42:43], v[150:151], v[154:155] neg_lo:[0,0,1] neg_hi:[0,0,1]
	v_mov_b32_e32 v155, v188
	v_mov_b32_e32 v188, v187
	v_mov_b32_e32 v154, v186
	v_pk_mul_f32 v[158:159], v[12:13], v[188:189]
	v_pk_fma_f32 v[150:151], v[10:11], v[150:151], v[156:157]
	v_pk_fma_f32 v[162:163], v[44:45], v[154:155], v[158:159] neg_lo:[0,0,1] neg_hi:[0,0,1]
	v_mov_b32_e32 v159, v184
	v_mov_b32_e32 v184, v183
	v_pk_mul_f32 v[156:157], v[44:45], v[188:189]
	v_mov_b32_e32 v158, v182
	v_pk_mul_f32 v[164:165], v[6:7], v[184:185]
	v_mov_b32_e32 v183, v168
	v_mov_b32_e32 v168, v167
	v_pk_fma_f32 v[156:157], v[12:13], v[154:155], v[156:157]
	v_pk_mul_f32 v[154:155], v[38:39], v[184:185]
	v_pk_fma_f32 v[164:165], v[38:39], v[158:159], v[164:165] neg_lo:[0,0,1] neg_hi:[0,0,1]
	v_mov_b32_e32 v182, v166
	v_pk_mul_f32 v[166:167], v[8:9], v[168:169]
	v_pk_fma_f32 v[154:155], v[6:7], v[158:159], v[154:155]
	v_pk_mul_f32 v[158:159], v[40:41], v[168:169]
	v_lshlrev_b64 v[168:169], 11, v[152:153]
	v_lshl_add_u64 v[168:169], s[14:15], 0, v[168:169]
	v_lshl_add_u64 v[148:149], v[148:149], 1, v[168:169]
	v_mov_b32_e32 v168, v146
	v_mov_b32_e32 v169, v146
	v_pk_fma_f32 v[166:167], v[40:41], v[182:183], v[166:167] neg_lo:[0,0,1] neg_hi:[0,0,1]
	v_pk_fma_f32 v[158:159], v[8:9], v[182:183], v[158:159]
	v_lshl_add_u64 v[148:149], v[148:149], 0, v[2:3]
	v_pk_mul_f32 v[162:163], v[168:169], v[162:163]
	v_pk_mul_f32 v[160:161], v[146:147], v[160:161]
	v_pk_mul_f32 v[156:157], v[168:169], v[156:157]
	v_pk_mul_f32 v[166:167], v[168:169], v[166:167]
	v_pk_mul_f32 v[164:165], v[146:147], v[164:165]
	v_cvt_pk_bf16_f32 v160, v160, v161
	v_cvt_pk_bf16_f32 v161, v162, v163
	v_pk_mul_f32 v[150:151], v[146:147], v[150:151]
	v_cvt_pk_bf16_f32 v162, v164, v165
	v_cvt_pk_bf16_f32 v163, v166, v167
	global_store_dwordx4 v[148:149], v[160:163], off sc1
	v_pk_mul_f32 v[158:159], v[168:169], v[158:159]
	v_pk_mul_f32 v[146:147], v[146:147], v[154:155]
	v_cvt_pk_bf16_f32 v154, v150, v151
	v_cvt_pk_bf16_f32 v155, v156, v157
	s_nop 0
	v_cvt_pk_bf16_f32 v156, v146, v147
	v_cvt_pk_bf16_f32 v157, v158, v159
	global_store_dwordx4 v[148:149], v[154:157], off offset:128 sc1

.LBB0_491:
	s_andn2_b64 vcc, exec, s[18:19]
	s_cbranch_vccnz .LBB0_495
	s_waitcnt lgkmcnt(0)
	v_ashrrev_i32_e32 v153, 31, v152
	v_readlane_b32 s14, v235, 47
	v_lshlrev_b64 v[150:151], 10, v[152:153]
	v_readlane_b32 s15, v235, 48
	v_cvt_pk_bf16_f32 v146, v42, v43
	v_mul_f32_e32 v2, v43, v43
	v_mul_f32_e32 v145, v45, v45
	v_lshl_add_u64 v[150:151], s[14:15], 0, v[150:151]
	v_lshl_add_u64 v[150:151], s[66:67], 1, v[150:151]
	v_lshl_add_u64 v[150:151], v[4:5], 1, v[150:151]
	v_cvt_pk_bf16_f32 v147, v44, v45
	v_cvt_pk_bf16_f32 v148, v38, v39
	v_cvt_pk_bf16_f32 v149, v40, v41
	global_store_dwordx4 v[150:151], v[146:149], off sc1
	v_fmac_f32_e32 v2, v42, v42
	v_fmac_f32_e32 v145, v44, v44
	v_cvt_pk_bf16_f32 v146, v10, v11
	v_cvt_pk_bf16_f32 v147, v12, v13
	v_cvt_pk_bf16_f32 v148, v6, v7
	v_cvt_pk_bf16_f32 v149, v8, v9
	global_store_dwordx4 v[150:151], v[146:149], off offset:256 sc1
	v_add_f32_e32 v2, v2, v145
	v_mul_f32_e32 v145, v39, v39
	v_mul_f32_e32 v146, v41, v41
	v_fmac_f32_e32 v145, v38, v38
	v_fmac_f32_e32 v146, v40, v40
	v_add_f32_e32 v145, v145, v146
	v_add_f32_e32 v2, v145, v2
	v_mul_f32_e32 v145, v11, v11
	v_mul_f32_e32 v146, v13, v13
	v_fmac_f32_e32 v145, v10, v10
	v_fmac_f32_e32 v146, v12, v12
	v_add_f32_e32 v145, v145, v146
	v_mul_f32_e32 v146, v7, v7
	v_mul_f32_e32 v147, v9, v9
	v_fmac_f32_e32 v146, v6, v6
	v_fmac_f32_e32 v147, v8, v8
	v_add_f32_e32 v146, v146, v147
	v_add_f32_e32 v145, v146, v145
	v_and_b32_e32 v146, 64, v178
	v_add_f32_e32 v2, v145, v2
	v_xor_b32_e32 v145, 16, v178
	v_add_u32_e32 v146, 64, v146
	v_cmp_lt_i32_e32 vcc, v145, v146
	s_nop 1
	v_cndmask_b32_e32 v145, v178, v145, vcc
	v_lshlrev_b32_e32 v145, 2, v145
	ds_bpermute_b32 v145, v145, v2
	s_waitcnt lgkmcnt(0)
	v_add_f32_e32 v2, v2, v145
	v_xor_b32_e32 v145, 32, v178
	v_cmp_lt_i32_e32 vcc, v145, v146
	s_nop 1
	v_cndmask_b32_e32 v145, v178, v145, vcc
	v_lshlrev_b32_e32 v145, 2, v145
	ds_bpermute_b32 v145, v145, v2
	s_and_saveexec_b64 s[14:15], s[12:13]
	s_cbranch_execz .LBB0_494
	s_waitcnt lgkmcnt(0)
	v_add_f32_e32 v2, v2, v145
	v_ashrrev_i32_e32 v145, 31, v144
	v_lshl_add_u64 v[144:145], v[144:145], 2, s[36:37]
	s_waitcnt vmcnt(0)
	flat_atomic_add_f32 v[144:145], v2 offset:704

.LBB0_496:
	s_andn2_b64 vcc, exec, s[18:19]
	s_cbranch_vccnz .LBB0_498
	s_waitcnt lgkmcnt(0)
	v_ashrrev_i32_e32 v153, 31, v152
	v_lshlrev_b64 v[144:145], 8, v[152:153]
	v_lshl_add_u64 v[144:145], s[88:89], 0, v[144:145]
	v_lshl_add_u64 v[150:151], v[144:145], 0, v[142:143]
	flat_load_dwordx4 v[142:145], v[150:151]
	global_load_dwordx4 v[146:149], v[150:151], off offset:16
	global_load_dwordx4 v[154:157], v[150:151], off offset:32
	global_load_dwordx4 v[158:161], v[150:151], off offset:48
	v_mov_b64_e32 v[150:151], s[78:79]
	v_mad_i64_i32 v[150:151], s[12:13], v152, s83, v[150:151]
	v_lshlrev_b32_e32 v2, 1, v179
	v_lshl_add_u64 v[140:141], v[140:141], 1, v[150:151]
	v_lshl_add_u64 v[150:151], v[140:141], 0, v[2:3]
	s_waitcnt vmcnt(0) lgkmcnt(0)
	v_mov_b32_e32 v141, v144
	v_mov_b32_e32 v144, v143
	v_mov_b32_e32 v143, v148
	v_mov_b32_e32 v148, v147
	v_mov_b32_e32 v147, v156
	v_mov_b32_e32 v156, v155
	v_mov_b32_e32 v155, v160
	v_mov_b32_e32 v160, v159
	v_mov_b32_e32 v140, v142
	v_mov_b32_e32 v142, v146
	v_mov_b32_e32 v146, v154
	v_mov_b32_e32 v154, v158
	v_pk_mul_f32 v[158:159], v[10:11], v[144:145]
	v_pk_mul_f32 v[162:163], v[12:13], v[148:149]
	v_pk_mul_f32 v[164:165], v[6:7], v[156:157]
	v_pk_mul_f32 v[166:167], v[8:9], v[160:161]
	v_pk_mul_f32 v[144:145], v[42:43], v[144:145]
	v_pk_mul_f32 v[148:149], v[44:45], v[148:149]
	v_pk_mul_f32 v[156:157], v[38:39], v[156:157]
	v_pk_mul_f32 v[160:161], v[40:41], v[160:161]
	v_pk_fma_f32 v[158:159], v[42:43], v[140:141], v[158:159] neg_lo:[0,0,1] neg_hi:[0,0,1]
	v_pk_fma_f32 v[162:163], v[44:45], v[142:143], v[162:163] neg_lo:[0,0,1] neg_hi:[0,0,1]
	v_pk_fma_f32 v[164:165], v[38:39], v[146:147], v[164:165] neg_lo:[0,0,1] neg_hi:[0,0,1]
	v_pk_fma_f32 v[166:167], v[40:41], v[154:155], v[166:167] neg_lo:[0,0,1] neg_hi:[0,0,1]
	v_pk_fma_f32 v[140:141], v[10:11], v[140:141], v[144:145]
	v_pk_fma_f32 v[142:143], v[12:13], v[142:143], v[148:149]
	v_pk_fma_f32 v[144:145], v[6:7], v[146:147], v[156:157]
	v_pk_fma_f32 v[146:147], v[8:9], v[154:155], v[160:161]
	v_pk_mul_f32 v[148:149], v[162:163], s[96:97] op_sel_hi:[1,0]
	v_pk_mul_f32 v[154:155], v[158:159], s[96:97] op_sel_hi:[1,0]
	v_pk_mul_f32 v[156:157], v[166:167], s[96:97] op_sel_hi:[1,0]
	v_pk_mul_f32 v[158:159], v[164:165], s[96:97] op_sel_hi:[1,0]
	v_pk_mul_f32 v[160:161], v[142:143], s[96:97] op_sel_hi:[1,0]
	v_pk_mul_f32 v[162:163], v[140:141], s[96:97] op_sel_hi:[1,0]
	v_cvt_pk_bf16_f32 v140, v154, v155
	v_cvt_pk_bf16_f32 v141, v148, v149
	v_cvt_pk_bf16_f32 v142, v158, v159
	v_cvt_pk_bf16_f32 v143, v156, v157
	v_pk_mul_f32 v[146:147], v[146:147], s[96:97] op_sel_hi:[1,0]
	v_pk_mul_f32 v[144:145], v[144:145], s[96:97] op_sel_hi:[1,0]
	global_store_dwordx4 v[150:151], v[140:143], off offset:256 sc1
	s_nop 1
	v_cvt_pk_bf16_f32 v140, v162, v163
	v_cvt_pk_bf16_f32 v141, v160, v161
	v_cvt_pk_bf16_f32 v142, v144, v145
	v_cvt_pk_bf16_f32 v143, v146, v147
	global_store_dwordx4 v[150:151], v[140:143], off offset:320 sc1

.LBB0_500:
	s_nop 0
	v_pk_mul_f32 v[156:157], v[124:125], s[96:97] op_sel_hi:[1,0]
	v_pk_mul_f32 v[154:155], v[122:123], s[96:97] op_sel_hi:[1,0]
	v_pk_mul_f32 v[158:159], v[120:121], s[96:97] op_sel_hi:[1,0]
	v_pk_mul_f32 v[160:161], v[118:119], s[96:97] op_sel_hi:[1,0]
	v_cvt_pk_bf16_f32 v154, v154, v155
	v_cvt_pk_bf16_f32 v155, v156, v157
	s_nop 0
	v_cvt_pk_bf16_f32 v156, v160, v161
	v_cvt_pk_bf16_f32 v157, v158, v159
	v_mov_b64_e32 v[158:159], s[78:79]
	s_waitcnt lgkmcnt(0)
	v_mad_i64_i32 v[152:153], s[50:51], v152, s83, v[158:159]
	v_lshl_add_u64 v[152:153], s[70:71], 1, v[152:153]
	v_lshl_add_u64 v[158:159], v[4:5], 1, v[152:153]
	global_store_dwordx4 v[158:159], v[154:157], off sc1
	v_pk_mul_f32 v[152:153], v[90:91], s[96:97] op_sel_hi:[1,0]
	v_pk_mul_f32 v[160:161], v[86:87], s[96:97] op_sel_hi:[1,0]
	v_pk_mul_f32 v[154:155], v[92:93], s[96:97] op_sel_hi:[1,0]
	v_pk_mul_f32 v[156:157], v[88:89], s[96:97] op_sel_hi:[1,0]
	v_cvt_pk_bf16_f32 v152, v152, v153
	v_cvt_pk_bf16_f32 v153, v154, v155
	v_cvt_pk_bf16_f32 v154, v160, v161
	s_nop 0
	v_cvt_pk_bf16_f32 v155, v156, v157
	global_store_dwordx4 v[158:159], v[152:155], off offset:384 sc1
	s_nop 1
	v_add_u32_e32 v152, 32, v144
	s_and_b64 vcc, exec, s[20:21]
	s_mov_b64 s[50:51], -1
	s_cbranch_vccz .LBB0_392

.LBB0_502:
	s_nop 0
	v_pk_mul_f32 v[156:157], v[116:117], s[96:97] op_sel_hi:[1,0]
	v_pk_mul_f32 v[154:155], v[114:115], s[96:97] op_sel_hi:[1,0]
	v_pk_mul_f32 v[158:159], v[112:113], s[96:97] op_sel_hi:[1,0]
	v_pk_mul_f32 v[160:161], v[110:111], s[96:97] op_sel_hi:[1,0]
	v_cvt_pk_bf16_f32 v154, v154, v155
	v_cvt_pk_bf16_f32 v155, v156, v157
	s_nop 0
	v_cvt_pk_bf16_f32 v156, v160, v161
	v_cvt_pk_bf16_f32 v157, v158, v159
	v_mov_b64_e32 v[158:159], s[78:79]
	s_waitcnt lgkmcnt(0)
	v_mad_i64_i32 v[152:153], s[50:51], v152, s83, v[158:159]
	v_lshl_add_u64 v[152:153], s[70:71], 1, v[152:153]
	v_lshl_add_u64 v[158:159], v[4:5], 1, v[152:153]
	global_store_dwordx4 v[158:159], v[154:157], off sc1
	v_pk_mul_f32 v[152:153], v[82:83], s[96:97] op_sel_hi:[1,0]
	v_pk_mul_f32 v[160:161], v[78:79], s[96:97] op_sel_hi:[1,0]
	v_pk_mul_f32 v[154:155], v[84:85], s[96:97] op_sel_hi:[1,0]
	v_pk_mul_f32 v[156:157], v[80:81], s[96:97] op_sel_hi:[1,0]
	v_cvt_pk_bf16_f32 v152, v152, v153
	v_cvt_pk_bf16_f32 v153, v154, v155
	v_cvt_pk_bf16_f32 v154, v160, v161
	s_nop 0
	v_cvt_pk_bf16_f32 v155, v156, v157
	global_store_dwordx4 v[158:159], v[152:155], off offset:384 sc1
	s_nop 1
	v_add_u32_e32 v152, 48, v144
	s_and_b64 vcc, exec, s[20:21]
	s_mov_b64 s[50:51], -1
	s_cbranch_vccz .LBB0_410

.LBB0_504:
	s_nop 0
	v_pk_mul_f32 v[156:157], v[108:109], s[96:97] op_sel_hi:[1,0]
	v_pk_mul_f32 v[154:155], v[106:107], s[96:97] op_sel_hi:[1,0]
	v_pk_mul_f32 v[158:159], v[104:105], s[96:97] op_sel_hi:[1,0]
	v_pk_mul_f32 v[160:161], v[102:103], s[96:97] op_sel_hi:[1,0]
	v_cvt_pk_bf16_f32 v154, v154, v155
	v_cvt_pk_bf16_f32 v155, v156, v157
	s_nop 0
	v_cvt_pk_bf16_f32 v156, v160, v161
	v_cvt_pk_bf16_f32 v157, v158, v159
	v_mov_b64_e32 v[158:159], s[78:79]
	s_waitcnt lgkmcnt(0)
	v_mad_i64_i32 v[152:153], s[50:51], v152, s83, v[158:159]
	v_lshl_add_u64 v[152:153], s[70:71], 1, v[152:153]
	v_lshl_add_u64 v[158:159], v[4:5], 1, v[152:153]
	global_store_dwordx4 v[158:159], v[154:157], off sc1
	v_pk_mul_f32 v[152:153], v[74:75], s[96:97] op_sel_hi:[1,0]
	v_pk_mul_f32 v[160:161], v[70:71], s[96:97] op_sel_hi:[1,0]
	v_pk_mul_f32 v[154:155], v[76:77], s[96:97] op_sel_hi:[1,0]
	v_pk_mul_f32 v[156:157], v[72:73], s[96:97] op_sel_hi:[1,0]
	v_cvt_pk_bf16_f32 v152, v152, v153
	v_cvt_pk_bf16_f32 v153, v154, v155
	v_cvt_pk_bf16_f32 v154, v160, v161
	s_nop 0
	v_cvt_pk_bf16_f32 v155, v156, v157
	global_store_dwordx4 v[158:159], v[152:155], off offset:384 sc1
	s_nop 1
	v_add_u32_e32 v152, 0x80, v144
	s_and_b64 vcc, exec, s[20:21]
	s_mov_b64 s[50:51], -1
	s_cbranch_vccz .LBB0_428

.LBB0_506:
	s_nop 0
	v_pk_mul_f32 v[156:157], v[68:69], s[96:97] op_sel_hi:[1,0]
	v_pk_mul_f32 v[154:155], v[66:67], s[96:97] op_sel_hi:[1,0]
	v_pk_mul_f32 v[158:159], v[64:65], s[96:97] op_sel_hi:[1,0]
	v_pk_mul_f32 v[160:161], v[62:63], s[96:97] op_sel_hi:[1,0]
	v_cvt_pk_bf16_f32 v154, v154, v155
	v_cvt_pk_bf16_f32 v155, v156, v157
	s_nop 0
	v_cvt_pk_bf16_f32 v156, v160, v161
	v_cvt_pk_bf16_f32 v157, v158, v159
	v_mov_b64_e32 v[158:159], s[78:79]
	s_waitcnt lgkmcnt(0)
	v_mad_i64_i32 v[152:153], s[50:51], v152, s83, v[158:159]
	v_lshl_add_u64 v[152:153], s[70:71], 1, v[152:153]
	v_lshl_add_u64 v[158:159], v[4:5], 1, v[152:153]
	global_store_dwordx4 v[158:159], v[154:157], off sc1
	v_pk_mul_f32 v[152:153], v[34:35], s[96:97] op_sel_hi:[1,0]
	v_pk_mul_f32 v[160:161], v[30:31], s[96:97] op_sel_hi:[1,0]
	v_pk_mul_f32 v[154:155], v[36:37], s[96:97] op_sel_hi:[1,0]
	v_pk_mul_f32 v[156:157], v[32:33], s[96:97] op_sel_hi:[1,0]
	v_cvt_pk_bf16_f32 v152, v152, v153
	v_cvt_pk_bf16_f32 v153, v154, v155
	v_cvt_pk_bf16_f32 v154, v160, v161
	s_nop 0
	v_cvt_pk_bf16_f32 v155, v156, v157
	global_store_dwordx4 v[158:159], v[152:155], off offset:384 sc1
	s_nop 1
	v_add_u32_e32 v152, 0x90, v144
	s_and_b64 vcc, exec, s[20:21]
	s_mov_b64 s[50:51], -1
	s_cbranch_vccz .LBB0_446

.LBB0_508:
	s_nop 0
	v_pk_mul_f32 v[156:157], v[60:61], s[96:97] op_sel_hi:[1,0]
	v_pk_mul_f32 v[154:155], v[58:59], s[96:97] op_sel_hi:[1,0]
	v_pk_mul_f32 v[158:159], v[56:57], s[96:97] op_sel_hi:[1,0]
	v_pk_mul_f32 v[160:161], v[54:55], s[96:97] op_sel_hi:[1,0]
	v_cvt_pk_bf16_f32 v154, v154, v155
	v_cvt_pk_bf16_f32 v155, v156, v157
	s_nop 0
	v_cvt_pk_bf16_f32 v156, v160, v161
	v_cvt_pk_bf16_f32 v157, v158, v159
	v_mov_b64_e32 v[158:159], s[78:79]
	s_waitcnt lgkmcnt(0)
	v_mad_i64_i32 v[152:153], s[50:51], v152, s83, v[158:159]
	v_lshl_add_u64 v[152:153], s[70:71], 1, v[152:153]
	v_lshl_add_u64 v[158:159], v[4:5], 1, v[152:153]
	global_store_dwordx4 v[158:159], v[154:157], off sc1
	v_pk_mul_f32 v[152:153], v[26:27], s[96:97] op_sel_hi:[1,0]
	v_pk_mul_f32 v[160:161], v[22:23], s[96:97] op_sel_hi:[1,0]
	v_pk_mul_f32 v[154:155], v[28:29], s[96:97] op_sel_hi:[1,0]
	v_pk_mul_f32 v[156:157], v[24:25], s[96:97] op_sel_hi:[1,0]
	v_cvt_pk_bf16_f32 v152, v152, v153
	v_cvt_pk_bf16_f32 v153, v154, v155
	v_cvt_pk_bf16_f32 v154, v160, v161
	s_nop 0
	v_cvt_pk_bf16_f32 v155, v156, v157
	global_store_dwordx4 v[158:159], v[152:155], off offset:384 sc1
	s_nop 1
	v_add_u32_e32 v152, 0xa0, v144
	s_and_b64 vcc, exec, s[20:21]
	s_mov_b64 s[50:51], -1
	s_cbranch_vccz .LBB0_464

.LBB0_510:
	s_nop 0
	v_pk_mul_f32 v[156:157], v[52:53], s[96:97] op_sel_hi:[1,0]
	v_pk_mul_f32 v[154:155], v[50:51], s[96:97] op_sel_hi:[1,0]
	v_pk_mul_f32 v[158:159], v[48:49], s[96:97] op_sel_hi:[1,0]
	v_pk_mul_f32 v[160:161], v[46:47], s[96:97] op_sel_hi:[1,0]
	v_cvt_pk_bf16_f32 v154, v154, v155
	v_cvt_pk_bf16_f32 v155, v156, v157
	s_nop 0
	v_cvt_pk_bf16_f32 v156, v160, v161
	v_cvt_pk_bf16_f32 v157, v158, v159
	v_mov_b64_e32 v[158:159], s[78:79]
	s_waitcnt lgkmcnt(0)
	v_mad_i64_i32 v[152:153], s[50:51], v152, s83, v[158:159]
	v_lshl_add_u64 v[152:153], s[70:71], 1, v[152:153]
	v_lshl_add_u64 v[158:159], v[4:5], 1, v[152:153]
	global_store_dwordx4 v[158:159], v[154:157], off sc1
	v_pk_mul_f32 v[152:153], v[18:19], s[96:97] op_sel_hi:[1,0]
	v_pk_mul_f32 v[160:161], v[14:15], s[96:97] op_sel_hi:[1,0]
	v_pk_mul_f32 v[154:155], v[20:21], s[96:97] op_sel_hi:[1,0]
	v_pk_mul_f32 v[156:157], v[16:17], s[96:97] op_sel_hi:[1,0]
	v_cvt_pk_bf16_f32 v152, v152, v153
	v_cvt_pk_bf16_f32 v153, v154, v155
	v_cvt_pk_bf16_f32 v154, v160, v161
	s_nop 0
	v_cvt_pk_bf16_f32 v155, v156, v157
	global_store_dwordx4 v[158:159], v[152:155], off offset:384 sc1
	s_nop 1
	v_add_u32_e32 v152, 0xb0, v144
	s_and_b64 vcc, exec, s[20:21]
	s_mov_b64 s[20:21], -1
	s_cbranch_vccz .LBB0_482

.LBB0_512:
	v_pk_mul_f32 v[142:143], v[44:45], s[96:97] op_sel_hi:[1,0]
	v_pk_mul_f32 v[140:141], v[42:43], s[96:97] op_sel_hi:[1,0]
	s_waitcnt lgkmcnt(0)
	v_pk_mul_f32 v[144:145], v[40:41], s[96:97] op_sel_hi:[1,0]
	v_pk_mul_f32 v[146:147], v[38:39], s[96:97] op_sel_hi:[1,0]
	v_cvt_pk_bf16_f32 v140, v140, v141
	v_cvt_pk_bf16_f32 v141, v142, v143
	s_nop 0
	v_cvt_pk_bf16_f32 v142, v146, v147
	v_cvt_pk_bf16_f32 v143, v144, v145
	v_mov_b64_e32 v[144:145], s[78:79]
	v_mad_i64_i32 v[144:145], s[12:13], v152, s83, v[144:145]
	v_lshl_add_u64 v[144:145], s[70:71], 1, v[144:145]
	v_lshl_add_u64 v[4:5], v[4:5], 1, v[144:145]
	global_store_dwordx4 v[4:5], v[140:143], off sc1
	v_pk_mul_f32 v[144:145], v[8:9], s[96:97] op_sel_hi:[1,0]
	v_pk_mul_f32 v[146:147], v[6:7], s[96:97] op_sel_hi:[1,0]
	v_pk_mul_f32 v[142:143], v[12:13], s[96:97] op_sel_hi:[1,0]
	v_pk_mul_f32 v[140:141], v[10:11], s[96:97] op_sel_hi:[1,0]
	s_nop 0
	v_cvt_pk_bf16_f32 v140, v140, v141
	v_cvt_pk_bf16_f32 v141, v142, v143
	v_cvt_pk_bf16_f32 v142, v146, v147
	v_cvt_pk_bf16_f32 v143, v144, v145
	global_store_dwordx4 v[4:5], v[140:143], off offset:384 sc1

.LBB0_629:
	s_cmp_lg_u32 s94, 0
	s_cbranch_scc0 .LBB0_635
	s_lshl_b32 s0, s92, 8
	v_mov_b32_e32 v166, v135
	v_mov_b32_e32 v130, v168
	s_or_b32 s0, s0, s62
	s_nop 0
	v_lshl_add_u32 v164, v130, 3, s0
	v_ashrrev_i32_e32 v165, 31, v164
	v_lshl_add_u64 v[130:131], v[164:165], 2, s[8:9]
	global_load_dwordx4 v[150:153], v[130:131], off offset:16
	global_load_dwordx4 v[156:159], v[130:131], off
	global_load_dwordx4 v[160:163], v[130:131], off offset:528
	global_load_dwordx4 v[174:177], v[130:131], off offset:512
	s_lshl_b32 s0, s93, 8
	s_add_i32 s0, s0, s61
	v_lshlrev_b64 v[164:165], 1, v[164:165]
	s_waitcnt vmcnt(0)
	v_fmamk_f32 v130, v156, 0x3b000000, v173
	v_fmamk_f32 v131, v157, 0x3b000000, v173
	v_rsq_f32_e32 v156, v130
	v_fmamk_f32 v130, v150, 0x3b000000, v173
	v_rsq_f32_e32 v157, v131
	v_fmamk_f32 v131, v151, 0x3b000000, v173
	v_rsq_f32_e32 v154, v130
	v_fmamk_f32 v130, v174, 0x3b000000, v173
	v_rsq_f32_e32 v155, v131
	v_fmamk_f32 v131, v175, 0x3b000000, v173
	v_fmamk_f32 v150, v158, 0x3b000000, v173
	v_fmamk_f32 v151, v159, 0x3b000000, v173
	v_rsq_f32_e32 v132, v130
	v_fmamk_f32 v130, v160, 0x3b000000, v173
	v_rsq_f32_e32 v133, v131
	v_fmamk_f32 v131, v161, 0x3b000000, v173
	v_rsq_f32_e32 v160, v150
	v_rsq_f32_e32 v161, v151
	v_fmamk_f32 v150, v152, 0x3b000000, v173
	v_rsq_f32_e32 v158, v150
	v_fmamk_f32 v150, v176, 0x3b000000, v173
	v_fmamk_f32 v151, v153, 0x3b000000, v173
	v_rsq_f32_e32 v152, v150
	v_fmamk_f32 v150, v162, 0x3b000000, v173
	v_rsq_f32_e32 v159, v151
	v_fmamk_f32 v151, v177, 0x3b000000, v173
	v_add_u32_e32 v162, s0, v166
	v_rsq_f32_e32 v153, v151
	v_fmamk_f32 v151, v163, 0x3b000000, v173
	v_pk_mul_f32 v[166:167], v[124:125], v[160:161]
	v_pk_mul_f32 v[174:175], v[122:123], v[156:157]
	v_ashrrev_i32_e32 v163, 31, v162
	v_rsq_f32_e32 v130, v130
	v_rsq_f32_e32 v131, v131
	v_rsq_f32_e32 v150, v150
	v_rsq_f32_e32 v151, v151
	v_cvt_pk_bf16_f32 v174, v174, v175
	v_cvt_pk_bf16_f32 v175, v166, v167
	v_lshlrev_b64 v[166:167], 15, v[162:163]
	v_pk_mul_f32 v[176:177], v[126:127], v[154:155]
	v_lshl_add_u64 v[166:167], s[22:23], 0, v[166:167]
	v_pk_mul_f32 v[178:179], v[128:129], v[158:159]
	v_cvt_pk_bf16_f32 v176, v176, v177
	v_lshl_add_u64 v[166:167], v[166:167], 0, v[164:165]
	v_cvt_pk_bf16_f32 v177, v178, v179
	global_store_dwordx4 v[166:167], v[174:177], off sc1
	v_pk_mul_f32 v[178:179], v[116:117], v[150:151]
	v_pk_mul_f32 v[180:181], v[114:115], v[130:131]
	v_pk_mul_f32 v[176:177], v[120:121], v[152:153]
	v_pk_mul_f32 v[174:175], v[118:119], v[132:133]
	s_mov_b64 s[0:1], 0x100
	v_cvt_pk_bf16_f32 v174, v174, v175
	v_cvt_pk_bf16_f32 v175, v176, v177
	v_cvt_pk_bf16_f32 v176, v180, v181
	v_cvt_pk_bf16_f32 v177, v178, v179
	global_store_dwordx4 v[166:167], v[174:177], off offset:256 sc1
	v_add_u32_e32 v166, 16, v162
	v_ashrrev_i32_e32 v167, 31, v166
	v_lshlrev_b64 v[166:167], 15, v[166:167]
	v_pk_mul_f32 v[176:177], v[112:113], v[160:161]
	v_pk_mul_f32 v[174:175], v[110:111], v[156:157]
	v_lshl_add_u64 v[166:167], s[22:23], 0, v[166:167]
	v_pk_mul_f32 v[178:179], v[108:109], v[158:159]
	v_pk_mul_f32 v[180:181], v[106:107], v[154:155]
	v_cvt_pk_bf16_f32 v174, v174, v175
	v_cvt_pk_bf16_f32 v175, v176, v177
	v_lshl_add_u64 v[166:167], v[166:167], 0, v[164:165]
	v_cvt_pk_bf16_f32 v176, v180, v181
	v_cvt_pk_bf16_f32 v177, v178, v179
	global_store_dwordx4 v[166:167], v[174:177], off sc1
	v_pk_mul_f32 v[178:179], v[100:101], v[150:151]
	v_pk_mul_f32 v[180:181], v[98:99], v[130:131]
	v_pk_mul_f32 v[176:177], v[104:105], v[152:153]
	v_pk_mul_f32 v[174:175], v[102:103], v[132:133]
	s_nop 0
	v_cvt_pk_bf16_f32 v174, v174, v175
	v_cvt_pk_bf16_f32 v175, v176, v177
	v_cvt_pk_bf16_f32 v176, v180, v181
	v_cvt_pk_bf16_f32 v177, v178, v179
	global_store_dwordx4 v[166:167], v[174:177], off offset:256 sc1
	v_add_u32_e32 v166, 32, v162
	v_ashrrev_i32_e32 v167, 31, v166
	v_lshlrev_b64 v[166:167], 15, v[166:167]
	v_pk_mul_f32 v[176:177], v[96:97], v[160:161]
	v_pk_mul_f32 v[174:175], v[94:95], v[156:157]
	v_lshl_add_u64 v[166:167], s[22:23], 0, v[166:167]
	v_pk_mul_f32 v[178:179], v[92:93], v[158:159]
	v_pk_mul_f32 v[180:181], v[90:91], v[154:155]
	v_cvt_pk_bf16_f32 v174, v174, v175
	v_cvt_pk_bf16_f32 v175, v176, v177
	v_lshl_add_u64 v[166:167], v[166:167], 0, v[164:165]
	v_cvt_pk_bf16_f32 v176, v180, v181
	v_cvt_pk_bf16_f32 v177, v178, v179
	global_store_dwordx4 v[166:167], v[174:177], off sc1
	v_pk_mul_f32 v[178:179], v[84:85], v[150:151]
	v_pk_mul_f32 v[180:181], v[82:83], v[130:131]
	v_pk_mul_f32 v[176:177], v[88:89], v[152:153]
	v_pk_mul_f32 v[174:175], v[86:87], v[132:133]
	s_nop 0
	v_cvt_pk_bf16_f32 v174, v174, v175
	v_cvt_pk_bf16_f32 v175, v176, v177
	v_cvt_pk_bf16_f32 v176, v180, v181
	v_cvt_pk_bf16_f32 v177, v178, v179
	global_store_dwordx4 v[166:167], v[174:177], off offset:256 sc1
	v_add_u32_e32 v166, 48, v162
	v_ashrrev_i32_e32 v167, 31, v166
	v_lshlrev_b64 v[166:167], 15, v[166:167]
	v_pk_mul_f32 v[176:177], v[80:81], v[160:161]
	v_pk_mul_f32 v[174:175], v[78:79], v[156:157]
	v_lshl_add_u64 v[166:167], s[22:23], 0, v[166:167]
	v_pk_mul_f32 v[178:179], v[76:77], v[158:159]
	v_pk_mul_f32 v[180:181], v[74:75], v[154:155]
	v_cvt_pk_bf16_f32 v174, v174, v175
	v_cvt_pk_bf16_f32 v175, v176, v177
	v_lshl_add_u64 v[166:167], v[166:167], 0, v[164:165]
	v_cvt_pk_bf16_f32 v176, v180, v181
	v_cvt_pk_bf16_f32 v177, v178, v179
	global_store_dwordx4 v[166:167], v[174:177], off sc1
	v_pk_mul_f32 v[178:179], v[68:69], v[150:151]
	v_pk_mul_f32 v[180:181], v[66:67], v[130:131]
	v_pk_mul_f32 v[176:177], v[72:73], v[152:153]
	v_pk_mul_f32 v[174:175], v[70:71], v[132:133]
	s_nop 0
	v_cvt_pk_bf16_f32 v174, v174, v175
	v_cvt_pk_bf16_f32 v175, v176, v177
	v_cvt_pk_bf16_f32 v176, v180, v181
	v_cvt_pk_bf16_f32 v177, v178, v179
	global_store_dwordx4 v[166:167], v[174:177], off offset:256 sc1
	v_add_u32_e32 v166, 0x80, v162
	v_ashrrev_i32_e32 v167, 31, v166
	v_lshlrev_b64 v[166:167], 15, v[166:167]
	v_pk_mul_f32 v[176:177], v[64:65], v[160:161]
	v_pk_mul_f32 v[174:175], v[62:63], v[156:157]
	v_lshl_add_u64 v[166:167], s[22:23], 0, v[166:167]
	v_pk_mul_f32 v[178:179], v[60:61], v[158:159]
	v_pk_mul_f32 v[180:181], v[58:59], v[154:155]
	v_cvt_pk_bf16_f32 v174, v174, v175
	v_cvt_pk_bf16_f32 v175, v176, v177
	v_lshl_add_u64 v[166:167], v[166:167], 0, v[164:165]
	v_cvt_pk_bf16_f32 v176, v180, v181
	v_cvt_pk_bf16_f32 v177, v178, v179
	global_store_dwordx4 v[166:167], v[174:177], off sc1
	v_pk_mul_f32 v[178:179], v[52:53], v[150:151]
	v_pk_mul_f32 v[180:181], v[50:51], v[130:131]
	v_pk_mul_f32 v[176:177], v[56:57], v[152:153]
	v_pk_mul_f32 v[174:175], v[54:55], v[132:133]
	s_nop 0
	v_cvt_pk_bf16_f32 v174, v174, v175
	v_cvt_pk_bf16_f32 v175, v176, v177
	v_cvt_pk_bf16_f32 v176, v180, v181
	v_cvt_pk_bf16_f32 v177, v178, v179
	global_store_dwordx4 v[166:167], v[174:177], off offset:256 sc1
	v_add_u32_e32 v166, 0x90, v162
	v_ashrrev_i32_e32 v167, 31, v166
	v_lshlrev_b64 v[166:167], 15, v[166:167]
	v_pk_mul_f32 v[176:177], v[48:49], v[160:161]
	v_pk_mul_f32 v[174:175], v[46:47], v[156:157]
	v_lshl_add_u64 v[166:167], s[22:23], 0, v[166:167]
	v_pk_mul_f32 v[178:179], v[44:45], v[158:159]
	v_pk_mul_f32 v[180:181], v[42:43], v[154:155]
	v_cvt_pk_bf16_f32 v174, v174, v175
	v_cvt_pk_bf16_f32 v175, v176, v177
	v_lshl_add_u64 v[166:167], v[166:167], 0, v[164:165]
	v_cvt_pk_bf16_f32 v176, v180, v181
	v_cvt_pk_bf16_f32 v177, v178, v179
	global_store_dwordx4 v[166:167], v[174:177], off sc1
	v_pk_mul_f32 v[178:179], v[36:37], v[150:151]
	v_pk_mul_f32 v[180:181], v[34:35], v[130:131]
	v_pk_mul_f32 v[176:177], v[40:41], v[152:153]
	v_pk_mul_f32 v[174:175], v[38:39], v[132:133]
	s_nop 0
	v_cvt_pk_bf16_f32 v174, v174, v175
	v_cvt_pk_bf16_f32 v175, v176, v177
	v_cvt_pk_bf16_f32 v176, v180, v181
	v_cvt_pk_bf16_f32 v177, v178, v179
	global_store_dwordx4 v[166:167], v[174:177], off offset:256 sc1
	v_add_u32_e32 v166, 0xa0, v162
	v_ashrrev_i32_e32 v167, 31, v166
	v_lshlrev_b64 v[166:167], 15, v[166:167]
	v_pk_mul_f32 v[176:177], v[32:33], v[160:161]
	v_pk_mul_f32 v[174:175], v[30:31], v[156:157]
	v_lshl_add_u64 v[166:167], s[22:23], 0, v[166:167]
	v_pk_mul_f32 v[178:179], v[28:29], v[158:159]
	v_pk_mul_f32 v[180:181], v[26:27], v[154:155]
	v_cvt_pk_bf16_f32 v174, v174, v175
	v_cvt_pk_bf16_f32 v175, v176, v177
	v_lshl_add_u64 v[166:167], v[166:167], 0, v[164:165]
	v_cvt_pk_bf16_f32 v176, v180, v181
	v_cvt_pk_bf16_f32 v177, v178, v179
	v_add_u32_e32 v162, 0xb0, v162
	global_store_dwordx4 v[166:167], v[174:177], off sc1
	v_pk_mul_f32 v[156:157], v[14:15], v[156:157]
	v_pk_mul_f32 v[158:159], v[12:13], v[158:159]
	v_pk_mul_f32 v[176:177], v[24:25], v[152:153]
	v_pk_mul_f32 v[174:175], v[22:23], v[132:133]
	v_ashrrev_i32_e32 v163, 31, v162
	v_pk_mul_f32 v[178:179], v[20:21], v[150:151]
	v_pk_mul_f32 v[180:181], v[18:19], v[130:131]
	v_cvt_pk_bf16_f32 v174, v174, v175
	v_cvt_pk_bf16_f32 v175, v176, v177
	v_pk_mul_f32 v[160:161], v[16:17], v[160:161]
	v_cvt_pk_bf16_f32 v176, v180, v181
	v_cvt_pk_bf16_f32 v177, v178, v179
	global_store_dwordx4 v[166:167], v[174:177], off offset:256 sc1
	v_pk_mul_f32 v[166:167], v[10:11], v[154:155]
	v_cvt_pk_bf16_f32 v154, v156, v157
	v_cvt_pk_bf16_f32 v155, v160, v161
	v_pk_mul_f32 v[132:133], v[6:7], v[132:133]
	v_cvt_pk_bf16_f32 v156, v166, v167
	v_cvt_pk_bf16_f32 v157, v158, v159
	v_lshlrev_b64 v[158:159], 15, v[162:163]
	v_lshl_add_u64 v[158:159], s[22:23], 0, v[158:159]
	v_lshl_add_u64 v[158:159], v[158:159], 0, v[164:165]
	v_pk_mul_f32 v[150:151], v[4:5], v[150:151]
	global_store_dwordx4 v[158:159], v[154:157], off sc1
	v_pk_mul_f32 v[152:153], v[8:9], v[152:153]
	s_nop 0
	v_pk_mul_f32 v[154:155], v[2:3], v[130:131]
	v_cvt_pk_bf16_f32 v130, v132, v133
	v_cvt_pk_bf16_f32 v131, v152, v153
	s_nop 0
	v_cvt_pk_bf16_f32 v132, v154, v155
	v_cvt_pk_bf16_f32 v133, v150, v151
	v_lshl_add_u64 v[150:151], v[158:159], 0, s[0:1]
	s_cbranch_execnz .LBB0_632
.LBB0_631:
	s_lshl_b32 s0, s93, 8
	v_mov_b32_e32 v130, v168
	v_mov_b32_e32 v131, v135
	s_add_i32 s0, s0, s61
	s_nop 0
	v_add_u32_e32 v132, s0, v131
	v_ashrrev_i32_e32 v133, 31, v132
	v_lshl_add_u32 v150, v130, 3, s62
	v_lshl_add_u64 v[130:131], v[132:133], 2, s[8:9]
	global_load_dword v133, v[130:131], off
	global_load_dword v200, v[130:131], off offset:64
	global_load_dword v201, v[130:131], off offset:128
	global_load_dword v202, v[130:131], off offset:192
	global_load_dword v203, v[130:131], off offset:512
	global_load_dword v204, v[130:131], off offset:576
	global_load_dword v205, v[130:131], off offset:640
	global_load_dword v206, v[130:131], off offset:704
	v_ashrrev_i32_e32 v151, 31, v150
	s_waitcnt vmcnt(0) lgkmcnt(0)
	v_fmamk_f32 v133, v133, 0x3b000000, v173
	v_rsq_f32_e32 v152, v133
	s_nop 0
	v_pk_mul_f32 v[122:123], v[122:123], v[152:153] op_sel_hi:[1,0]
	v_pk_mul_f32 v[124:125], v[124:125], v[152:153] op_sel_hi:[1,0]
	v_pk_mul_f32 v[154:155], v[128:129], v[152:153] op_sel_hi:[1,0]
	v_pk_mul_f32 v[128:129], v[126:127], v[152:153] op_sel_hi:[1,0]
	v_cvt_pk_bf16_f32 v126, v122, v123
	v_mov_b64_e32 v[122:123], s[20:21]
	v_cvt_pk_bf16_f32 v127, v124, v125
	v_mad_i64_i32 v[124:125], s[0:1], v132, s88, v[122:123]
	s_mul_i32 s0, s92, 0x180
	s_ashr_i32 s1, s0, 31
	s_lshl_b64 s[0:1], s[0:1], 1
	v_cvt_pk_bf16_f32 v128, v128, v129
	v_cvt_pk_bf16_f32 v129, v154, v155
	v_lshl_add_u64 v[154:155], v[124:125], 0, s[0:1]
	v_lshlrev_b64 v[124:125], 1, v[150:151]
	v_lshl_add_u64 v[150:151], v[154:155], 0, v[124:125]
	global_store_dwordx4 v[150:151], v[126:129], off sc1
	v_pk_mul_f32 v[120:121], v[120:121], v[152:153] op_sel_hi:[1,0]
	v_pk_mul_f32 v[118:119], v[118:119], v[152:153] op_sel_hi:[1,0]
	v_pk_mul_f32 v[126:127], v[116:117], v[152:153] op_sel_hi:[1,0]
	v_pk_mul_f32 v[116:117], v[114:115], v[152:153] op_sel_hi:[1,0]
	v_cvt_pk_bf16_f32 v114, v118, v119
	v_cvt_pk_bf16_f32 v115, v120, v121
	s_nop 0
	v_cvt_pk_bf16_f32 v116, v116, v117
	v_cvt_pk_bf16_f32 v117, v126, v127
	global_store_dwordx4 v[150:151], v[114:117], off offset:384 sc1
	s_nop 0
	s_nop 0
	v_add_u32_e32 v115, 16, v132
	v_mov_b32_e32 v114, v200
	v_fmamk_f32 v114, v114, 0x3b000000, v173
	v_rsq_f32_e32 v114, v114
	s_nop 0
	v_pk_mul_f32 v[110:111], v[110:111], v[114:115] op_sel_hi:[1,0]
	v_pk_mul_f32 v[116:117], v[108:109], v[114:115] op_sel_hi:[1,0]
	v_pk_mul_f32 v[108:109], v[106:107], v[114:115] op_sel_hi:[1,0]
	v_cvt_pk_bf16_f32 v106, v110, v111
	v_mad_i64_i32 v[110:111], s[44:45], v115, s88, v[122:123]
	v_lshl_add_u64 v[110:111], v[110:111], 0, s[0:1]
	v_pk_mul_f32 v[112:113], v[112:113], v[114:115] op_sel_hi:[1,0]
	v_lshl_add_u64 v[110:111], v[110:111], 0, v[124:125]
	v_cvt_pk_bf16_f32 v107, v112, v113
	v_cvt_pk_bf16_f32 v108, v108, v109
	v_cvt_pk_bf16_f32 v109, v116, v117
	global_store_dwordx4 v[110:111], v[106:109], off sc1
	v_pk_mul_f32 v[104:105], v[104:105], v[114:115] op_sel_hi:[1,0]
	v_pk_mul_f32 v[102:103], v[102:103], v[114:115] op_sel_hi:[1,0]
	v_pk_mul_f32 v[106:107], v[100:101], v[114:115] op_sel_hi:[1,0]
	v_pk_mul_f32 v[100:101], v[98:99], v[114:115] op_sel_hi:[1,0]
	v_cvt_pk_bf16_f32 v98, v102, v103
	v_cvt_pk_bf16_f32 v99, v104, v105
	s_nop 0
	v_cvt_pk_bf16_f32 v100, v100, v101
	v_cvt_pk_bf16_f32 v101, v106, v107
	global_store_dwordx4 v[110:111], v[98:101], off offset:384 sc1
	s_nop 0
	s_nop 0
	v_add_u32_e32 v99, 32, v132
	v_mov_b32_e32 v98, v201
	v_fmamk_f32 v98, v98, 0x3b000000, v173
	v_rsq_f32_e32 v98, v98
	s_nop 0
	v_pk_mul_f32 v[94:95], v[94:95], v[98:99] op_sel_hi:[1,0]
	v_pk_mul_f32 v[100:101], v[92:93], v[98:99] op_sel_hi:[1,0]
	v_pk_mul_f32 v[92:93], v[90:91], v[98:99] op_sel_hi:[1,0]
	v_cvt_pk_bf16_f32 v90, v94, v95
	v_mad_i64_i32 v[94:95], s[44:45], v99, s88, v[122:123]
	v_lshl_add_u64 v[94:95], v[94:95], 0, s[0:1]
	v_pk_mul_f32 v[96:97], v[96:97], v[98:99] op_sel_hi:[1,0]
	v_lshl_add_u64 v[94:95], v[94:95], 0, v[124:125]
	v_cvt_pk_bf16_f32 v91, v96, v97
	v_cvt_pk_bf16_f32 v92, v92, v93
	v_cvt_pk_bf16_f32 v93, v100, v101
	global_store_dwordx4 v[94:95], v[90:93], off sc1
	v_pk_mul_f32 v[88:89], v[88:89], v[98:99] op_sel_hi:[1,0]
	v_pk_mul_f32 v[86:87], v[86:87], v[98:99] op_sel_hi:[1,0]
	v_pk_mul_f32 v[90:91], v[84:85], v[98:99] op_sel_hi:[1,0]
	v_pk_mul_f32 v[84:85], v[82:83], v[98:99] op_sel_hi:[1,0]
	v_cvt_pk_bf16_f32 v82, v86, v87
	v_cvt_pk_bf16_f32 v83, v88, v89
	s_nop 0
	v_cvt_pk_bf16_f32 v84, v84, v85
	v_cvt_pk_bf16_f32 v85, v90, v91
	global_store_dwordx4 v[94:95], v[82:85], off offset:384 sc1
	s_nop 0
	s_nop 0
	v_add_u32_e32 v83, 48, v132
	v_mov_b32_e32 v82, v202
	v_fmamk_f32 v82, v82, 0x3b000000, v173
	v_rsq_f32_e32 v82, v82
	s_nop 0
	v_pk_mul_f32 v[78:79], v[78:79], v[82:83] op_sel_hi:[1,0]
	v_pk_mul_f32 v[84:85], v[76:77], v[82:83] op_sel_hi:[1,0]
	v_pk_mul_f32 v[76:77], v[74:75], v[82:83] op_sel_hi:[1,0]
	v_cvt_pk_bf16_f32 v74, v78, v79
	v_mad_i64_i32 v[78:79], s[44:45], v83, s88, v[122:123]
	v_lshl_add_u64 v[78:79], v[78:79], 0, s[0:1]
	v_pk_mul_f32 v[80:81], v[80:81], v[82:83] op_sel_hi:[1,0]
	v_lshl_add_u64 v[78:79], v[78:79], 0, v[124:125]
	v_cvt_pk_bf16_f32 v75, v80, v81
	v_cvt_pk_bf16_f32 v76, v76, v77
	v_cvt_pk_bf16_f32 v77, v84, v85
	global_store_dwordx4 v[78:79], v[74:77], off sc1
	v_pk_mul_f32 v[72:73], v[72:73], v[82:83] op_sel_hi:[1,0]
	v_pk_mul_f32 v[70:71], v[70:71], v[82:83] op_sel_hi:[1,0]
	v_pk_mul_f32 v[74:75], v[68:69], v[82:83] op_sel_hi:[1,0]
	v_pk_mul_f32 v[68:69], v[66:67], v[82:83] op_sel_hi:[1,0]
	v_cvt_pk_bf16_f32 v66, v70, v71
	v_cvt_pk_bf16_f32 v67, v72, v73
	s_nop 0
	v_cvt_pk_bf16_f32 v68, v68, v69
	v_cvt_pk_bf16_f32 v69, v74, v75
	global_store_dwordx4 v[78:79], v[66:69], off offset:384 sc1
	s_nop 0
	s_nop 0
	v_add_u32_e32 v67, 0x80, v132
	v_mov_b32_e32 v66, v203
	v_fmamk_f32 v66, v66, 0x3b000000, v173
	v_rsq_f32_e32 v66, v66
	s_nop 0
	v_pk_mul_f32 v[62:63], v[62:63], v[66:67] op_sel_hi:[1,0]
	v_pk_mul_f32 v[68:69], v[60:61], v[66:67] op_sel_hi:[1,0]
	v_pk_mul_f32 v[60:61], v[58:59], v[66:67] op_sel_hi:[1,0]
	v_cvt_pk_bf16_f32 v58, v62, v63
	v_mad_i64_i32 v[62:63], s[44:45], v67, s88, v[122:123]
	v_lshl_add_u64 v[62:63], v[62:63], 0, s[0:1]
	v_pk_mul_f32 v[64:65], v[64:65], v[66:67] op_sel_hi:[1,0]
	v_lshl_add_u64 v[62:63], v[62:63], 0, v[124:125]
	v_cvt_pk_bf16_f32 v59, v64, v65
	v_cvt_pk_bf16_f32 v60, v60, v61
	v_cvt_pk_bf16_f32 v61, v68, v69
	global_store_dwordx4 v[62:63], v[58:61], off sc1
	v_pk_mul_f32 v[56:57], v[56:57], v[66:67] op_sel_hi:[1,0]
	v_pk_mul_f32 v[54:55], v[54:55], v[66:67] op_sel_hi:[1,0]
	v_pk_mul_f32 v[58:59], v[52:53], v[66:67] op_sel_hi:[1,0]
	v_pk_mul_f32 v[52:53], v[50:51], v[66:67] op_sel_hi:[1,0]
	v_cvt_pk_bf16_f32 v50, v54, v55
	v_cvt_pk_bf16_f32 v51, v56, v57
	s_nop 0
	v_cvt_pk_bf16_f32 v52, v52, v53
	v_cvt_pk_bf16_f32 v53, v58, v59
	global_store_dwordx4 v[62:63], v[50:53], off offset:384 sc1
	s_nop 0
	s_nop 0
	v_add_u32_e32 v51, 0x90, v132
	v_mov_b32_e32 v50, v204
	v_fmamk_f32 v50, v50, 0x3b000000, v173
	v_rsq_f32_e32 v50, v50
	s_nop 0
	v_pk_mul_f32 v[46:47], v[46:47], v[50:51] op_sel_hi:[1,0]
	v_pk_mul_f32 v[52:53], v[44:45], v[50:51] op_sel_hi:[1,0]
	v_pk_mul_f32 v[44:45], v[42:43], v[50:51] op_sel_hi:[1,0]
	v_cvt_pk_bf16_f32 v42, v46, v47
	v_mad_i64_i32 v[46:47], s[44:45], v51, s88, v[122:123]
	v_lshl_add_u64 v[46:47], v[46:47], 0, s[0:1]
	v_pk_mul_f32 v[48:49], v[48:49], v[50:51] op_sel_hi:[1,0]
	v_lshl_add_u64 v[46:47], v[46:47], 0, v[124:125]
	v_cvt_pk_bf16_f32 v43, v48, v49
	v_cvt_pk_bf16_f32 v44, v44, v45
	v_cvt_pk_bf16_f32 v45, v52, v53
	global_store_dwordx4 v[46:47], v[42:45], off sc1
	v_pk_mul_f32 v[40:41], v[40:41], v[50:51] op_sel_hi:[1,0]
	v_pk_mul_f32 v[38:39], v[38:39], v[50:51] op_sel_hi:[1,0]
	v_pk_mul_f32 v[42:43], v[36:37], v[50:51] op_sel_hi:[1,0]
	v_pk_mul_f32 v[36:37], v[34:35], v[50:51] op_sel_hi:[1,0]
	v_cvt_pk_bf16_f32 v34, v38, v39
	v_cvt_pk_bf16_f32 v35, v40, v41
	s_nop 0
	v_cvt_pk_bf16_f32 v36, v36, v37
	v_cvt_pk_bf16_f32 v37, v42, v43
	global_store_dwordx4 v[46:47], v[34:37], off offset:384 sc1
	s_nop 0
	s_nop 0
	v_add_u32_e32 v35, 0xa0, v132
	v_mov_b32_e32 v34, v205
	v_fmamk_f32 v34, v34, 0x3b000000, v173
	v_rsq_f32_e32 v34, v34
	s_nop 0
	v_pk_mul_f32 v[30:31], v[30:31], v[34:35] op_sel_hi:[1,0]
	v_pk_mul_f32 v[36:37], v[28:29], v[34:35] op_sel_hi:[1,0]
	v_pk_mul_f32 v[28:29], v[26:27], v[34:35] op_sel_hi:[1,0]
	v_cvt_pk_bf16_f32 v26, v30, v31
	v_mad_i64_i32 v[30:31], s[44:45], v35, s88, v[122:123]
	v_lshl_add_u64 v[30:31], v[30:31], 0, s[0:1]
	v_pk_mul_f32 v[32:33], v[32:33], v[34:35] op_sel_hi:[1,0]
	v_lshl_add_u64 v[30:31], v[30:31], 0, v[124:125]
	v_cvt_pk_bf16_f32 v27, v32, v33
	v_cvt_pk_bf16_f32 v28, v28, v29
	v_cvt_pk_bf16_f32 v29, v36, v37
	global_store_dwordx4 v[30:31], v[26:29], off sc1
	v_pk_mul_f32 v[24:25], v[24:25], v[34:35] op_sel_hi:[1,0]
	v_pk_mul_f32 v[22:23], v[22:23], v[34:35] op_sel_hi:[1,0]
	v_pk_mul_f32 v[26:27], v[20:21], v[34:35] op_sel_hi:[1,0]
	v_pk_mul_f32 v[20:21], v[18:19], v[34:35] op_sel_hi:[1,0]
	v_cvt_pk_bf16_f32 v18, v22, v23
	v_cvt_pk_bf16_f32 v19, v24, v25
	s_nop 0
	v_cvt_pk_bf16_f32 v20, v20, v21
	v_cvt_pk_bf16_f32 v21, v26, v27
	global_store_dwordx4 v[30:31], v[18:21], off offset:384 sc1
	s_nop 0
	s_nop 0
	v_add_u32_e32 v19, 0xb0, v132
	v_mov_b32_e32 v18, v206
	v_fmamk_f32 v18, v18, 0x3b000000, v173
	v_rsq_f32_e32 v18, v18
	s_nop 0
	v_pk_mul_f32 v[14:15], v[14:15], v[18:19] op_sel_hi:[1,0]
	v_pk_mul_f32 v[20:21], v[12:13], v[18:19] op_sel_hi:[1,0]
	v_pk_mul_f32 v[12:13], v[10:11], v[18:19] op_sel_hi:[1,0]
	v_cvt_pk_bf16_f32 v10, v14, v15
	v_mad_i64_i32 v[14:15], s[44:45], v19, s88, v[122:123]
	v_lshl_add_u64 v[14:15], v[14:15], 0, s[0:1]
	v_lshl_add_u64 v[14:15], v[14:15], 0, v[124:125]
	s_mov_b64 s[0:1], 0x180
	v_lshl_add_u64 v[150:151], v[14:15], 0, s[0:1]
	v_pk_mul_f32 v[16:17], v[16:17], v[18:19] op_sel_hi:[1,0]
	v_pk_mul_f32 v[8:9], v[8:9], v[18:19] op_sel_hi:[1,0]
	v_cvt_pk_bf16_f32 v11, v16, v17
	v_cvt_pk_bf16_f32 v12, v12, v13
	v_cvt_pk_bf16_f32 v13, v20, v21
	global_store_dwordx4 v[14:15], v[10:13], off sc1
	v_pk_mul_f32 v[6:7], v[6:7], v[18:19] op_sel_hi:[1,0]
	v_pk_mul_f32 v[4:5], v[4:5], v[18:19] op_sel_hi:[1,0]
	v_pk_mul_f32 v[2:3], v[2:3], v[18:19] op_sel_hi:[1,0]
	v_cvt_pk_bf16_f32 v130, v6, v7
	v_cvt_pk_bf16_f32 v131, v8, v9
	s_nop 0
	v_cvt_pk_bf16_f32 v132, v2, v3
	v_cvt_pk_bf16_f32 v133, v4, v5
.LBB0_632:
	s_and_b64 vcc, exec, s[6:7]
	s_mov_b64 s[0:1], -1
	global_store_dwordx4 v[150:151], v[130:133], off sc1
	s_cbranch_vccnz .LBB0_606
	s_andn2_b64 vcc, exec, s[18:19]
	s_cbranch_vccnz .LBB0_605
	s_barrier
	s_branch .LBB0_605

.LBB0_1090:
	v_mov_b32_e32 v144, v151
	v_mov_b32_e32 v145, v150
	s_waitcnt vmcnt(0)
	v_cvt_pk_bf16_f32 v152, v126, v127
	v_cvt_pk_bf16_f32 v153, v128, v129
	v_cvt_pk_bf16_f32 v154, v122, v123
	v_mul_f32_e32 v123, v123, v123
	v_fmac_f32_e32 v123, v122, v122
	v_mul_f32_e32 v122, v125, v125
	v_fmac_f32_e32 v122, v124, v124
	v_cvt_pk_bf16_f32 v155, v124, v125
	v_add_f32_e32 v122, v123, v122
	v_mul_f32_e32 v123, v119, v119
	v_mul_f32_e32 v124, v121, v121
	v_mul_f32_e32 v127, v127, v127
	v_fmac_f32_e32 v123, v118, v118
	v_fmac_f32_e32 v124, v120, v120
	v_fmac_f32_e32 v127, v126, v126
	v_mul_f32_e32 v126, v129, v129
	v_add_f32_e32 v123, v123, v124
	v_mul_f32_e32 v124, v115, v115
	v_mul_f32_e32 v125, v117, v117
	s_lshl_b32 s4, s76, 8
	v_fmac_f32_e32 v126, v128, v128
	v_fmac_f32_e32 v124, v114, v114
	v_fmac_f32_e32 v125, v116, v116
	s_or_b32 s4, s4, s47
	v_add_f32_e32 v126, v127, v126
	v_add_f32_e32 v124, v124, v125
	v_lshl_add_u32 v142, v144, 3, s4
	s_lshl_b32 s4, s75, 8
	v_add_f32_e32 v122, v122, v126
	v_add_f32_e32 v123, v124, v123
	v_and_b32_e32 v124, 64, v148
	s_add_i32 s4, s4, s46
	v_add_f32_e32 v123, v123, v122
	v_xor_b32_e32 v122, 16, v148
	v_add_u32_e32 v126, 64, v124
	v_cmp_eq_u32_e32 vcc, 0, v144
	v_add_u32_e32 v144, s4, v145
	v_cmp_lt_i32_e64 s[4:5], v122, v126
	v_ashrrev_i32_e32 v145, 31, v144
	v_lshlrev_b64 v[156:157], 12, v[144:145]
	v_cndmask_b32_e64 v122, v148, v122, s[4:5]
	v_lshlrev_b32_e32 v122, 2, v122
	v_ashrrev_i32_e32 v143, 31, v142
	ds_bpermute_b32 v127, v122, v123
	v_lshl_add_u64 v[124:125], s[18:19], 0, v[156:157]
	v_lshl_add_u64 v[128:129], v[142:143], 1, v[124:125]
	global_store_dwordx4 v[128:129], v[152:155], off sc1
	v_cvt_pk_bf16_f32 v124, v118, v119
	v_xor_b32_e32 v118, 32, v148
	v_cmp_lt_i32_e64 s[4:5], v118, v126
	s_waitcnt lgkmcnt(0)
	v_add_f32_e32 v119, v123, v127
	v_cvt_pk_bf16_f32 v125, v120, v121
	v_cvt_pk_bf16_f32 v126, v114, v115
	v_cvt_pk_bf16_f32 v127, v116, v117
	global_store_dwordx4 v[128:129], v[124:127], off offset:256 sc1
	v_cndmask_b32_e64 v118, v148, v118, s[4:5]
	v_lshlrev_b32_e32 v118, 2, v118
	ds_bpermute_b32 v123, v118, v119
	s_and_saveexec_b64 s[4:5], vcc
	s_cbranch_execz .LBB0_1092
	v_lshl_add_u64 v[114:115], v[144:145], 2, s[16:17]
	s_waitcnt lgkmcnt(0)
	v_add_f32_e32 v116, v119, v123
	flat_atomic_add_f32 v[114:115], v116
.LBB0_1092:
	s_or_b64 exec, exec, s[4:5]
	v_cvt_pk_bf16_f32 v124, v110, v111
	v_cvt_pk_bf16_f32 v125, v112, v113
	v_cvt_pk_bf16_f32 v126, v106, v107
	v_mul_f32_e32 v107, v107, v107
	v_fmac_f32_e32 v107, v106, v106
	v_mul_f32_e32 v106, v109, v109
	v_fmac_f32_e32 v106, v108, v108
	v_cvt_pk_bf16_f32 v127, v108, v109
	v_add_f32_e32 v106, v107, v106
	v_mul_f32_e32 v107, v103, v103
	v_mul_f32_e32 v108, v105, v105
	v_mul_f32_e32 v111, v111, v111
	v_fmac_f32_e32 v107, v102, v102
	v_fmac_f32_e32 v108, v104, v104
	v_fmac_f32_e32 v111, v110, v110
	v_mul_f32_e32 v110, v113, v113
	v_add_f32_e32 v107, v107, v108
	v_mul_f32_e32 v108, v99, v99
	v_mul_f32_e32 v109, v101, v101
	v_fmac_f32_e32 v110, v112, v112
	v_fmac_f32_e32 v108, v98, v98
	v_fmac_f32_e32 v109, v100, v100
	v_add_f32_e32 v110, v111, v110
	v_add_f32_e32 v108, v108, v109
	v_add_f32_e32 v106, v106, v110
	v_add_f32_e32 v107, v108, v107
	v_add_f32_e32 v108, v107, v106
	v_add_u32_e32 v114, 16, v144
	ds_bpermute_b32 v109, v122, v108
	v_ashrrev_i32_e32 v115, 31, v114
	v_lshlrev_b64 v[116:117], 12, v[114:115]
	v_lshl_add_u64 v[106:107], s[18:19], 0, v[116:117]
	v_lshl_add_u64 v[110:111], v[142:143], 1, v[106:107]
	global_store_dwordx4 v[110:111], v[124:127], off sc1
	v_cvt_pk_bf16_f32 v106, v102, v103
	s_waitcnt lgkmcnt(0)
	v_add_f32_e32 v102, v108, v109
	ds_bpermute_b32 v103, v118, v102
	v_cvt_pk_bf16_f32 v107, v104, v105
	v_cvt_pk_bf16_f32 v108, v98, v99
	v_cvt_pk_bf16_f32 v109, v100, v101
	global_store_dwordx4 v[110:111], v[106:109], off offset:256 sc1
	s_and_saveexec_b64 s[4:5], vcc
	s_cbranch_execz .LBB0_1094
	v_lshl_add_u64 v[98:99], v[114:115], 2, s[16:17]
	s_waitcnt lgkmcnt(0)
	v_add_f32_e32 v100, v102, v103
	flat_atomic_add_f32 v[98:99], v100
.LBB0_1094:
	s_or_b64 exec, exec, s[4:5]
	v_cvt_pk_bf16_f32 v100, v94, v95
	v_cvt_pk_bf16_f32 v101, v96, v97
	v_cvt_pk_bf16_f32 v102, v90, v91
	v_mul_f32_e32 v91, v91, v91
	v_fmac_f32_e32 v91, v90, v90
	v_mul_f32_e32 v90, v93, v93
	v_fmac_f32_e32 v90, v92, v92
	s_waitcnt lgkmcnt(0)
	v_cvt_pk_bf16_f32 v103, v92, v93
	v_add_f32_e32 v90, v91, v90
	v_mul_f32_e32 v91, v87, v87
	v_mul_f32_e32 v92, v89, v89
	v_mul_f32_e32 v95, v95, v95
	v_fmac_f32_e32 v91, v86, v86
	v_fmac_f32_e32 v92, v88, v88
	v_fmac_f32_e32 v95, v94, v94
	v_mul_f32_e32 v94, v97, v97
	v_add_f32_e32 v91, v91, v92
	v_mul_f32_e32 v92, v83, v83
	v_mul_f32_e32 v93, v85, v85
	v_fmac_f32_e32 v94, v96, v96
	v_fmac_f32_e32 v92, v82, v82
	v_fmac_f32_e32 v93, v84, v84
	v_add_f32_e32 v94, v95, v94
	v_add_f32_e32 v92, v92, v93
	v_add_f32_e32 v90, v90, v94
	v_add_f32_e32 v91, v92, v91
	v_add_f32_e32 v92, v91, v90
	v_add_u32_e32 v98, 32, v144
	ds_bpermute_b32 v93, v122, v92
	v_ashrrev_i32_e32 v99, 31, v98
	v_lshlrev_b64 v[104:105], 12, v[98:99]
	v_lshl_add_u64 v[90:91], s[18:19], 0, v[104:105]
	v_lshl_add_u64 v[94:95], v[142:143], 1, v[90:91]
	global_store_dwordx4 v[94:95], v[100:103], off sc1
	v_cvt_pk_bf16_f32 v90, v86, v87
	s_waitcnt lgkmcnt(0)
	v_add_f32_e32 v86, v92, v93
	ds_bpermute_b32 v87, v118, v86
	v_cvt_pk_bf16_f32 v91, v88, v89
	v_cvt_pk_bf16_f32 v92, v82, v83
	v_cvt_pk_bf16_f32 v93, v84, v85
	global_store_dwordx4 v[94:95], v[90:93], off offset:256 sc1
	s_and_saveexec_b64 s[4:5], vcc
	s_cbranch_execz .LBB0_1096
	v_lshl_add_u64 v[82:83], v[98:99], 2, s[16:17]
	s_waitcnt lgkmcnt(0)
	v_add_f32_e32 v84, v86, v87
	flat_atomic_add_f32 v[82:83], v84
.LBB0_1096:
	s_or_b64 exec, exec, s[4:5]
	v_cvt_pk_bf16_f32 v84, v78, v79
	v_cvt_pk_bf16_f32 v85, v80, v81
	v_cvt_pk_bf16_f32 v86, v74, v75
	v_mul_f32_e32 v75, v75, v75
	v_fmac_f32_e32 v75, v74, v74
	v_mul_f32_e32 v74, v77, v77
	v_fmac_f32_e32 v74, v76, v76
	s_waitcnt lgkmcnt(0)
	v_cvt_pk_bf16_f32 v87, v76, v77
	v_add_f32_e32 v74, v75, v74
	v_mul_f32_e32 v75, v71, v71
	v_mul_f32_e32 v76, v73, v73
	v_mul_f32_e32 v79, v79, v79
	v_fmac_f32_e32 v75, v70, v70
	v_fmac_f32_e32 v76, v72, v72
	v_fmac_f32_e32 v79, v78, v78
	v_mul_f32_e32 v78, v81, v81
	v_add_f32_e32 v75, v75, v76
	v_mul_f32_e32 v76, v67, v67
	v_mul_f32_e32 v77, v69, v69
	v_fmac_f32_e32 v78, v80, v80
	v_fmac_f32_e32 v76, v66, v66
	v_fmac_f32_e32 v77, v68, v68
	v_add_f32_e32 v78, v79, v78
	v_add_f32_e32 v76, v76, v77
	v_add_f32_e32 v74, v74, v78
	v_add_f32_e32 v75, v76, v75
	v_add_f32_e32 v76, v75, v74
	v_add_u32_e32 v82, 48, v144
	ds_bpermute_b32 v77, v122, v76
	v_ashrrev_i32_e32 v83, 31, v82
	v_lshlrev_b64 v[88:89], 12, v[82:83]
	v_lshl_add_u64 v[74:75], s[18:19], 0, v[88:89]
	v_lshl_add_u64 v[78:79], v[142:143], 1, v[74:75]
	global_store_dwordx4 v[78:79], v[84:87], off sc1
	v_cvt_pk_bf16_f32 v74, v70, v71
	s_waitcnt lgkmcnt(0)
	v_add_f32_e32 v70, v76, v77
	ds_bpermute_b32 v71, v118, v70
	v_cvt_pk_bf16_f32 v75, v72, v73
	v_cvt_pk_bf16_f32 v76, v66, v67
	v_cvt_pk_bf16_f32 v77, v68, v69
	global_store_dwordx4 v[78:79], v[74:77], off offset:256 sc1
	s_and_saveexec_b64 s[4:5], vcc
	s_cbranch_execz .LBB0_1098
	v_lshl_add_u64 v[66:67], v[82:83], 2, s[16:17]
	s_waitcnt lgkmcnt(0)
	v_add_f32_e32 v68, v70, v71
	flat_atomic_add_f32 v[66:67], v68
.LBB0_1098:
	s_or_b64 exec, exec, s[4:5]
	v_cvt_pk_bf16_f32 v68, v62, v63
	v_cvt_pk_bf16_f32 v69, v64, v65
	v_cvt_pk_bf16_f32 v70, v58, v59
	v_mul_f32_e32 v59, v59, v59
	v_fmac_f32_e32 v59, v58, v58
	v_mul_f32_e32 v58, v61, v61
	v_fmac_f32_e32 v58, v60, v60
	s_waitcnt lgkmcnt(0)
	v_cvt_pk_bf16_f32 v71, v60, v61
	v_add_f32_e32 v58, v59, v58
	v_mul_f32_e32 v59, v55, v55
	v_mul_f32_e32 v60, v57, v57
	v_mul_f32_e32 v63, v63, v63
	v_fmac_f32_e32 v59, v54, v54
	v_fmac_f32_e32 v60, v56, v56
	v_fmac_f32_e32 v63, v62, v62
	v_mul_f32_e32 v62, v65, v65
	v_add_f32_e32 v59, v59, v60
	v_mul_f32_e32 v60, v51, v51
	v_mul_f32_e32 v61, v53, v53
	v_fmac_f32_e32 v62, v64, v64
	v_fmac_f32_e32 v60, v50, v50
	v_fmac_f32_e32 v61, v52, v52
	v_add_f32_e32 v62, v63, v62
	v_add_f32_e32 v60, v60, v61
	v_add_f32_e32 v58, v58, v62
	v_add_f32_e32 v59, v60, v59
	v_add_f32_e32 v60, v59, v58
	v_add_u32_e32 v66, 0x80, v144
	ds_bpermute_b32 v61, v122, v60
	v_ashrrev_i32_e32 v67, 31, v66
	v_lshlrev_b64 v[72:73], 12, v[66:67]
	v_lshl_add_u64 v[58:59], s[18:19], 0, v[72:73]
	v_lshl_add_u64 v[62:63], v[142:143], 1, v[58:59]
	global_store_dwordx4 v[62:63], v[68:71], off sc1
	v_cvt_pk_bf16_f32 v58, v54, v55
	s_waitcnt lgkmcnt(0)
	v_add_f32_e32 v54, v60, v61
	ds_bpermute_b32 v55, v118, v54
	v_cvt_pk_bf16_f32 v59, v56, v57
	v_cvt_pk_bf16_f32 v60, v50, v51
	v_cvt_pk_bf16_f32 v61, v52, v53
	global_store_dwordx4 v[62:63], v[58:61], off offset:256 sc1
	s_and_saveexec_b64 s[4:5], vcc
	s_cbranch_execz .LBB0_1100
	v_lshl_add_u64 v[50:51], v[66:67], 2, s[16:17]
	s_waitcnt lgkmcnt(0)
	v_add_f32_e32 v52, v54, v55
	flat_atomic_add_f32 v[50:51], v52
.LBB0_1100:
	s_or_b64 exec, exec, s[4:5]
	v_cvt_pk_bf16_f32 v52, v46, v47
	v_cvt_pk_bf16_f32 v53, v48, v49
	v_cvt_pk_bf16_f32 v54, v42, v43
	v_mul_f32_e32 v43, v43, v43
	v_fmac_f32_e32 v43, v42, v42
	v_mul_f32_e32 v42, v45, v45
	v_fmac_f32_e32 v42, v44, v44
	s_waitcnt lgkmcnt(0)
	v_cvt_pk_bf16_f32 v55, v44, v45
	v_add_f32_e32 v42, v43, v42
	v_mul_f32_e32 v43, v39, v39
	v_mul_f32_e32 v44, v41, v41
	v_mul_f32_e32 v47, v47, v47
	v_fmac_f32_e32 v43, v38, v38
	v_fmac_f32_e32 v44, v40, v40
	v_fmac_f32_e32 v47, v46, v46
	v_mul_f32_e32 v46, v49, v49
	v_add_f32_e32 v43, v43, v44
	v_mul_f32_e32 v44, v35, v35
	v_mul_f32_e32 v45, v37, v37
	v_fmac_f32_e32 v46, v48, v48
	v_fmac_f32_e32 v44, v34, v34
	v_fmac_f32_e32 v45, v36, v36
	v_add_f32_e32 v46, v47, v46
	v_add_f32_e32 v44, v44, v45
	v_add_f32_e32 v42, v42, v46
	v_add_f32_e32 v43, v44, v43
	v_add_f32_e32 v44, v43, v42
	v_add_u32_e32 v50, 0x90, v144
	ds_bpermute_b32 v45, v122, v44
	v_ashrrev_i32_e32 v51, 31, v50
	v_lshlrev_b64 v[56:57], 12, v[50:51]
	v_lshl_add_u64 v[42:43], s[18:19], 0, v[56:57]
	v_lshl_add_u64 v[46:47], v[142:143], 1, v[42:43]
	global_store_dwordx4 v[46:47], v[52:55], off sc1
	v_cvt_pk_bf16_f32 v42, v38, v39
	s_waitcnt lgkmcnt(0)
	v_add_f32_e32 v38, v44, v45
	ds_bpermute_b32 v39, v118, v38
	v_cvt_pk_bf16_f32 v43, v40, v41
	v_cvt_pk_bf16_f32 v44, v34, v35
	v_cvt_pk_bf16_f32 v45, v36, v37
	global_store_dwordx4 v[46:47], v[42:45], off offset:256 sc1
	s_and_saveexec_b64 s[4:5], vcc
	s_cbranch_execz .LBB0_1102
	v_lshl_add_u64 v[34:35], v[50:51], 2, s[16:17]
	s_waitcnt lgkmcnt(0)
	v_add_f32_e32 v36, v38, v39
	flat_atomic_add_f32 v[34:35], v36
.LBB0_1102:
	s_or_b64 exec, exec, s[4:5]
	v_cvt_pk_bf16_f32 v36, v30, v31
	v_cvt_pk_bf16_f32 v37, v32, v33
	v_cvt_pk_bf16_f32 v38, v26, v27
	v_mul_f32_e32 v27, v27, v27
	v_fmac_f32_e32 v27, v26, v26
	v_mul_f32_e32 v26, v29, v29
	v_fmac_f32_e32 v26, v28, v28
	s_waitcnt lgkmcnt(0)
	v_cvt_pk_bf16_f32 v39, v28, v29
	v_add_f32_e32 v26, v27, v26
	v_mul_f32_e32 v27, v23, v23
	v_mul_f32_e32 v28, v25, v25
	v_mul_f32_e32 v31, v31, v31
	v_fmac_f32_e32 v27, v22, v22
	v_fmac_f32_e32 v28, v24, v24
	v_fmac_f32_e32 v31, v30, v30
	v_mul_f32_e32 v30, v33, v33
	v_add_f32_e32 v27, v27, v28
	v_mul_f32_e32 v28, v19, v19
	v_mul_f32_e32 v29, v21, v21
	v_fmac_f32_e32 v30, v32, v32
	v_fmac_f32_e32 v28, v18, v18
	v_fmac_f32_e32 v29, v20, v20
	v_add_f32_e32 v30, v31, v30
	v_add_f32_e32 v28, v28, v29
	v_add_f32_e32 v26, v26, v30
	v_add_f32_e32 v27, v28, v27
	v_add_f32_e32 v28, v27, v26
	v_add_u32_e32 v34, 0xa0, v144
	ds_bpermute_b32 v29, v122, v28
	v_ashrrev_i32_e32 v35, 31, v34
	v_lshlrev_b64 v[40:41], 12, v[34:35]
	v_lshl_add_u64 v[26:27], s[18:19], 0, v[40:41]
	v_lshl_add_u64 v[30:31], v[142:143], 1, v[26:27]
	global_store_dwordx4 v[30:31], v[36:39], off sc1
	v_cvt_pk_bf16_f32 v26, v22, v23
	s_waitcnt lgkmcnt(0)
	v_add_f32_e32 v22, v28, v29
	ds_bpermute_b32 v23, v118, v22
	v_cvt_pk_bf16_f32 v27, v24, v25
	v_cvt_pk_bf16_f32 v28, v18, v19
	v_cvt_pk_bf16_f32 v29, v20, v21
	global_store_dwordx4 v[30:31], v[26:29], off offset:256 sc1
	s_and_saveexec_b64 s[4:5], vcc
	s_cbranch_execz .LBB0_1104
	v_lshl_add_u64 v[18:19], v[34:35], 2, s[16:17]
	s_waitcnt lgkmcnt(0)
	v_add_f32_e32 v20, v22, v23
	flat_atomic_add_f32 v[18:19], v20
.LBB0_1104:
	s_or_b64 exec, exec, s[4:5]
	v_cvt_pk_bf16_f32 v20, v14, v15
	v_cvt_pk_bf16_f32 v21, v16, v17
	v_cvt_pk_bf16_f32 v22, v10, v11
	v_mul_f32_e32 v11, v11, v11
	v_fmac_f32_e32 v11, v10, v10
	v_mul_f32_e32 v10, v13, v13
	v_fmac_f32_e32 v10, v12, v12
	s_waitcnt lgkmcnt(0)
	v_cvt_pk_bf16_f32 v23, v12, v13
	v_add_f32_e32 v10, v11, v10
	v_mul_f32_e32 v11, v7, v7
	v_mul_f32_e32 v12, v9, v9
	v_mul_f32_e32 v15, v15, v15
	v_fmac_f32_e32 v11, v6, v6
	v_fmac_f32_e32 v12, v8, v8
	v_fmac_f32_e32 v15, v14, v14
	v_mul_f32_e32 v14, v17, v17
	v_add_f32_e32 v11, v11, v12
	v_mul_f32_e32 v12, v3, v3
	v_mul_f32_e32 v13, v5, v5
	v_fmac_f32_e32 v14, v16, v16
	v_fmac_f32_e32 v12, v2, v2
	v_fmac_f32_e32 v13, v4, v4
	v_add_f32_e32 v14, v15, v14
	v_add_f32_e32 v12, v12, v13
	v_add_f32_e32 v10, v10, v14
	v_add_f32_e32 v11, v12, v11
	v_add_f32_e32 v12, v11, v10
	v_add_u32_e32 v18, 0xb0, v144
	ds_bpermute_b32 v13, v122, v12
	v_ashrrev_i32_e32 v19, 31, v18
	v_lshlrev_b64 v[24:25], 12, v[18:19]
	v_lshl_add_u64 v[10:11], s[18:19], 0, v[24:25]
	v_lshl_add_u64 v[14:15], v[142:143], 1, v[10:11]
	global_store_dwordx4 v[14:15], v[20:23], off sc1
	v_cvt_pk_bf16_f32 v10, v6, v7
	s_waitcnt lgkmcnt(0)
	v_add_f32_e32 v6, v12, v13
	ds_bpermute_b32 v7, v118, v6
	v_cvt_pk_bf16_f32 v11, v8, v9
	v_cvt_pk_bf16_f32 v12, v2, v3
	v_cvt_pk_bf16_f32 v13, v4, v5
	global_store_dwordx4 v[14:15], v[10:13], off offset:256 sc1
	s_and_saveexec_b64 s[4:5], vcc
	s_cbranch_execz .LBB0_1106
	v_lshl_add_u64 v[2:3], v[18:19], 2, s[16:17]
	s_waitcnt lgkmcnt(0)
	v_add_f32_e32 v4, v6, v7
	flat_atomic_add_f32 v[2:3], v4

.LBB0_1202:
	s_lshl_b32 s36, s71, 8
	v_mov_b32_e32 v146, v151
	v_mov_b32_e32 v144, v150
	s_add_i32 s36, s36, s59
	v_mov_b32_e32 v158, v118
	v_add_u32_e32 v148, s36, v144
	v_ashrrev_i32_e32 v149, 31, v148
	v_lshl_add_u64 v[144:145], v[148:149], 2, s[14:15]
	global_load_dword v149, v[144:145], off
	global_load_dword v200, v[144:145], off offset:64
	global_load_dword v201, v[144:145], off offset:128
	global_load_dword v202, v[144:145], off offset:192
	global_load_dword v203, v[144:145], off offset:512
	global_load_dword v204, v[144:145], off offset:576
	global_load_dword v205, v[144:145], off offset:640
	global_load_dword v206, v[144:145], off offset:704
	v_mov_b32_e32 v118, v116
	v_mov_b32_e32 v160, v114
	v_mov_b32_e32 v114, v120
	v_add_u32_e32 v164, 16, v148
	v_ashrrev_i32_e32 v165, 31, v164
	v_lshl_add_u64 v[166:167], v[164:165], 2, s[14:15]
	s_lshl_b32 s36, s70, 7
	v_mov_b64_e32 v[144:145], s[16:17]
	s_ashr_i32 s37, s36, 31
	v_lshl_add_u32 v146, v146, 3, s60
	s_lshl_b64 s[36:37], s[36:37], 1
	v_ashrrev_i32_e32 v147, 31, v146
	v_mad_i64_i32 v[162:163], s[38:39], v148, s65, v[144:145]
	v_lshl_add_u64 v[162:163], v[162:163], 0, s[36:37]
	v_lshlrev_b64 v[146:147], 1, v[146:147]
	v_lshl_add_u64 v[162:163], v[162:163], 0, v[146:147]
	s_and_b64 vcc, exec, s[0:1]
	s_waitcnt vmcnt(0) lgkmcnt(0)
	v_fmamk_f32 v116, v149, 0x3a000000, v156
	v_rsq_f32_e32 v120, v116
	s_nop 0
	v_pk_mul_f32 v[122:123], v[122:123], v[120:121] op_sel_hi:[1,0]
	s_nop 0
	v_mul_f32_e32 v116, 0xbfb8aa3b, v122
	v_exp_f32_e32 v116, v116
	v_pk_mul_f32 v[126:127], v[126:127], v[120:121] op_sel_hi:[1,0]
	v_pk_mul_f32 v[124:125], v[124:125], v[120:121] op_sel_hi:[1,0]
	v_mul_f32_e32 v149, 0xbfb8aa3b, v126
	v_exp_f32_e32 v149, v149
	v_add_f32_e32 v116, 1.0, v116
	v_pk_mul_f32 v[128:129], v[128:129], v[120:121] op_sel_hi:[1,0]
	v_mov_b32_e32 v161, v126
	v_mov_b32_e32 v126, v115
	v_mul_f32_e32 v168, 0xbfb8aa3b, v124
	v_mov_b32_e32 v115, v124
	v_mov_b32_e32 v124, v121
	v_rcp_f32_e32 v121, v116
	v_mul_f32_e32 v157, 0xbfb8aa3b, v123
	v_mov_b32_e32 v159, v122
	v_exp_f32_e32 v157, v157
	v_add_f32_e32 v149, 1.0, v149
	v_mov_b32_e32 v122, v119
	v_mul_f32_e32 v169, 0xbfb8aa3b, v128
	v_mov_b32_e32 v119, v128
	v_mov_b32_e32 v128, v117
	v_pk_mul_f32 v[116:117], v[158:159], v[120:121]
	v_rcp_f32_e32 v121, v149
	v_mul_f32_e32 v165, 0xbfb8aa3b, v127
	v_exp_f32_e32 v149, v165
	v_add_f32_e32 v157, 1.0, v157
	v_pk_mul_f32 v[158:159], v[160:161], v[120:121]
	v_rcp_f32_e32 v121, v157
	v_exp_f32_e32 v165, v168
	v_add_f32_e32 v149, 1.0, v149
	v_exp_f32_e32 v157, v169
	v_pk_mul_f32 v[122:123], v[122:123], v[120:121]
	v_rcp_f32_e32 v121, v149
	v_add_f32_e32 v161, 1.0, v165
	v_mul_f32_e32 v170, 0xbfb8aa3b, v125
	v_exp_f32_e32 v160, v170
	v_pk_mul_f32 v[126:127], v[126:127], v[120:121]
	v_rcp_f32_e32 v121, v161
	v_add_f32_e32 v157, 1.0, v157
	v_mul_f32_e32 v161, v116, v117
	v_mul_f32_e32 v171, 0xbfb8aa3b, v129
	v_pk_mul_f32 v[116:117], v[114:115], v[120:121]
	v_rcp_f32_e32 v121, v157
	v_exp_f32_e32 v149, v171
	v_add_f32_e32 v160, 1.0, v160
	v_mul_f32_e32 v115, v116, v117
	v_pk_mul_f32 v[118:119], v[118:119], v[120:121]
	v_rcp_f32_e32 v121, v160
	v_add_f32_e32 v149, 1.0, v149
	v_mul_f32_e32 v114, v122, v123
	v_mul_f32_e32 v123, v118, v119
	v_pk_mul_f32 v[116:117], v[124:125], v[120:121]
	v_rcp_f32_e32 v121, v149
	v_mul_f32_e32 v116, v116, v117
	v_mul_f32_e32 v157, v158, v159
	v_cvt_pk_bf16_f32 v114, v161, v114
	v_pk_mul_f32 v[118:119], v[128:129], v[120:121]
	v_mul_f32_e32 v122, v126, v127
	v_mul_f32_e32 v117, v118, v119
	v_cvt_pk_bf16_f32 v115, v115, v116
	v_cvt_pk_bf16_f32 v116, v157, v122
	v_cvt_pk_bf16_f32 v117, v123, v117
	global_store_dwordx4 v[162:163], v[114:117], off sc1
	s_nop 0
	v_add_u32_e32 v118, 32, v148
	v_mov_b32_e32 v114, v102
	v_mov_b32_e32 v102, v100
	v_mov_b32_e32 v116, v98
	v_mov_b32_e32 v98, v104
	v_ashrrev_i32_e32 v119, 31, v118
	v_lshl_add_u64 v[122:123], v[118:119], 2, s[14:15]
	v_mad_i64_i32 v[120:121], s[38:39], v164, s65, v[144:145]
	v_lshl_add_u64 v[120:121], v[120:121], 0, s[36:37]
	v_lshl_add_u64 v[120:121], v[120:121], 0, v[146:147]
	v_mov_b32_e32 v115, v200
	v_fmamk_f32 v100, v115, 0x3a000000, v156
	v_rsq_f32_e32 v104, v100
	s_nop 0
	v_pk_mul_f32 v[110:111], v[110:111], v[104:105] op_sel_hi:[1,0]
	s_nop 0
	v_mul_f32_e32 v100, 0xbfb8aa3b, v110
	v_exp_f32_e32 v100, v100
	v_pk_mul_f32 v[106:107], v[106:107], v[104:105] op_sel_hi:[1,0]
	v_pk_mul_f32 v[112:113], v[112:113], v[104:105] op_sel_hi:[1,0]
	v_mul_f32_e32 v119, 0xbfb8aa3b, v106
	v_exp_f32_e32 v119, v119
	v_add_f32_e32 v100, 1.0, v100
	v_pk_mul_f32 v[108:109], v[108:109], v[104:105] op_sel_hi:[1,0]
	v_mov_b32_e32 v117, v106
	v_mov_b32_e32 v106, v99
	v_mul_f32_e32 v126, 0xbfb8aa3b, v112
	v_mov_b32_e32 v99, v112
	v_mov_b32_e32 v112, v105
	v_rcp_f32_e32 v105, v100
	v_mul_f32_e32 v124, 0xbfb8aa3b, v111
	v_mov_b32_e32 v115, v110
	v_exp_f32_e32 v124, v124
	v_add_f32_e32 v119, 1.0, v119
	v_mov_b32_e32 v110, v103
	v_mul_f32_e32 v127, 0xbfb8aa3b, v108
	v_mov_b32_e32 v103, v108
	v_mov_b32_e32 v108, v101
	v_pk_mul_f32 v[100:101], v[114:115], v[104:105]
	v_rcp_f32_e32 v105, v119
	v_mul_f32_e32 v125, 0xbfb8aa3b, v107
	v_exp_f32_e32 v119, v125
	v_add_f32_e32 v124, 1.0, v124
	v_pk_mul_f32 v[114:115], v[116:117], v[104:105]
	v_rcp_f32_e32 v105, v124
	v_exp_f32_e32 v125, v126
	v_add_f32_e32 v119, 1.0, v119
	v_exp_f32_e32 v116, v127
	v_pk_mul_f32 v[110:111], v[110:111], v[104:105]
	v_rcp_f32_e32 v105, v119
	v_add_f32_e32 v124, 1.0, v125
	v_mul_f32_e32 v128, 0xbfb8aa3b, v113
	v_exp_f32_e32 v117, v128
	v_pk_mul_f32 v[106:107], v[106:107], v[104:105]
	v_rcp_f32_e32 v105, v124
	v_add_f32_e32 v116, 1.0, v116
	v_mul_f32_e32 v124, v100, v101
	v_mul_f32_e32 v129, 0xbfb8aa3b, v109
	v_pk_mul_f32 v[100:101], v[98:99], v[104:105]
	v_rcp_f32_e32 v105, v116
	v_exp_f32_e32 v119, v129
	v_add_f32_e32 v117, 1.0, v117
	v_mul_f32_e32 v99, v100, v101
	v_pk_mul_f32 v[102:103], v[102:103], v[104:105]
	v_rcp_f32_e32 v105, v117
	v_add_f32_e32 v119, 1.0, v119
	v_mul_f32_e32 v106, v106, v107
	v_mul_f32_e32 v107, v102, v103
	v_pk_mul_f32 v[100:101], v[112:113], v[104:105]
	v_rcp_f32_e32 v105, v119
	v_mul_f32_e32 v98, v110, v111
	v_mul_f32_e32 v100, v100, v101
	v_mul_f32_e32 v114, v114, v115
	v_pk_mul_f32 v[102:103], v[108:109], v[104:105]
	v_cvt_pk_bf16_f32 v98, v124, v98
	v_cvt_pk_bf16_f32 v99, v99, v100
	v_cvt_pk_bf16_f32 v100, v114, v106
	v_mad_i64_i32 v[104:105], s[38:39], v118, s65, v[144:145]
	v_mul_f32_e32 v101, v102, v103
	v_cvt_pk_bf16_f32 v101, v107, v101
	global_store_dwordx4 v[120:121], v[98:101], off sc1
	s_nop 0
	v_add_u32_e32 v102, 48, v148
	v_mov_b32_e32 v98, v86
	v_mov_b32_e32 v86, v84
	v_mov_b32_e32 v100, v82
	v_mov_b32_e32 v82, v88
	v_ashrrev_i32_e32 v103, 31, v102
	v_lshl_add_u64 v[106:107], v[102:103], 2, s[14:15]
	v_lshl_add_u64 v[104:105], v[104:105], 0, s[36:37]
	v_lshl_add_u64 v[104:105], v[104:105], 0, v[146:147]
	v_mov_b32_e32 v99, v201
	v_fmamk_f32 v84, v99, 0x3a000000, v156
	v_rsq_f32_e32 v88, v84
	s_nop 0
	v_pk_mul_f32 v[94:95], v[94:95], v[88:89] op_sel_hi:[1,0]
	s_nop 0
	v_mul_f32_e32 v84, 0xbfb8aa3b, v94
	v_exp_f32_e32 v84, v84
	v_pk_mul_f32 v[90:91], v[90:91], v[88:89] op_sel_hi:[1,0]
	v_pk_mul_f32 v[96:97], v[96:97], v[88:89] op_sel_hi:[1,0]
	v_mul_f32_e32 v103, 0xbfb8aa3b, v90
	v_exp_f32_e32 v103, v103
	v_add_f32_e32 v84, 1.0, v84
	v_pk_mul_f32 v[92:93], v[92:93], v[88:89] op_sel_hi:[1,0]
	v_mov_b32_e32 v101, v90
	v_mov_b32_e32 v90, v83
	v_mul_f32_e32 v110, 0xbfb8aa3b, v96
	v_mov_b32_e32 v83, v96
	v_mov_b32_e32 v96, v89
	v_rcp_f32_e32 v89, v84
	v_mul_f32_e32 v108, 0xbfb8aa3b, v95
	v_mov_b32_e32 v99, v94
	v_exp_f32_e32 v108, v108
	v_add_f32_e32 v103, 1.0, v103
	v_mov_b32_e32 v94, v87
	v_mul_f32_e32 v111, 0xbfb8aa3b, v92
	v_mov_b32_e32 v87, v92
	v_mov_b32_e32 v92, v85
	v_pk_mul_f32 v[84:85], v[98:99], v[88:89]
	v_rcp_f32_e32 v89, v103
	v_mul_f32_e32 v109, 0xbfb8aa3b, v91
	v_exp_f32_e32 v103, v109
	v_add_f32_e32 v108, 1.0, v108
	v_pk_mul_f32 v[98:99], v[100:101], v[88:89]
	v_rcp_f32_e32 v89, v108
	v_exp_f32_e32 v109, v110
	v_add_f32_e32 v103, 1.0, v103
	v_exp_f32_e32 v100, v111
	v_pk_mul_f32 v[94:95], v[94:95], v[88:89]
	v_rcp_f32_e32 v89, v103
	v_add_f32_e32 v108, 1.0, v109
	v_mul_f32_e32 v112, 0xbfb8aa3b, v97
	v_exp_f32_e32 v101, v112
	v_pk_mul_f32 v[90:91], v[90:91], v[88:89]
	v_rcp_f32_e32 v89, v108
	v_add_f32_e32 v100, 1.0, v100
	v_mul_f32_e32 v108, v84, v85
	v_mul_f32_e32 v113, 0xbfb8aa3b, v93
	v_pk_mul_f32 v[84:85], v[82:83], v[88:89]
	v_rcp_f32_e32 v89, v100
	v_exp_f32_e32 v103, v113
	v_add_f32_e32 v101, 1.0, v101
	v_mul_f32_e32 v83, v84, v85
	v_pk_mul_f32 v[86:87], v[86:87], v[88:89]
	v_rcp_f32_e32 v89, v101
	v_add_f32_e32 v103, 1.0, v103
	v_mul_f32_e32 v90, v90, v91
	v_mul_f32_e32 v91, v86, v87
	v_pk_mul_f32 v[84:85], v[96:97], v[88:89]
	v_rcp_f32_e32 v89, v103
	v_mul_f32_e32 v82, v94, v95
	v_mul_f32_e32 v84, v84, v85
	v_mul_f32_e32 v98, v98, v99
	v_pk_mul_f32 v[86:87], v[92:93], v[88:89]
	v_cvt_pk_bf16_f32 v82, v108, v82
	v_cvt_pk_bf16_f32 v83, v83, v84
	v_cvt_pk_bf16_f32 v84, v98, v90
	v_mad_i64_i32 v[88:89], s[38:39], v102, s65, v[144:145]
	v_mul_f32_e32 v85, v86, v87
	v_cvt_pk_bf16_f32 v85, v91, v85
	global_store_dwordx4 v[104:105], v[82:85], off sc1
	s_nop 0
	v_add_u32_e32 v86, 0x80, v148
	v_mov_b32_e32 v82, v70
	v_mov_b32_e32 v70, v68
	v_mov_b32_e32 v84, v66
	v_mov_b32_e32 v66, v72
	v_ashrrev_i32_e32 v87, 31, v86
	v_lshl_add_u64 v[90:91], v[86:87], 2, s[14:15]
	v_lshl_add_u64 v[88:89], v[88:89], 0, s[36:37]
	v_lshl_add_u64 v[88:89], v[88:89], 0, v[146:147]
	v_mov_b32_e32 v83, v202
	v_fmamk_f32 v68, v83, 0x3a000000, v156
	v_rsq_f32_e32 v72, v68
	s_nop 0
	v_pk_mul_f32 v[78:79], v[78:79], v[72:73] op_sel_hi:[1,0]
	s_nop 0
	v_mul_f32_e32 v68, 0xbfb8aa3b, v78
	v_exp_f32_e32 v68, v68
	v_pk_mul_f32 v[74:75], v[74:75], v[72:73] op_sel_hi:[1,0]
	v_pk_mul_f32 v[80:81], v[80:81], v[72:73] op_sel_hi:[1,0]
	v_mul_f32_e32 v87, 0xbfb8aa3b, v74
	v_exp_f32_e32 v87, v87
	v_add_f32_e32 v68, 1.0, v68
	v_pk_mul_f32 v[76:77], v[76:77], v[72:73] op_sel_hi:[1,0]
	v_mov_b32_e32 v85, v74
	v_mov_b32_e32 v74, v67
	v_mul_f32_e32 v94, 0xbfb8aa3b, v80
	v_mov_b32_e32 v67, v80
	v_mov_b32_e32 v80, v73
	v_rcp_f32_e32 v73, v68
	v_mul_f32_e32 v92, 0xbfb8aa3b, v79
	v_mov_b32_e32 v83, v78
	v_exp_f32_e32 v92, v92
	v_add_f32_e32 v87, 1.0, v87
	v_mov_b32_e32 v78, v71
	v_mul_f32_e32 v95, 0xbfb8aa3b, v76
	v_mov_b32_e32 v71, v76
	v_mov_b32_e32 v76, v69
	v_pk_mul_f32 v[68:69], v[82:83], v[72:73]
	v_rcp_f32_e32 v73, v87
	v_mul_f32_e32 v93, 0xbfb8aa3b, v75
	v_exp_f32_e32 v87, v93
	v_add_f32_e32 v92, 1.0, v92
	v_pk_mul_f32 v[82:83], v[84:85], v[72:73]
	v_rcp_f32_e32 v73, v92
	v_exp_f32_e32 v93, v94
	v_add_f32_e32 v87, 1.0, v87
	v_exp_f32_e32 v84, v95
	v_pk_mul_f32 v[78:79], v[78:79], v[72:73]
	v_rcp_f32_e32 v73, v87
	v_add_f32_e32 v92, 1.0, v93
	v_mul_f32_e32 v96, 0xbfb8aa3b, v81
	v_exp_f32_e32 v85, v96
	v_pk_mul_f32 v[74:75], v[74:75], v[72:73]
	v_rcp_f32_e32 v73, v92
	v_add_f32_e32 v84, 1.0, v84
	v_mul_f32_e32 v92, v68, v69
	v_mul_f32_e32 v97, 0xbfb8aa3b, v77
	v_pk_mul_f32 v[68:69], v[66:67], v[72:73]
	v_rcp_f32_e32 v73, v84
	v_exp_f32_e32 v87, v97
	v_add_f32_e32 v85, 1.0, v85
	v_mul_f32_e32 v67, v68, v69
	v_pk_mul_f32 v[70:71], v[70:71], v[72:73]
	v_rcp_f32_e32 v73, v85
	v_add_f32_e32 v87, 1.0, v87
	v_mul_f32_e32 v74, v74, v75
	v_mul_f32_e32 v75, v70, v71
	v_pk_mul_f32 v[68:69], v[80:81], v[72:73]
	v_rcp_f32_e32 v73, v87
	v_mul_f32_e32 v66, v78, v79
	v_mul_f32_e32 v68, v68, v69
	v_mul_f32_e32 v82, v82, v83
	v_pk_mul_f32 v[70:71], v[76:77], v[72:73]
	v_cvt_pk_bf16_f32 v66, v92, v66
	v_cvt_pk_bf16_f32 v67, v67, v68
	v_cvt_pk_bf16_f32 v68, v82, v74
	v_mad_i64_i32 v[72:73], s[38:39], v86, s65, v[144:145]
	v_mul_f32_e32 v69, v70, v71
	v_cvt_pk_bf16_f32 v69, v75, v69
	global_store_dwordx4 v[88:89], v[66:69], off sc1
	s_nop 0
	v_add_u32_e32 v70, 0x90, v148
	v_mov_b32_e32 v66, v54
	v_mov_b32_e32 v54, v52
	v_mov_b32_e32 v68, v50
	v_mov_b32_e32 v50, v56
	v_ashrrev_i32_e32 v71, 31, v70
	v_lshl_add_u64 v[74:75], v[70:71], 2, s[14:15]
	v_lshl_add_u64 v[72:73], v[72:73], 0, s[36:37]
	v_lshl_add_u64 v[72:73], v[72:73], 0, v[146:147]
	v_mov_b32_e32 v67, v203
	v_fmamk_f32 v52, v67, 0x3a000000, v156
	v_rsq_f32_e32 v56, v52
	s_nop 0
	v_pk_mul_f32 v[62:63], v[62:63], v[56:57] op_sel_hi:[1,0]
	s_nop 0
	v_mul_f32_e32 v52, 0xbfb8aa3b, v62
	v_exp_f32_e32 v52, v52
	v_pk_mul_f32 v[58:59], v[58:59], v[56:57] op_sel_hi:[1,0]
	v_pk_mul_f32 v[64:65], v[64:65], v[56:57] op_sel_hi:[1,0]
	v_mul_f32_e32 v71, 0xbfb8aa3b, v58
	v_exp_f32_e32 v71, v71
	v_add_f32_e32 v52, 1.0, v52
	v_pk_mul_f32 v[60:61], v[60:61], v[56:57] op_sel_hi:[1,0]
	v_mov_b32_e32 v69, v58
	v_mov_b32_e32 v58, v51
	v_mul_f32_e32 v78, 0xbfb8aa3b, v64
	v_mov_b32_e32 v51, v64
	v_mov_b32_e32 v64, v57
	v_rcp_f32_e32 v57, v52
	v_mul_f32_e32 v76, 0xbfb8aa3b, v63
	v_mov_b32_e32 v67, v62
	v_exp_f32_e32 v76, v76
	v_add_f32_e32 v71, 1.0, v71
	v_mov_b32_e32 v62, v55
	v_mul_f32_e32 v79, 0xbfb8aa3b, v60
	v_mov_b32_e32 v55, v60
	v_mov_b32_e32 v60, v53
	v_pk_mul_f32 v[52:53], v[66:67], v[56:57]
	v_rcp_f32_e32 v57, v71
	v_mul_f32_e32 v77, 0xbfb8aa3b, v59
	v_exp_f32_e32 v71, v77
	v_add_f32_e32 v76, 1.0, v76
	v_pk_mul_f32 v[66:67], v[68:69], v[56:57]
	v_rcp_f32_e32 v57, v76
	v_exp_f32_e32 v77, v78
	v_add_f32_e32 v71, 1.0, v71
	v_exp_f32_e32 v68, v79
	v_pk_mul_f32 v[62:63], v[62:63], v[56:57]
	v_rcp_f32_e32 v57, v71
	v_add_f32_e32 v76, 1.0, v77
	v_mul_f32_e32 v80, 0xbfb8aa3b, v65
	v_exp_f32_e32 v69, v80
	v_pk_mul_f32 v[58:59], v[58:59], v[56:57]
	v_rcp_f32_e32 v57, v76
	v_add_f32_e32 v68, 1.0, v68
	v_mul_f32_e32 v76, v52, v53
	v_mul_f32_e32 v81, 0xbfb8aa3b, v61
	v_pk_mul_f32 v[52:53], v[50:51], v[56:57]
	v_rcp_f32_e32 v57, v68
	v_exp_f32_e32 v71, v81
	v_add_f32_e32 v69, 1.0, v69
	v_mul_f32_e32 v51, v52, v53
	v_pk_mul_f32 v[54:55], v[54:55], v[56:57]
	v_rcp_f32_e32 v57, v69
	v_add_f32_e32 v71, 1.0, v71
	v_mul_f32_e32 v58, v58, v59
	v_mul_f32_e32 v59, v54, v55
	v_pk_mul_f32 v[52:53], v[64:65], v[56:57]
	v_rcp_f32_e32 v57, v71
	v_mul_f32_e32 v50, v62, v63
	v_mul_f32_e32 v52, v52, v53
	v_mul_f32_e32 v66, v66, v67
	v_pk_mul_f32 v[54:55], v[60:61], v[56:57]
	v_cvt_pk_bf16_f32 v50, v76, v50
	v_cvt_pk_bf16_f32 v51, v51, v52
	v_cvt_pk_bf16_f32 v52, v66, v58
	v_mad_i64_i32 v[56:57], s[38:39], v70, s65, v[144:145]
	v_mul_f32_e32 v53, v54, v55
	v_cvt_pk_bf16_f32 v53, v59, v53
	global_store_dwordx4 v[72:73], v[50:53], off sc1
	s_nop 0
	v_add_u32_e32 v54, 0xa0, v148
	v_mov_b32_e32 v50, v38
	v_mov_b32_e32 v38, v36
	v_mov_b32_e32 v52, v34
	v_mov_b32_e32 v34, v40
	v_ashrrev_i32_e32 v55, 31, v54
	v_lshl_add_u64 v[58:59], v[54:55], 2, s[14:15]
	v_lshl_add_u64 v[56:57], v[56:57], 0, s[36:37]
	v_lshl_add_u64 v[56:57], v[56:57], 0, v[146:147]
	v_mov_b32_e32 v51, v204
	v_fmamk_f32 v36, v51, 0x3a000000, v156
	v_rsq_f32_e32 v40, v36
	s_nop 0
	v_pk_mul_f32 v[46:47], v[46:47], v[40:41] op_sel_hi:[1,0]
	s_nop 0
	v_mul_f32_e32 v36, 0xbfb8aa3b, v46
	v_exp_f32_e32 v36, v36
	v_pk_mul_f32 v[42:43], v[42:43], v[40:41] op_sel_hi:[1,0]
	v_pk_mul_f32 v[48:49], v[48:49], v[40:41] op_sel_hi:[1,0]
	v_mul_f32_e32 v55, 0xbfb8aa3b, v42
	v_exp_f32_e32 v55, v55
	v_add_f32_e32 v36, 1.0, v36
	v_pk_mul_f32 v[44:45], v[44:45], v[40:41] op_sel_hi:[1,0]
	v_mov_b32_e32 v53, v42
	v_mov_b32_e32 v42, v35
	v_mul_f32_e32 v62, 0xbfb8aa3b, v48
	v_mov_b32_e32 v35, v48
	v_mov_b32_e32 v48, v41
	v_rcp_f32_e32 v41, v36
	v_mul_f32_e32 v60, 0xbfb8aa3b, v47
	v_mov_b32_e32 v51, v46
	v_exp_f32_e32 v60, v60
	v_add_f32_e32 v55, 1.0, v55
	v_mov_b32_e32 v46, v39
	v_mul_f32_e32 v63, 0xbfb8aa3b, v44
	v_mov_b32_e32 v39, v44
	v_mov_b32_e32 v44, v37
	v_pk_mul_f32 v[36:37], v[50:51], v[40:41]
	v_rcp_f32_e32 v41, v55
	v_mul_f32_e32 v61, 0xbfb8aa3b, v43
	v_exp_f32_e32 v55, v61
	v_add_f32_e32 v60, 1.0, v60
	v_pk_mul_f32 v[50:51], v[52:53], v[40:41]
	v_rcp_f32_e32 v41, v60
	v_exp_f32_e32 v61, v62
	v_add_f32_e32 v55, 1.0, v55
	v_exp_f32_e32 v52, v63
	v_pk_mul_f32 v[46:47], v[46:47], v[40:41]
	v_rcp_f32_e32 v41, v55
	v_add_f32_e32 v60, 1.0, v61
	v_mul_f32_e32 v64, 0xbfb8aa3b, v49
	v_exp_f32_e32 v53, v64
	v_pk_mul_f32 v[42:43], v[42:43], v[40:41]
	v_rcp_f32_e32 v41, v60
	v_add_f32_e32 v52, 1.0, v52
	v_mul_f32_e32 v60, v36, v37
	v_mul_f32_e32 v65, 0xbfb8aa3b, v45
	v_pk_mul_f32 v[36:37], v[34:35], v[40:41]
	v_rcp_f32_e32 v41, v52
	v_exp_f32_e32 v55, v65
	v_add_f32_e32 v53, 1.0, v53
	v_mul_f32_e32 v35, v36, v37
	v_pk_mul_f32 v[38:39], v[38:39], v[40:41]
	v_rcp_f32_e32 v41, v53
	v_add_f32_e32 v55, 1.0, v55
	v_mul_f32_e32 v42, v42, v43
	v_mul_f32_e32 v43, v38, v39
	v_pk_mul_f32 v[36:37], v[48:49], v[40:41]
	v_rcp_f32_e32 v41, v55
	v_mul_f32_e32 v34, v46, v47
	v_mul_f32_e32 v36, v36, v37
	v_mul_f32_e32 v50, v50, v51
	v_pk_mul_f32 v[38:39], v[44:45], v[40:41]
	v_cvt_pk_bf16_f32 v34, v60, v34
	v_cvt_pk_bf16_f32 v35, v35, v36
	v_cvt_pk_bf16_f32 v36, v50, v42
	v_mad_i64_i32 v[40:41], s[38:39], v54, s65, v[144:145]
	v_mul_f32_e32 v37, v38, v39
	v_cvt_pk_bf16_f32 v37, v43, v37
	global_store_dwordx4 v[56:57], v[34:37], off sc1
	s_nop 0
	v_add_u32_e32 v38, 0xb0, v148
	v_mov_b32_e32 v34, v22
	v_mov_b32_e32 v22, v20
	v_mov_b32_e32 v36, v18
	v_mov_b32_e32 v18, v24
	v_ashrrev_i32_e32 v39, 31, v38
	v_lshl_add_u64 v[42:43], v[38:39], 2, s[14:15]
	v_lshl_add_u64 v[40:41], v[40:41], 0, s[36:37]
	v_lshl_add_u64 v[40:41], v[40:41], 0, v[146:147]
	v_mov_b32_e32 v35, v205
	v_fmamk_f32 v20, v35, 0x3a000000, v156
	v_rsq_f32_e32 v24, v20
	s_nop 0
	v_pk_mul_f32 v[30:31], v[30:31], v[24:25] op_sel_hi:[1,0]
	s_nop 0
	v_mul_f32_e32 v20, 0xbfb8aa3b, v30
	v_exp_f32_e32 v20, v20
	v_pk_mul_f32 v[26:27], v[26:27], v[24:25] op_sel_hi:[1,0]
	v_pk_mul_f32 v[32:33], v[32:33], v[24:25] op_sel_hi:[1,0]
	v_mul_f32_e32 v39, 0xbfb8aa3b, v26
	v_exp_f32_e32 v39, v39
	v_add_f32_e32 v20, 1.0, v20
	v_pk_mul_f32 v[28:29], v[28:29], v[24:25] op_sel_hi:[1,0]
	v_mov_b32_e32 v37, v26
	v_mov_b32_e32 v26, v19
	v_mul_f32_e32 v46, 0xbfb8aa3b, v32
	v_mov_b32_e32 v19, v32
	v_mov_b32_e32 v32, v25
	v_rcp_f32_e32 v25, v20
	v_mul_f32_e32 v44, 0xbfb8aa3b, v31
	v_mov_b32_e32 v35, v30
	v_exp_f32_e32 v44, v44
	v_add_f32_e32 v39, 1.0, v39
	v_mov_b32_e32 v30, v23
	v_mul_f32_e32 v47, 0xbfb8aa3b, v28
	v_mov_b32_e32 v23, v28
	v_mov_b32_e32 v28, v21
	v_pk_mul_f32 v[20:21], v[34:35], v[24:25]
	v_rcp_f32_e32 v25, v39
	v_mul_f32_e32 v45, 0xbfb8aa3b, v27
	v_exp_f32_e32 v39, v45
	v_add_f32_e32 v44, 1.0, v44
	v_pk_mul_f32 v[34:35], v[36:37], v[24:25]
	v_rcp_f32_e32 v25, v44
	v_exp_f32_e32 v45, v46
	v_add_f32_e32 v39, 1.0, v39
	v_exp_f32_e32 v36, v47
	v_pk_mul_f32 v[30:31], v[30:31], v[24:25]
	v_rcp_f32_e32 v25, v39
	v_add_f32_e32 v44, 1.0, v45
	v_mul_f32_e32 v48, 0xbfb8aa3b, v33
	v_exp_f32_e32 v37, v48
	v_pk_mul_f32 v[26:27], v[26:27], v[24:25]
	v_rcp_f32_e32 v25, v44
	v_add_f32_e32 v36, 1.0, v36
	v_mul_f32_e32 v44, v20, v21
	v_mul_f32_e32 v49, 0xbfb8aa3b, v29
	v_pk_mul_f32 v[20:21], v[18:19], v[24:25]
	v_rcp_f32_e32 v25, v36
	v_exp_f32_e32 v39, v49
	v_add_f32_e32 v37, 1.0, v37
	v_mul_f32_e32 v19, v20, v21
	v_pk_mul_f32 v[22:23], v[22:23], v[24:25]
	v_rcp_f32_e32 v25, v37
	v_add_f32_e32 v39, 1.0, v39
	v_mul_f32_e32 v26, v26, v27
	v_mul_f32_e32 v27, v22, v23
	v_pk_mul_f32 v[20:21], v[32:33], v[24:25]
	v_rcp_f32_e32 v25, v39
	v_mul_f32_e32 v18, v30, v31
	v_mul_f32_e32 v20, v20, v21
	v_mul_f32_e32 v34, v34, v35
	v_pk_mul_f32 v[22:23], v[28:29], v[24:25]
	v_cvt_pk_bf16_f32 v18, v44, v18
	v_cvt_pk_bf16_f32 v19, v19, v20
	v_cvt_pk_bf16_f32 v20, v34, v26
	s_nop 0
	v_mul_f32_e32 v21, v22, v23
	v_cvt_pk_bf16_f32 v21, v27, v21
	global_store_dwordx4 v[40:41], v[18:21], off sc1
	s_nop 0
	v_mad_i64_i32 v[22:23], s[0:1], v38, s65, v[144:145]
	v_mov_b32_e32 v18, v6
	v_mov_b32_e32 v6, v4
	v_mov_b32_e32 v20, v2
	v_mov_b32_e32 v2, v8
	v_lshl_add_u64 v[22:23], v[22:23], 0, s[36:37]
	v_lshl_add_u64 v[22:23], v[22:23], 0, v[146:147]
	s_mov_b64 s[0:1], -1
	v_mov_b32_e32 v19, v206
	v_fmamk_f32 v4, v19, 0x3a000000, v156
	v_rsq_f32_e32 v8, v4
	s_nop 0
	v_pk_mul_f32 v[14:15], v[14:15], v[8:9] op_sel_hi:[1,0]
	s_nop 0
	v_mul_f32_e32 v4, 0xbfb8aa3b, v14
	v_exp_f32_e32 v4, v4
	v_pk_mul_f32 v[10:11], v[10:11], v[8:9] op_sel_hi:[1,0]
	v_pk_mul_f32 v[16:17], v[16:17], v[8:9] op_sel_hi:[1,0]
	v_mul_f32_e32 v24, 0xbfb8aa3b, v10
	v_exp_f32_e32 v24, v24
	v_add_f32_e32 v4, 1.0, v4
	v_pk_mul_f32 v[12:13], v[12:13], v[8:9] op_sel_hi:[1,0]
	v_mov_b32_e32 v21, v10
	v_mov_b32_e32 v10, v3
	v_mul_f32_e32 v27, 0xbfb8aa3b, v16
	v_mov_b32_e32 v3, v16
	v_mov_b32_e32 v16, v9
	v_rcp_f32_e32 v9, v4
	v_mul_f32_e32 v25, 0xbfb8aa3b, v15
	v_mov_b32_e32 v19, v14
	v_exp_f32_e32 v25, v25
	v_add_f32_e32 v24, 1.0, v24
	v_mov_b32_e32 v14, v7
	v_mul_f32_e32 v28, 0xbfb8aa3b, v12
	v_mov_b32_e32 v7, v12
	v_mov_b32_e32 v12, v5
	v_pk_mul_f32 v[4:5], v[18:19], v[8:9]
	v_rcp_f32_e32 v9, v24
	v_mul_f32_e32 v26, 0xbfb8aa3b, v11
	v_exp_f32_e32 v24, v26
	v_add_f32_e32 v25, 1.0, v25
	v_pk_mul_f32 v[18:19], v[20:21], v[8:9]
	v_rcp_f32_e32 v9, v25
	v_exp_f32_e32 v26, v27
	v_add_f32_e32 v24, 1.0, v24
	v_exp_f32_e32 v20, v28
	v_pk_mul_f32 v[14:15], v[14:15], v[8:9]
	v_rcp_f32_e32 v9, v24
	v_add_f32_e32 v25, 1.0, v26
	v_mul_f32_e32 v29, 0xbfb8aa3b, v17
	v_exp_f32_e32 v21, v29
	v_pk_mul_f32 v[10:11], v[10:11], v[8:9]
	v_rcp_f32_e32 v9, v25
	v_add_f32_e32 v20, 1.0, v20
	v_mul_f32_e32 v25, v4, v5
	v_mul_f32_e32 v30, 0xbfb8aa3b, v13
	v_pk_mul_f32 v[4:5], v[2:3], v[8:9]
	v_rcp_f32_e32 v9, v20
	v_exp_f32_e32 v24, v30
	v_add_f32_e32 v21, 1.0, v21
	v_mul_f32_e32 v3, v4, v5
	v_pk_mul_f32 v[6:7], v[6:7], v[8:9]
	v_rcp_f32_e32 v9, v21
	v_add_f32_e32 v24, 1.0, v24
	v_mul_f32_e32 v10, v10, v11
	v_mul_f32_e32 v11, v6, v7
	v_pk_mul_f32 v[4:5], v[16:17], v[8:9]
	v_rcp_f32_e32 v9, v24
	v_mul_f32_e32 v2, v14, v15
	v_mul_f32_e32 v4, v4, v5
	v_mul_f32_e32 v18, v18, v19
	v_pk_mul_f32 v[6:7], v[12:13], v[8:9]
	v_cvt_pk_bf16_f32 v2, v25, v2
	v_cvt_pk_bf16_f32 v3, v3, v4
	v_cvt_pk_bf16_f32 v4, v18, v10
	s_nop 0
	v_mul_f32_e32 v5, v6, v7
	v_cvt_pk_bf16_f32 v5, v11, v5
	global_store_dwordx4 v[22:23], v[2:5], off sc1
	s_cbranch_vccnz .LBB0_1186
	s_andn2_b64 vcc, exec, s[12:13]
	s_cbranch_vccnz .LBB0_1185
	s_barrier
	s_branch .LBB0_1185

.LBB0_1300:
	v_mov_b32_e32 v143, v150
	v_mov_b32_e32 v145, v151
	v_cvt_pk_bf16_f32 v152, v118, v119
	v_mul_f32_e32 v119, v119, v119
	v_fmac_f32_e32 v119, v118, v118
	v_mul_f32_e32 v118, v121, v121
	v_fmac_f32_e32 v118, v120, v120
	v_cvt_pk_bf16_f32 v153, v120, v121
	v_add_f32_e32 v118, v119, v118
	v_mul_f32_e32 v119, v123, v123
	v_mul_f32_e32 v120, v125, v125
	v_fmac_f32_e32 v119, v122, v122
	v_fmac_f32_e32 v120, v124, v124
	v_add_f32_e32 v119, v119, v120
	v_add_f32_e32 v118, v119, v118
	v_mul_f32_e32 v119, v115, v115
	v_mul_f32_e32 v120, v117, v117
	v_fmac_f32_e32 v119, v114, v114
	v_fmac_f32_e32 v120, v116, v116
	v_add_f32_e32 v119, v119, v120
	v_mul_f32_e32 v120, v127, v127
	v_mul_f32_e32 v121, v129, v129
	s_lshl_b32 s4, s74, 8
	v_fmac_f32_e32 v120, v126, v126
	v_fmac_f32_e32 v121, v128, v128
	s_or_b32 s4, s4, s47
	v_add_f32_e32 v120, v120, v121
	v_lshl_add_u32 v142, v145, 3, s4
	s_lshl_b32 s4, s73, 8
	v_add_f32_e32 v119, v120, v119
	v_and_b32_e32 v120, 64, v148
	s_add_i32 s4, s4, s46
	v_cvt_pk_bf16_f32 v154, v122, v123
	v_add_f32_e32 v119, v119, v118
	v_xor_b32_e32 v118, 16, v148
	v_add_u32_e32 v122, 64, v120
	v_add_u32_e32 v144, s4, v143
	v_cmp_lt_i32_e64 s[4:5], v118, v122
	v_cmp_eq_u32_e32 vcc, 0, v145
	v_ashrrev_i32_e32 v145, 31, v144
	v_cndmask_b32_e64 v118, v148, v118, s[4:5]
	v_lshlrev_b64 v[156:157], 12, v[144:145]
	v_lshlrev_b32_e32 v118, 2, v118
	v_ashrrev_i32_e32 v143, 31, v142
	ds_bpermute_b32 v123, v118, v119
	v_lshl_add_u64 v[120:121], s[10:11], 0, v[156:157]
	v_cvt_pk_bf16_f32 v155, v124, v125
	v_lshl_add_u64 v[124:125], v[142:143], 1, v[120:121]
	global_store_dwordx4 v[124:125], v[152:155], off sc1
	v_cvt_pk_bf16_f32 v120, v114, v115
	v_xor_b32_e32 v115, 32, v148
	v_cmp_lt_i32_e64 s[4:5], v115, v122
	s_waitcnt lgkmcnt(0)
	v_add_f32_e32 v114, v119, v123
	v_cvt_pk_bf16_f32 v121, v116, v117
	v_cvt_pk_bf16_f32 v122, v126, v127
	v_cvt_pk_bf16_f32 v123, v128, v129
	global_store_dwordx4 v[124:125], v[120:123], off offset:256 sc1
	v_cndmask_b32_e64 v115, v148, v115, s[4:5]
	v_lshlrev_b32_e32 v119, 2, v115
	ds_bpermute_b32 v115, v119, v114
	s_and_saveexec_b64 s[4:5], vcc
	s_cbranch_execz .LBB0_1302
	v_lshl_add_u64 v[116:117], v[144:145], 2, s[18:19]
	s_waitcnt lgkmcnt(0)
	v_add_f32_e32 v114, v114, v115
	s_waitcnt vmcnt(0)
	flat_atomic_add_f32 v[116:117], v114
.LBB0_1302:
	s_or_b64 exec, exec, s[4:5]
	v_cvt_pk_bf16_f32 v120, v94, v95
	v_mul_f32_e32 v95, v95, v95
	v_fmac_f32_e32 v95, v94, v94
	v_mul_f32_e32 v94, v97, v97
	v_fmac_f32_e32 v94, v96, v96
	v_cvt_pk_bf16_f32 v121, v96, v97
	v_add_f32_e32 v94, v95, v94
	v_mul_f32_e32 v95, v107, v107
	v_mul_f32_e32 v96, v109, v109
	v_fmac_f32_e32 v95, v106, v106
	v_fmac_f32_e32 v96, v108, v108
	v_add_f32_e32 v95, v95, v96
	v_add_f32_e32 v94, v95, v94
	v_mul_f32_e32 v95, v103, v103
	v_mul_f32_e32 v96, v105, v105
	v_fmac_f32_e32 v95, v102, v102
	v_fmac_f32_e32 v96, v104, v104
	v_add_f32_e32 v95, v95, v96
	v_mul_f32_e32 v96, v111, v111
	v_mul_f32_e32 v97, v113, v113
	v_fmac_f32_e32 v96, v110, v110
	v_fmac_f32_e32 v97, v112, v112
	v_add_f32_e32 v96, v96, v97
	v_add_f32_e32 v95, v96, v95
	v_cvt_pk_bf16_f32 v122, v106, v107
	v_add_f32_e32 v106, v95, v94
	ds_bpermute_b32 v107, v118, v106
	v_add_u32_e32 v114, 16, v144
	s_waitcnt lgkmcnt(0)
	v_ashrrev_i32_e32 v115, 31, v114
	v_lshlrev_b64 v[116:117], 12, v[114:115]
	v_lshl_add_u64 v[94:95], s[10:11], 0, v[116:117]
	v_lshl_add_u64 v[96:97], v[142:143], 1, v[94:95]
	v_add_f32_e32 v94, v106, v107
	ds_bpermute_b32 v95, v119, v94
	v_cvt_pk_bf16_f32 v123, v108, v109
	global_store_dwordx4 v[96:97], v[120:123], off sc1
	v_cvt_pk_bf16_f32 v102, v102, v103
	v_cvt_pk_bf16_f32 v103, v104, v105
	v_cvt_pk_bf16_f32 v104, v110, v111
	v_cvt_pk_bf16_f32 v105, v112, v113
	global_store_dwordx4 v[96:97], v[102:105], off offset:256 sc1
	s_and_saveexec_b64 s[4:5], vcc
	s_cbranch_execz .LBB0_1304
	v_lshl_add_u64 v[96:97], v[114:115], 2, s[18:19]
	s_waitcnt lgkmcnt(0)
	v_add_f32_e32 v94, v94, v95
	s_waitcnt vmcnt(0)
	flat_atomic_add_f32 v[96:97], v94
.LBB0_1304:
	s_or_b64 exec, exec, s[4:5]
	v_cvt_pk_bf16_f32 v102, v78, v79
	v_mul_f32_e32 v79, v79, v79
	v_fmac_f32_e32 v79, v78, v78
	v_mul_f32_e32 v78, v81, v81
	v_fmac_f32_e32 v78, v80, v80
	v_cvt_pk_bf16_f32 v103, v80, v81
	v_add_f32_e32 v78, v79, v78
	v_mul_f32_e32 v79, v91, v91
	v_mul_f32_e32 v80, v93, v93
	v_fmac_f32_e32 v79, v90, v90
	v_fmac_f32_e32 v80, v92, v92
	v_add_f32_e32 v79, v79, v80
	v_add_f32_e32 v78, v79, v78
	v_mul_f32_e32 v79, v87, v87
	v_mul_f32_e32 v80, v89, v89
	v_fmac_f32_e32 v79, v86, v86
	v_fmac_f32_e32 v80, v88, v88
	v_add_f32_e32 v79, v79, v80
	v_mul_f32_e32 v80, v99, v99
	v_mul_f32_e32 v81, v101, v101
	v_fmac_f32_e32 v80, v98, v98
	v_fmac_f32_e32 v81, v100, v100
	v_add_f32_e32 v80, v80, v81
	v_add_f32_e32 v79, v80, v79
	v_cvt_pk_bf16_f32 v104, v90, v91
	v_add_f32_e32 v90, v79, v78
	ds_bpermute_b32 v91, v118, v90
	v_add_u32_e32 v94, 32, v144
	s_waitcnt lgkmcnt(0)
	v_ashrrev_i32_e32 v95, 31, v94
	v_lshlrev_b64 v[96:97], 12, v[94:95]
	v_lshl_add_u64 v[78:79], s[10:11], 0, v[96:97]
	v_lshl_add_u64 v[80:81], v[142:143], 1, v[78:79]
	v_add_f32_e32 v78, v90, v91
	ds_bpermute_b32 v79, v119, v78
	v_cvt_pk_bf16_f32 v105, v92, v93
	global_store_dwordx4 v[80:81], v[102:105], off sc1
	v_cvt_pk_bf16_f32 v86, v86, v87
	v_cvt_pk_bf16_f32 v87, v88, v89
	v_cvt_pk_bf16_f32 v88, v98, v99
	v_cvt_pk_bf16_f32 v89, v100, v101
	global_store_dwordx4 v[80:81], v[86:89], off offset:256 sc1
	s_and_saveexec_b64 s[4:5], vcc
	s_cbranch_execz .LBB0_1306
	v_lshl_add_u64 v[80:81], v[94:95], 2, s[18:19]
	s_waitcnt lgkmcnt(0)
	v_add_f32_e32 v78, v78, v79
	s_waitcnt vmcnt(0)
	flat_atomic_add_f32 v[80:81], v78
.LBB0_1306:
	s_or_b64 exec, exec, s[4:5]
	v_cvt_pk_bf16_f32 v86, v54, v55
	v_mul_f32_e32 v55, v55, v55
	v_fmac_f32_e32 v55, v54, v54
	v_mul_f32_e32 v54, v57, v57
	v_fmac_f32_e32 v54, v56, v56
	v_cvt_pk_bf16_f32 v87, v56, v57
	v_add_f32_e32 v54, v55, v54
	v_mul_f32_e32 v55, v75, v75
	v_mul_f32_e32 v56, v77, v77
	v_fmac_f32_e32 v55, v74, v74
	v_fmac_f32_e32 v56, v76, v76
	v_add_f32_e32 v55, v55, v56
	v_add_f32_e32 v54, v55, v54
	v_mul_f32_e32 v55, v71, v71
	v_mul_f32_e32 v56, v73, v73
	v_fmac_f32_e32 v55, v70, v70
	v_fmac_f32_e32 v56, v72, v72
	v_add_f32_e32 v55, v55, v56
	v_mul_f32_e32 v56, v83, v83
	v_mul_f32_e32 v57, v85, v85
	v_fmac_f32_e32 v56, v82, v82
	v_fmac_f32_e32 v57, v84, v84
	v_add_f32_e32 v56, v56, v57
	v_add_f32_e32 v55, v56, v55
	v_cvt_pk_bf16_f32 v88, v74, v75
	v_add_f32_e32 v74, v55, v54
	ds_bpermute_b32 v75, v118, v74
	v_add_u32_e32 v78, 48, v144
	s_waitcnt lgkmcnt(0)
	v_ashrrev_i32_e32 v79, 31, v78
	v_lshlrev_b64 v[80:81], 12, v[78:79]
	v_lshl_add_u64 v[54:55], s[10:11], 0, v[80:81]
	v_lshl_add_u64 v[56:57], v[142:143], 1, v[54:55]
	v_add_f32_e32 v54, v74, v75
	ds_bpermute_b32 v55, v119, v54
	v_cvt_pk_bf16_f32 v89, v76, v77
	global_store_dwordx4 v[56:57], v[86:89], off sc1
	v_cvt_pk_bf16_f32 v70, v70, v71
	v_cvt_pk_bf16_f32 v71, v72, v73
	v_cvt_pk_bf16_f32 v72, v82, v83
	v_cvt_pk_bf16_f32 v73, v84, v85
	global_store_dwordx4 v[56:57], v[70:73], off offset:256 sc1
	s_and_saveexec_b64 s[4:5], vcc
	s_cbranch_execz .LBB0_1308
	v_lshl_add_u64 v[56:57], v[78:79], 2, s[18:19]
	s_waitcnt lgkmcnt(0)
	v_add_f32_e32 v54, v54, v55
	s_waitcnt vmcnt(0)
	flat_atomic_add_f32 v[56:57], v54
.LBB0_1308:
	s_or_b64 exec, exec, s[4:5]
	v_cvt_pk_bf16_f32 v70, v30, v31
	v_mul_f32_e32 v31, v31, v31
	v_fmac_f32_e32 v31, v30, v30
	v_mul_f32_e32 v30, v33, v33
	v_fmac_f32_e32 v30, v32, v32
	v_cvt_pk_bf16_f32 v71, v32, v33
	v_add_f32_e32 v30, v31, v30
	v_mul_f32_e32 v31, v43, v43
	v_mul_f32_e32 v32, v45, v45
	v_fmac_f32_e32 v31, v42, v42
	v_fmac_f32_e32 v32, v44, v44
	v_add_f32_e32 v31, v31, v32
	v_add_f32_e32 v30, v31, v30
	v_mul_f32_e32 v31, v39, v39
	v_mul_f32_e32 v32, v41, v41
	v_fmac_f32_e32 v31, v38, v38
	v_fmac_f32_e32 v32, v40, v40
	v_add_f32_e32 v31, v31, v32
	v_mul_f32_e32 v32, v63, v63
	v_mul_f32_e32 v33, v65, v65
	v_fmac_f32_e32 v32, v62, v62
	v_fmac_f32_e32 v33, v64, v64
	v_add_f32_e32 v32, v32, v33
	v_add_f32_e32 v31, v32, v31
	v_cvt_pk_bf16_f32 v72, v42, v43
	v_add_f32_e32 v42, v31, v30
	ds_bpermute_b32 v43, v118, v42
	v_add_u32_e32 v54, 0x80, v144
	s_waitcnt lgkmcnt(0)
	v_ashrrev_i32_e32 v55, 31, v54
	v_lshlrev_b64 v[56:57], 12, v[54:55]
	v_lshl_add_u64 v[30:31], s[10:11], 0, v[56:57]
	v_lshl_add_u64 v[32:33], v[142:143], 1, v[30:31]
	v_add_f32_e32 v30, v42, v43
	ds_bpermute_b32 v31, v119, v30
	v_cvt_pk_bf16_f32 v73, v44, v45
	global_store_dwordx4 v[32:33], v[70:73], off sc1
	v_cvt_pk_bf16_f32 v38, v38, v39
	v_cvt_pk_bf16_f32 v39, v40, v41
	v_cvt_pk_bf16_f32 v40, v62, v63
	v_cvt_pk_bf16_f32 v41, v64, v65
	global_store_dwordx4 v[32:33], v[38:41], off offset:256 sc1
	s_and_saveexec_b64 s[4:5], vcc
	s_cbranch_execz .LBB0_1310
	v_lshl_add_u64 v[32:33], v[54:55], 2, s[18:19]
	s_waitcnt lgkmcnt(0)
	v_add_f32_e32 v30, v30, v31
	s_waitcnt vmcnt(0)
	flat_atomic_add_f32 v[32:33], v30
.LBB0_1310:
	s_or_b64 exec, exec, s[4:5]
	v_cvt_pk_bf16_f32 v38, v14, v15
	v_mul_f32_e32 v15, v15, v15
	v_fmac_f32_e32 v15, v14, v14
	v_mul_f32_e32 v14, v17, v17
	v_fmac_f32_e32 v14, v16, v16
	v_cvt_pk_bf16_f32 v39, v16, v17
	v_add_f32_e32 v14, v15, v14
	v_mul_f32_e32 v15, v27, v27
	v_mul_f32_e32 v16, v29, v29
	v_fmac_f32_e32 v15, v26, v26
	v_fmac_f32_e32 v16, v28, v28
	v_add_f32_e32 v15, v15, v16
	v_add_f32_e32 v14, v15, v14
	v_mul_f32_e32 v15, v23, v23
	v_mul_f32_e32 v16, v25, v25
	v_fmac_f32_e32 v15, v22, v22
	v_fmac_f32_e32 v16, v24, v24
	v_add_f32_e32 v15, v15, v16
	v_mul_f32_e32 v16, v35, v35
	v_mul_f32_e32 v17, v37, v37
	v_fmac_f32_e32 v16, v34, v34
	v_fmac_f32_e32 v17, v36, v36
	v_add_f32_e32 v16, v16, v17
	v_add_f32_e32 v15, v16, v15
	v_cvt_pk_bf16_f32 v40, v26, v27
	v_add_f32_e32 v26, v15, v14
	ds_bpermute_b32 v27, v118, v26
	v_add_u32_e32 v30, 0x90, v144
	s_waitcnt lgkmcnt(0)
	v_ashrrev_i32_e32 v31, 31, v30
	v_lshlrev_b64 v[32:33], 12, v[30:31]
	v_lshl_add_u64 v[14:15], s[10:11], 0, v[32:33]
	v_lshl_add_u64 v[16:17], v[142:143], 1, v[14:15]
	v_add_f32_e32 v14, v26, v27
	ds_bpermute_b32 v15, v119, v14
	v_cvt_pk_bf16_f32 v41, v28, v29
	global_store_dwordx4 v[16:17], v[38:41], off sc1
	v_cvt_pk_bf16_f32 v22, v22, v23
	v_cvt_pk_bf16_f32 v23, v24, v25
	v_cvt_pk_bf16_f32 v24, v34, v35
	v_cvt_pk_bf16_f32 v25, v36, v37
	global_store_dwordx4 v[16:17], v[22:25], off offset:256 sc1
	s_and_saveexec_b64 s[4:5], vcc
	s_cbranch_execz .LBB0_1312
	v_lshl_add_u64 v[16:17], v[30:31], 2, s[18:19]
	s_waitcnt lgkmcnt(0)
	v_add_f32_e32 v14, v14, v15
	s_waitcnt vmcnt(0)
	flat_atomic_add_f32 v[16:17], v14
.LBB0_1312:
	s_or_b64 exec, exec, s[4:5]
	v_cvt_pk_bf16_f32 v22, v2, v3
	v_mul_f32_e32 v3, v3, v3
	v_fmac_f32_e32 v3, v2, v2
	v_mul_f32_e32 v2, v5, v5
	v_fmac_f32_e32 v2, v4, v4
	v_cvt_pk_bf16_f32 v23, v4, v5
	v_add_f32_e32 v2, v3, v2
	v_mul_f32_e32 v3, v11, v11
	v_mul_f32_e32 v4, v13, v13
	v_fmac_f32_e32 v3, v10, v10
	v_fmac_f32_e32 v4, v12, v12
	v_add_f32_e32 v3, v3, v4
	v_add_f32_e32 v2, v3, v2
	v_mul_f32_e32 v3, v7, v7
	v_mul_f32_e32 v4, v9, v9
	v_fmac_f32_e32 v3, v6, v6
	v_fmac_f32_e32 v4, v8, v8
	v_add_f32_e32 v3, v3, v4
	v_mul_f32_e32 v4, v19, v19
	v_mul_f32_e32 v5, v21, v21
	v_fmac_f32_e32 v4, v18, v18
	v_fmac_f32_e32 v5, v20, v20
	v_add_f32_e32 v4, v4, v5
	v_add_f32_e32 v3, v4, v3
	v_add_f32_e32 v5, v3, v2
	v_cvt_pk_bf16_f32 v24, v10, v11
	v_cvt_pk_bf16_f32 v25, v12, v13
	ds_bpermute_b32 v12, v118, v5
	v_add_u32_e32 v14, 0xa0, v144
	s_waitcnt lgkmcnt(0)
	v_ashrrev_i32_e32 v15, 31, v14
	v_lshlrev_b64 v[16:17], 12, v[14:15]
	v_lshl_add_u64 v[2:3], s[10:11], 0, v[16:17]
	v_lshl_add_u64 v[10:11], v[142:143], 1, v[2:3]
	v_add_f32_e32 v2, v5, v12
	ds_bpermute_b32 v3, v119, v2
	global_store_dwordx4 v[10:11], v[22:25], off sc1
	v_cvt_pk_bf16_f32 v4, v6, v7
	v_cvt_pk_bf16_f32 v5, v8, v9
	v_cvt_pk_bf16_f32 v6, v18, v19
	v_cvt_pk_bf16_f32 v7, v20, v21
	global_store_dwordx4 v[10:11], v[4:7], off offset:256 sc1
	s_and_saveexec_b64 s[4:5], vcc
	s_cbranch_execz .LBB0_1314
	v_lshl_add_u64 v[4:5], v[14:15], 2, s[18:19]
	s_waitcnt lgkmcnt(0)
	v_add_f32_e32 v2, v2, v3
	s_waitcnt vmcnt(0)
	flat_atomic_add_f32 v[4:5], v2
.LBB0_1314:
	s_or_b64 exec, exec, s[4:5]
	v_mul_f32_e32 v10, v51, v51
	v_mul_f32_e32 v11, v53, v53
	v_fmac_f32_e32 v10, v50, v50
	v_fmac_f32_e32 v11, v52, v52
	v_add_f32_e32 v10, v10, v11
	v_mul_f32_e32 v11, v59, v59
	v_mul_f32_e32 v12, v61, v61
	v_fmac_f32_e32 v11, v58, v58
	v_fmac_f32_e32 v12, v60, v60
	v_add_f32_e32 v11, v11, v12
	v_add_f32_e32 v10, v11, v10
	v_mul_f32_e32 v11, v47, v47
	v_mul_f32_e32 v12, v49, v49
	v_fmac_f32_e32 v11, v46, v46
	v_fmac_f32_e32 v12, v48, v48
	v_add_f32_e32 v11, v11, v12
	v_mul_f32_e32 v12, v67, v67
	v_mul_f32_e32 v13, v69, v69
	v_fmac_f32_e32 v12, v66, v66
	v_fmac_f32_e32 v13, v68, v68
	v_add_f32_e32 v12, v12, v13
	v_add_f32_e32 v11, v12, v11
	v_add_f32_e32 v12, v11, v10
	v_add_u32_e32 v2, 0xb0, v144
	ds_bpermute_b32 v13, v118, v12
	s_waitcnt lgkmcnt(0)
	v_ashrrev_i32_e32 v3, 31, v2
	v_lshlrev_b64 v[8:9], 12, v[2:3]
	v_lshl_add_u64 v[8:9], s[10:11], 0, v[8:9]
	v_cvt_pk_bf16_f32 v4, v50, v51
	v_lshl_add_u64 v[10:11], v[142:143], 1, v[8:9]
	v_cvt_pk_bf16_f32 v5, v52, v53
	v_cvt_pk_bf16_f32 v6, v58, v59
	v_cvt_pk_bf16_f32 v7, v60, v61
	global_store_dwordx4 v[10:11], v[4:7], off sc1
	s_nop 1
	v_add_f32_e32 v4, v12, v13
	ds_bpermute_b32 v5, v119, v4
	v_cvt_pk_bf16_f32 v6, v46, v47
	v_cvt_pk_bf16_f32 v7, v48, v49
	v_cvt_pk_bf16_f32 v8, v66, v67
	v_cvt_pk_bf16_f32 v9, v68, v69
	global_store_dwordx4 v[10:11], v[6:9], off offset:256 sc1
	s_and_saveexec_b64 s[4:5], vcc
	s_cbranch_execz .LBB0_1316
	v_lshl_add_u64 v[2:3], v[2:3], 2, s[18:19]
	s_waitcnt lgkmcnt(0)
	v_add_f32_e32 v4, v4, v5
	s_waitcnt vmcnt(0)
	flat_atomic_add_f32 v[2:3], v4
